# k6
# speedup vs baseline: 1.0315x; 1.0064x over previous
; #define DECODE(t_, z_, pm_, pn_) do { if constexpr (EPI == E_CHDFT) { z_ = (t_) >> 5; pm_ = ((t_) >> 4) & 1; pn_ = (int)sx * 16 + ((t_) & 15); break; } \
;     int wgid = (int)sx * tq + (t_); \
;     z_ = wgid / per; int id = wgid % per; \
;     int nig = WGM * nN, gid = id / nig, fm = gid * WGM, gsz = min(nM - fm, WGM); \
;     pm_ = fm + ((id % nig) % gsz); pn_ = (id % nig) / gsz; } while (0)
; #define STAGE_A(Ak_, b, h) do { const char* _s = (Ak_) + (h) * sHA; \
;     glds16(lds0 + ((b) * 2 + (h)) * (HT * 2), voffA, _s); glds16(lds0 + ((b) * 2 + (h)) * (HT * 2) + 8192, voffA, _s + s2A); } while (0)
; #define STAGE_B(Bk_, Bkh_, vh_, b, h) do { const char* _s = (h) ? (Bkh_) : (Bk_); const unsigned _v0 = (h) ? (vh_)[0] : voffB, _v1 = (h) ? (vh_)[1] : voffB; const long _d = (h) ? s2Bh : s2B; \
;     glds16(lds0 + (4 + (b) * 2 + (h)) * (HT * 2), _v0, _s); glds16(lds0 + (4 + (b) * 2 + (h)) * (HT * 2) + 8192, _v1, _s + _d); } while (0)
; #define BAR __builtin_amdgcn_s_barrier()
; template <int EPI>
; __device__ __forceinline__ void gemm_phase(const GemmDesc d, u16* shm, unsigned sx, unsigned srank, unsigned snloc) {
;     ...
;       f32x4 acc[2][2][4][2] = {};
;       bf16x8 At[4][2], B0[2][2], B1[2][2];
;       const int tn = t + (int)snloc;
;       const bool has_next = tn < tq;
;       int zn = z, pmn = pm, pnn = pn; const char *Aun = Au, *Bun = Bu, *Bunh = Buh; unsigned voffBhn[2] = {voffBh[0], voffBh[1]};
;       if (has_next) { DECODE(tn, zn, pmn, pnn); BASES(zn, pmn, pnn, Aun, Bun, Bunh, voffBhn); }
; #pragma unroll 1
;       for (int kt = 0; kt < nt; kt += 2) {
;         const bool lastk = (kt + 2 >= nt);
;         const char* A1 = Au + (long)(kt + 1) * sKA;
;         const char* A2 = lastk ? Aun : Au + (long)(kt + 2) * sKA;
;         const char* B2 = lastk ? Bun : Bu + (long)(kt + 2) * sKB;
;         const char* B2h = lastk ? Bunh : Buh + (long)(kt + 2) * sKB;
;         const unsigned vh[2] = {lastk ? voffBhn[0] : voffBh[0], lastk ? voffBhn[1] : voffBh[1]};
;         const char* A3 = A2 + sKA; const char* B3 = B2 + sKB; const char* B3h = B2h + sKB;
;         LDB(B0, 0, 0); SCHED; LDA(At, 0, 0); STAGE_A(A1, 1, 1);
;         WAIT_L(8); BAR; MMA(0, 0, At, B0); BAR; SCHED;
;         LDB(B1, 0, 1); STAGE_B(B2, B2h, vh, 0, 0);
;         BAR; MMA(0, 1, At, B1); BAR;
;         LDA(At, 0, 1); STAGE_A(A2, 0, 0);
;         BAR; MMA(1, 0, At, B0); BAR; SCHED;
.LBB0_428:
	s_add_u32 s42, s22, 0x100080
	s_addc_u32 s43, s23, 0
	s_add_u32 s15, s18, 0x100
	s_addc_u32 s89, s19, 0
	s_add_u32 s90, s4, 0x100
	s_addc_u32 s91, s5, 0
	s_mov_b32 s20, 0
.LBB0_429:
	s_add_i32 s21, s20, 2
	s_add_u32 s4, s42, 0xfff00080
	s_addc_u32 s5, s43, -1
	s_cmp_lt_u32 s20, 62
	s_cselect_b32 s92, s15, s16
	s_cselect_b32 s63, s5, s11
	s_cselect_b32 s62, s4, s10
	s_cselect_b32 s93, s89, s17
	s_cselect_b32 s53, s91, s25
	s_cselect_b32 s52, s90, s24
	s_add_u32 s46, s92, 0x80
	s_addc_u32 s47, s93, 0
	s_add_u32 s22, s62, 0x80
	s_addc_u32 s23, s63, 0
	s_add_u32 s94, s42, 0x80000
	s_addc_u32 s95, s43, 0
	s_add_u32 s96, s92, 0x80000
	s_addc_u32 s97, s93, 0
	s_add_u32 s64, s62, 0x80000
	s_addc_u32 s65, s63, 0
	s_add_u32 s54, s52, 0x80000
	s_addc_u32 s55, s53, 0
	s_add_u32 s50, s62, 0x100000
	s_addc_u32 s51, s63, 0
	s_add_u32 s28, s62, 0x180000
	s_addc_u32 s29, s63, 0
	s_add_u32 s48, s92, 0x80080
	s_addc_u32 s49, s93, 0
	s_add_u32 s30, s62, 0x80080
	s_addc_u32 s31, s63, 0
	s_add_u32 s18, s52, 0x80
	s_addc_u32 s19, s53, 0
	s_add_u32 s4, s52, 0x80080
	s_addc_u32 s5, s53, 0
	s_add_u32 s44, s42, 0x100
	s_addc_u32 s45, s43, 0
	s_add_u32 s15, s15, 0x100
	s_addc_u32 s89, s89, 0
	s_add_u32 s90, s90, 0x100
	s_addc_u32 s91, s91, 0
	ds_read_b128 v[128:131], v148
	ds_read_b128 v[132:135], v148 offset:1024
	ds_read_b128 v[136:139], v148 offset:2048
	ds_read_b128 v[140:143], v148 offset:3072
	ds_read_b128 v[156:159], v149
	ds_read_b128 v[160:163], v149 offset:1024
	ds_read_b128 v[164:167], v150
	ds_read_b128 v[168:171], v150 offset:1024
	ds_read_b128 v[172:175], v151
	ds_read_b128 v[178:181], v151 offset:1024
	ds_read_b128 v[192:195], v152
	ds_read_b128 v[196:199], v152 offset:1024
	s_mov_b32 m0, s79
	s_nop 0
	global_load_lds_dwordx4 v145, s[42:43]
	s_mov_b32 m0, s80
	s_nop 0
	global_load_lds_dwordx4 v145, s[94:95]
	s_waitcnt lgkmcnt(8)
	s_barrier
	s_setprio 1
	s_waitcnt lgkmcnt(7)
	v_mfma_f32_16x16x32_bf16 v[124:127], v[156:159], v[128:131], 0
	v_mfma_f32_16x16x32_bf16 v[120:123], v[156:159], v[136:139], 0
	s_waitcnt lgkmcnt(5)
	v_mfma_f32_16x16x32_bf16 v[108:111], v[164:167], v[128:131], 0
	v_mfma_f32_16x16x32_bf16 v[104:107], v[164:167], v[136:139], 0
	s_waitcnt lgkmcnt(3)
	v_mfma_f32_16x16x32_bf16 v[92:95], v[172:175], v[128:131], 0
	v_mfma_f32_16x16x32_bf16 v[88:91], v[172:175], v[136:139], 0
	s_waitcnt lgkmcnt(1)
	v_mfma_f32_16x16x32_bf16 v[76:79], v[192:195], v[128:131], 0
	v_mfma_f32_16x16x32_bf16 v[72:75], v[192:195], v[136:139], 0
	v_mfma_f32_16x16x32_bf16 v[124:127], v[160:163], v[132:135], v[124:127]
	v_mfma_f32_16x16x32_bf16 v[120:123], v[160:163], v[140:143], v[120:123]
	v_mfma_f32_16x16x32_bf16 v[108:111], v[168:171], v[132:135], v[108:111]
	v_mfma_f32_16x16x32_bf16 v[104:107], v[168:171], v[140:143], v[104:107]
	v_mfma_f32_16x16x32_bf16 v[92:95], v[178:181], v[132:135], v[92:95]
	v_mfma_f32_16x16x32_bf16 v[88:91], v[178:181], v[140:143], v[88:91]
	s_waitcnt lgkmcnt(0)
	v_mfma_f32_16x16x32_bf16 v[76:79], v[196:199], v[132:135], v[76:79]
	v_mfma_f32_16x16x32_bf16 v[72:75], v[196:199], v[140:143], v[72:75]
	s_setprio 0
	s_barrier
	ds_read_b128 v[200:203], v153
	ds_read_b128 v[204:207], v153 offset:1024
	ds_read_b128 v[208:211], v153 offset:2048
	ds_read_b128 v[212:215], v153 offset:3072
	s_mov_b32 m0, s37
	s_nop 0
	global_load_lds_dwordx4 v145, s[92:93]
	s_mov_b32 m0, s38
	s_nop 0
	global_load_lds_dwordx4 v145, s[96:97]
	s_barrier
	s_setprio 1
	s_waitcnt lgkmcnt(3)
	v_mfma_f32_16x16x32_bf16 v[116:119], v[156:159], v[200:203], 0
	s_waitcnt lgkmcnt(1)
	v_mfma_f32_16x16x32_bf16 v[112:115], v[156:159], v[208:211], 0
	v_mfma_f32_16x16x32_bf16 v[100:103], v[164:167], v[200:203], 0
	v_mfma_f32_16x16x32_bf16 v[96:99], v[164:167], v[208:211], 0
	v_mfma_f32_16x16x32_bf16 v[84:87], v[172:175], v[200:203], 0
	v_mfma_f32_16x16x32_bf16 v[80:83], v[172:175], v[208:211], 0
	v_mfma_f32_16x16x32_bf16 v[68:71], v[192:195], v[200:203], 0
	v_mfma_f32_16x16x32_bf16 v[64:67], v[192:195], v[208:211], 0
	v_mfma_f32_16x16x32_bf16 v[116:119], v[160:163], v[204:207], v[116:119]
	s_waitcnt lgkmcnt(0)
	v_mfma_f32_16x16x32_bf16 v[112:115], v[160:163], v[212:215], v[112:115]
	v_mfma_f32_16x16x32_bf16 v[100:103], v[168:171], v[204:207], v[100:103]
	v_mfma_f32_16x16x32_bf16 v[96:99], v[168:171], v[212:215], v[96:99]
	v_mfma_f32_16x16x32_bf16 v[84:87], v[178:181], v[204:207], v[84:87]
	v_mfma_f32_16x16x32_bf16 v[80:83], v[178:181], v[212:215], v[80:83]
	v_mfma_f32_16x16x32_bf16 v[68:71], v[196:199], v[204:207], v[68:71]
	v_mfma_f32_16x16x32_bf16 v[64:67], v[196:199], v[212:215], v[64:67]
	s_setprio 0
	s_barrier
	ds_read_b128 v[156:159], v149 offset:16384
	ds_read_b128 v[160:163], v149 offset:17408
	ds_read_b128 v[164:167], v150 offset:16384
	ds_read_b128 v[168:171], v150 offset:17408
	ds_read_b128 v[172:175], v151 offset:16384
	ds_read_b128 v[178:181], v151 offset:17408
	ds_read_b128 v[192:195], v152 offset:16384
	ds_read_b128 v[196:199], v152 offset:17408
	s_mov_b32 m0, s3
	s_nop 0
	global_load_lds_dwordx4 v145, s[62:63]
	s_mov_b32 m0, s39
	s_nop 0
	global_load_lds_dwordx4 v145, s[64:65]
	s_barrier
; #define STAGE_A(Ak_, b, h) do { const char* _s = (Ak_) + (h) * sHA; \
;     glds16(lds0 + ((b) * 2 + (h)) * (HT * 2), voffA, _s); glds16(lds0 + ((b) * 2 + (h)) * (HT * 2) + 8192, voffA, _s + s2A); } while (0)
; #define STAGE_B(Bk_, Bkh_, vh_, b, h) do { const char* _s = (h) ? (Bkh_) : (Bk_); const unsigned _v0 = (h) ? (vh_)[0] : voffB, _v1 = (h) ? (vh_)[1] : voffB; const long _d = (h) ? s2Bh : s2B; \
;     glds16(lds0 + (4 + (b) * 2 + (h)) * (HT * 2), _v0, _s); glds16(lds0 + (4 + (b) * 2 + (h)) * (HT * 2) + 8192, _v1, _s + _d); } while (0)
; #define LDA(dst, b, h) for (int m = 0; m < 4; ++m) for (int k = 0; k < 2; ++k) \
;     dst[m][k] = *reinterpret_cast<const bf16x8*>((char*)SA(b, h) + lds_byte(wr * 64 + m * 16 + fr, k * 32 + fq * 8))
; #define LDB(dst, b, h) for (int n = 0; n < 2; ++n) for (int k = 0; k < 2; ++k) \
;     dst[n][k] = *reinterpret_cast<const bf16x8*>((char*)SB(b, h) + lds_byte(wc * 32 + n * 16 + fr, k * 32 + fq * 8))
; #define MMA(ai, bj, At_, Bt_) do { __builtin_amdgcn_s_setprio(1); \
;     for (int m = 0; m < 4; ++m) for (int n = 0; n < 2; ++n) for (int k = 0; k < 2; ++k) \
;       acc[ai][bj][m][n] = __builtin_amdgcn_mfma_f32_16x16x32_bf16(At_[m][k], Bt_[n][k], acc[ai][bj][m][n], 0, 0, 0); \
;     __builtin_amdgcn_s_setprio(0); } while (0)
; #define WAIT_V(n) asm volatile("s_waitcnt vmcnt(" #n ")" ::: "memory")
; #define WAIT_L(n) asm volatile("s_waitcnt lgkmcnt(" #n ")" ::: "memory")
; #define BAR __builtin_amdgcn_s_barrier()
; #define SCHED __builtin_amdgcn_sched_barrier(0)
; template <int EPI>
; __device__ __forceinline__ void gemm_phase(const GemmDesc d, u16* shm, unsigned sx, unsigned srank, unsigned snloc) {
;     ...
;         BAR; MMA(1, 0, At, B0); BAR; SCHED;
;         STAGE_B(B2, B2h, vh, 0, 1);
;         WAIT_V(6); BAR; MMA(1, 1, At, B1); BAR;
;         LDB(B0, 1, 0); SCHED; LDA(At, 1, 0); STAGE_A(A2, 0, 1);
;         WAIT_L(8); BAR; MMA(0, 0, At, B0); BAR; SCHED;
;         LDB(B1, 1, 1); STAGE_B(B3, B3h, vh, 1, 0);
;         BAR; MMA(0, 1, At, B1); BAR;
;         LDA(At, 1, 1); STAGE_A(A3, 1, 0);
;         BAR; MMA(1, 0, At, B0); BAR; SCHED;
	s_setprio 1
	s_waitcnt lgkmcnt(7)
	v_mfma_f32_16x16x32_bf16 v[60:63], v[156:159], v[128:131], 0
	v_mfma_f32_16x16x32_bf16 v[56:59], v[156:159], v[136:139], 0
	s_waitcnt lgkmcnt(5)
	v_mfma_f32_16x16x32_bf16 v[44:47], v[164:167], v[128:131], 0
	v_mfma_f32_16x16x32_bf16 v[40:43], v[164:167], v[136:139], 0
	s_waitcnt lgkmcnt(3)
	v_mfma_f32_16x16x32_bf16 v[28:31], v[172:175], v[128:131], 0
	v_mfma_f32_16x16x32_bf16 v[24:27], v[172:175], v[136:139], 0
	s_waitcnt lgkmcnt(1)
	v_mfma_f32_16x16x32_bf16 v[12:15], v[192:195], v[128:131], 0
	v_mfma_f32_16x16x32_bf16 v[8:11], v[192:195], v[136:139], 0
	v_mfma_f32_16x16x32_bf16 v[60:63], v[160:163], v[132:135], v[60:63]
	v_mfma_f32_16x16x32_bf16 v[56:59], v[160:163], v[140:143], v[56:59]
	v_mfma_f32_16x16x32_bf16 v[44:47], v[168:171], v[132:135], v[44:47]
	v_mfma_f32_16x16x32_bf16 v[40:43], v[168:171], v[140:143], v[40:43]
	v_mfma_f32_16x16x32_bf16 v[28:31], v[178:181], v[132:135], v[28:31]
	v_mfma_f32_16x16x32_bf16 v[24:27], v[178:181], v[140:143], v[24:27]
	s_waitcnt lgkmcnt(0)
	v_mfma_f32_16x16x32_bf16 v[12:15], v[196:199], v[132:135], v[12:15]
	v_mfma_f32_16x16x32_bf16 v[8:11], v[196:199], v[140:143], v[8:11]
	s_setprio 0
	s_barrier
	s_mov_b32 m0, s40
	s_nop 0
	global_load_lds_dwordx4 v145, s[52:53]
	s_mov_b32 m0, s41
	s_nop 0
	global_load_lds_dwordx4 v145, s[54:55]
	s_waitcnt vmcnt(6)
	s_barrier
	s_setprio 1
	v_mfma_f32_16x16x32_bf16 v[52:55], v[156:159], v[200:203], 0
	v_mfma_f32_16x16x32_bf16 v[48:51], v[156:159], v[208:211], 0
	v_mfma_f32_16x16x32_bf16 v[36:39], v[164:167], v[200:203], 0
	v_mfma_f32_16x16x32_bf16 v[32:35], v[164:167], v[208:211], 0
	v_mfma_f32_16x16x32_bf16 v[20:23], v[172:175], v[200:203], 0
	v_mfma_f32_16x16x32_bf16 v[16:19], v[172:175], v[208:211], 0
	v_mfma_f32_16x16x32_bf16 v[4:7], v[192:195], v[200:203], 0
	v_mfma_f32_16x16x32_bf16 v[0:3], v[192:195], v[208:211], 0
	v_mfma_f32_16x16x32_bf16 v[52:55], v[160:163], v[204:207], v[52:55]
	v_mfma_f32_16x16x32_bf16 v[48:51], v[160:163], v[212:215], v[48:51]
	v_mfma_f32_16x16x32_bf16 v[36:39], v[168:171], v[204:207], v[36:39]
	v_mfma_f32_16x16x32_bf16 v[32:35], v[168:171], v[212:215], v[32:35]
	v_mfma_f32_16x16x32_bf16 v[20:23], v[178:181], v[204:207], v[20:23]
	v_mfma_f32_16x16x32_bf16 v[16:19], v[178:181], v[212:215], v[16:19]
	v_mfma_f32_16x16x32_bf16 v[4:7], v[196:199], v[204:207], v[4:7]
	v_mfma_f32_16x16x32_bf16 v[0:3], v[196:199], v[212:215], v[0:3]
	s_setprio 0
	s_barrier
	ds_read_b128 v[128:131], v154
	ds_read_b128 v[132:135], v154 offset:1024
	ds_read_b128 v[136:139], v154 offset:2048
	ds_read_b128 v[140:143], v154 offset:3072
	ds_read_b128 v[156:159], v149 offset:32768
	ds_read_b128 v[160:163], v149 offset:33792
	ds_read_b128 v[164:167], v150 offset:32768
	ds_read_b128 v[168:171], v150 offset:33792
	ds_read_b128 v[172:175], v151 offset:32768
	ds_read_b128 v[178:181], v151 offset:33792
	ds_read_b128 v[192:195], v152 offset:32768
	ds_read_b128 v[196:199], v152 offset:33792
	s_mov_b32 m0, s57
	s_nop 0
	global_load_lds_dwordx4 v145, s[50:51]
	s_mov_b32 m0, s59
	s_nop 0
	global_load_lds_dwordx4 v145, s[28:29]
	s_waitcnt lgkmcnt(8)
	s_barrier
	s_setprio 1
	s_waitcnt lgkmcnt(7)
	v_mfma_f32_16x16x32_bf16 v[124:127], v[156:159], v[128:131], v[124:127]
	v_mfma_f32_16x16x32_bf16 v[120:123], v[156:159], v[136:139], v[120:123]
	s_waitcnt lgkmcnt(5)
	v_mfma_f32_16x16x32_bf16 v[108:111], v[164:167], v[128:131], v[108:111]
	v_mfma_f32_16x16x32_bf16 v[104:107], v[164:167], v[136:139], v[104:107]
	s_waitcnt lgkmcnt(3)
	v_mfma_f32_16x16x32_bf16 v[92:95], v[172:175], v[128:131], v[92:95]
	v_mfma_f32_16x16x32_bf16 v[88:91], v[172:175], v[136:139], v[88:91]
	s_waitcnt lgkmcnt(1)
	v_mfma_f32_16x16x32_bf16 v[76:79], v[192:195], v[128:131], v[76:79]
	v_mfma_f32_16x16x32_bf16 v[72:75], v[192:195], v[136:139], v[72:75]
	v_mfma_f32_16x16x32_bf16 v[124:127], v[160:163], v[132:135], v[124:127]
	v_mfma_f32_16x16x32_bf16 v[120:123], v[160:163], v[140:143], v[120:123]
	v_mfma_f32_16x16x32_bf16 v[108:111], v[168:171], v[132:135], v[108:111]
	v_mfma_f32_16x16x32_bf16 v[104:107], v[168:171], v[140:143], v[104:107]
	v_mfma_f32_16x16x32_bf16 v[92:95], v[178:181], v[132:135], v[92:95]
	v_mfma_f32_16x16x32_bf16 v[88:91], v[178:181], v[140:143], v[88:91]
	s_waitcnt lgkmcnt(0)
	v_mfma_f32_16x16x32_bf16 v[76:79], v[196:199], v[132:135], v[76:79]
	v_mfma_f32_16x16x32_bf16 v[72:75], v[196:199], v[140:143], v[72:75]
	s_setprio 0
	s_barrier
	ds_read_b128 v[200:203], v155
	ds_read_b128 v[204:207], v155 offset:1024
	ds_read_b128 v[208:211], v155 offset:2048
	ds_read_b128 v[212:215], v155 offset:3072
	s_mov_b32 m0, s71
	s_nop 0
	global_load_lds_dwordx4 v145, s[46:47]
	s_mov_b32 m0, s72
	s_nop 0
	global_load_lds_dwordx4 v145, s[48:49]
	s_barrier
	s_setprio 1
	s_waitcnt lgkmcnt(3)
	v_mfma_f32_16x16x32_bf16 v[116:119], v[156:159], v[200:203], v[116:119]
	s_waitcnt lgkmcnt(1)
	v_mfma_f32_16x16x32_bf16 v[112:115], v[156:159], v[208:211], v[112:115]
	v_mfma_f32_16x16x32_bf16 v[100:103], v[164:167], v[200:203], v[100:103]
	v_mfma_f32_16x16x32_bf16 v[96:99], v[164:167], v[208:211], v[96:99]
	v_mfma_f32_16x16x32_bf16 v[84:87], v[172:175], v[200:203], v[84:87]
	v_mfma_f32_16x16x32_bf16 v[80:83], v[172:175], v[208:211], v[80:83]
	v_mfma_f32_16x16x32_bf16 v[68:71], v[192:195], v[200:203], v[68:71]
	v_mfma_f32_16x16x32_bf16 v[64:67], v[192:195], v[208:211], v[64:67]
	v_mfma_f32_16x16x32_bf16 v[116:119], v[160:163], v[204:207], v[116:119]
	s_waitcnt lgkmcnt(0)
	v_mfma_f32_16x16x32_bf16 v[112:115], v[160:163], v[212:215], v[112:115]
	v_mfma_f32_16x16x32_bf16 v[100:103], v[168:171], v[204:207], v[100:103]
	v_mfma_f32_16x16x32_bf16 v[96:99], v[168:171], v[212:215], v[96:99]
	v_mfma_f32_16x16x32_bf16 v[84:87], v[178:181], v[204:207], v[84:87]
	v_mfma_f32_16x16x32_bf16 v[80:83], v[178:181], v[212:215], v[80:83]
	v_mfma_f32_16x16x32_bf16 v[68:71], v[196:199], v[204:207], v[68:71]
	v_mfma_f32_16x16x32_bf16 v[64:67], v[196:199], v[212:215], v[64:67]
	s_setprio 0
	s_barrier
; #define STAGE_A(Ak_, b, h) do { const char* _s = (Ak_) + (h) * sHA; \
;     glds16(lds0 + ((b) * 2 + (h)) * (HT * 2), voffA, _s); glds16(lds0 + ((b) * 2 + (h)) * (HT * 2) + 8192, voffA, _s + s2A); } while (0)
; #define STAGE_B(Bk_, Bkh_, vh_, b, h) do { const char* _s = (h) ? (Bkh_) : (Bk_); const unsigned _v0 = (h) ? (vh_)[0] : voffB, _v1 = (h) ? (vh_)[1] : voffB; const long _d = (h) ? s2Bh : s2B; \
;     glds16(lds0 + (4 + (b) * 2 + (h)) * (HT * 2), _v0, _s); glds16(lds0 + (4 + (b) * 2 + (h)) * (HT * 2) + 8192, _v1, _s + _d); } while (0)
; #define LDA(dst, b, h) for (int m = 0; m < 4; ++m) for (int k = 0; k < 2; ++k) \
;     dst[m][k] = *reinterpret_cast<const bf16x8*>((char*)SA(b, h) + lds_byte(wr * 64 + m * 16 + fr, k * 32 + fq * 8))
; #define LDB(dst, b, h) for (int n = 0; n < 2; ++n) for (int k = 0; k < 2; ++k) \
;     dst[n][k] = *reinterpret_cast<const bf16x8*>((char*)SB(b, h) + lds_byte(wc * 32 + n * 16 + fr, k * 32 + fq * 8))
; #define WAIT_V(n) asm volatile("s_waitcnt vmcnt(" #n ")" ::: "memory")
; #define WAIT_L(n) asm volatile("s_waitcnt lgkmcnt(" #n ")" ::: "memory")
; #define BAR __builtin_amdgcn_s_barrier()
; template <int EPI>
; __device__ __forceinline__ void gemm_phase(const GemmDesc d, u16* shm, unsigned sx, unsigned srank, unsigned snloc) {
;     ...
;       for (int kt = 0; kt < nt; kt += 2) {
;         const bool lastk = (kt + 2 >= nt);
;         const char* A1 = Au + (long)(kt + 1) * sKA;
;         const char* A2 = lastk ? Aun : Au + (long)(kt + 2) * sKA;
;         const char* B2 = lastk ? Bun : Bu + (long)(kt + 2) * sKB;
;         const char* B2h = lastk ? Bunh : Buh + (long)(kt + 2) * sKB;
;         const unsigned vh[2] = {lastk ? voffBhn[0] : voffBh[0], lastk ? voffBhn[1] : voffBh[1]};
;         const char* A3 = A2 + sKA; const char* B3 = B2 + sKB; const char* B3h = B2h + sKB;
;         LDB(B0, 0, 0); SCHED; LDA(At, 0, 0); STAGE_A(A1, 1, 1);
;         WAIT_L(8); BAR; MMA(0, 0, At, B0); BAR; SCHED;
;     ...
;         WAIT_V(6); BAR; MMA(1, 1, At, B1); BAR;
;         LDB(B0, 1, 0); SCHED; LDA(At, 1, 0); STAGE_A(A2, 0, 1);
;         WAIT_L(8); BAR; MMA(0, 0, At, B0); BAR; SCHED;
;         LDB(B1, 1, 1); STAGE_B(B3, B3h, vh, 1, 0);
;         BAR; MMA(0, 1, At, B1); BAR;
;         LDA(At, 1, 1); STAGE_A(A3, 1, 0);
;         BAR; MMA(1, 0, At, B0); BAR; SCHED;
;         STAGE_B(B3, B3h, vh, 1, 1);
;         WAIT_V(6); BAR; MMA(1, 1, At, B1); BAR;
	ds_read_b128 v[156:159], v149 offset:49152
	ds_read_b128 v[160:163], v149 offset:50176
	ds_read_b128 v[164:167], v150 offset:49152
	ds_read_b128 v[168:171], v150 offset:50176
	ds_read_b128 v[172:175], v151 offset:49152
	ds_read_b128 v[178:181], v151 offset:50176
	ds_read_b128 v[192:195], v152 offset:49152
	ds_read_b128 v[196:199], v152 offset:50176
	s_mov_b32 m0, s73
	s_nop 0
	global_load_lds_dwordx4 v145, s[22:23]
	s_mov_b32 m0, s76
	s_nop 0
	global_load_lds_dwordx4 v145, s[30:31]
	s_barrier
	s_setprio 1
	s_waitcnt lgkmcnt(7)
	v_mfma_f32_16x16x32_bf16 v[60:63], v[156:159], v[128:131], v[60:63]
	v_mfma_f32_16x16x32_bf16 v[56:59], v[156:159], v[136:139], v[56:59]
	s_waitcnt lgkmcnt(5)
	v_mfma_f32_16x16x32_bf16 v[44:47], v[164:167], v[128:131], v[44:47]
	v_mfma_f32_16x16x32_bf16 v[40:43], v[164:167], v[136:139], v[40:43]
	s_waitcnt lgkmcnt(3)
	v_mfma_f32_16x16x32_bf16 v[28:31], v[172:175], v[128:131], v[28:31]
	v_mfma_f32_16x16x32_bf16 v[24:27], v[172:175], v[136:139], v[24:27]
	s_waitcnt lgkmcnt(1)
	v_mfma_f32_16x16x32_bf16 v[12:15], v[192:195], v[128:131], v[12:15]
	v_mfma_f32_16x16x32_bf16 v[8:11], v[192:195], v[136:139], v[8:11]
	v_mfma_f32_16x16x32_bf16 v[60:63], v[160:163], v[132:135], v[60:63]
	v_mfma_f32_16x16x32_bf16 v[56:59], v[160:163], v[140:143], v[56:59]
	v_mfma_f32_16x16x32_bf16 v[44:47], v[168:171], v[132:135], v[44:47]
	v_mfma_f32_16x16x32_bf16 v[40:43], v[168:171], v[140:143], v[40:43]
	v_mfma_f32_16x16x32_bf16 v[28:31], v[178:181], v[132:135], v[28:31]
	v_mfma_f32_16x16x32_bf16 v[24:27], v[178:181], v[140:143], v[24:27]
	s_waitcnt lgkmcnt(0)
	v_mfma_f32_16x16x32_bf16 v[12:15], v[196:199], v[132:135], v[12:15]
	v_mfma_f32_16x16x32_bf16 v[8:11], v[196:199], v[140:143], v[8:11]
	s_setprio 0
	s_barrier
	s_mov_b32 m0, s77
	s_nop 0
	global_load_lds_dwordx4 v145, s[18:19]
	s_mov_b32 m0, s78
	s_nop 0
	global_load_lds_dwordx4 v145, s[4:5]
	s_mov_b64 s[42:43], s[44:45]
	s_mov_b32 s20, s21
	s_add_i32 s21, s20, 2
	s_add_u32 s4, s42, 0xfff00080
	s_addc_u32 s5, s43, -1
	s_cmp_lt_u32 s20, 62
	s_cselect_b32 s92, s15, s16
	s_cselect_b32 s63, s5, s11
	s_cselect_b32 s62, s4, s10
	s_cselect_b32 s93, s89, s17
	s_cselect_b32 s53, s91, s25
	s_cselect_b32 s52, s90, s24
	s_add_u32 s46, s92, 0x80
	s_addc_u32 s47, s93, 0
	s_add_u32 s22, s62, 0x80
	s_addc_u32 s23, s63, 0
	s_add_u32 s94, s42, 0x80000
	s_addc_u32 s95, s43, 0
	s_add_u32 s96, s92, 0x80000
	s_addc_u32 s97, s93, 0
	s_add_u32 s64, s62, 0x80000
	s_addc_u32 s65, s63, 0
	s_add_u32 s54, s52, 0x80000
	s_addc_u32 s55, s53, 0
	s_add_u32 s50, s62, 0x100000
	s_addc_u32 s51, s63, 0
	s_add_u32 s28, s62, 0x180000
	s_addc_u32 s29, s63, 0
	s_add_u32 s48, s92, 0x80080
	s_addc_u32 s49, s93, 0
	s_add_u32 s30, s62, 0x80080
	s_addc_u32 s31, s63, 0
	s_add_u32 s18, s52, 0x80
	s_addc_u32 s19, s53, 0
	s_add_u32 s4, s52, 0x80080
	s_addc_u32 s5, s53, 0
	s_add_u32 s44, s42, 0x100
	s_addc_u32 s45, s43, 0
	s_add_u32 s15, s15, 0x100
	s_addc_u32 s89, s89, 0
	s_add_u32 s90, s90, 0x100
	s_addc_u32 s91, s91, 0
	s_waitcnt vmcnt(6)
	s_barrier
	s_setprio 1
	v_mfma_f32_16x16x32_bf16 v[52:55], v[156:159], v[200:203], v[52:55]
	v_mfma_f32_16x16x32_bf16 v[48:51], v[156:159], v[208:211], v[48:51]
	v_mfma_f32_16x16x32_bf16 v[36:39], v[164:167], v[200:203], v[36:39]
	v_mfma_f32_16x16x32_bf16 v[32:35], v[164:167], v[208:211], v[32:35]
	v_mfma_f32_16x16x32_bf16 v[20:23], v[172:175], v[200:203], v[20:23]
	v_mfma_f32_16x16x32_bf16 v[16:19], v[172:175], v[208:211], v[16:19]
	v_mfma_f32_16x16x32_bf16 v[4:7], v[192:195], v[200:203], v[4:7]
	v_mfma_f32_16x16x32_bf16 v[0:3], v[192:195], v[208:211], v[0:3]
	v_mfma_f32_16x16x32_bf16 v[52:55], v[160:163], v[204:207], v[52:55]
	v_mfma_f32_16x16x32_bf16 v[48:51], v[160:163], v[212:215], v[48:51]
	v_mfma_f32_16x16x32_bf16 v[36:39], v[168:171], v[204:207], v[36:39]
	v_mfma_f32_16x16x32_bf16 v[32:35], v[168:171], v[212:215], v[32:35]
	v_mfma_f32_16x16x32_bf16 v[20:23], v[178:181], v[204:207], v[20:23]
	v_mfma_f32_16x16x32_bf16 v[16:19], v[178:181], v[212:215], v[16:19]
	v_mfma_f32_16x16x32_bf16 v[4:7], v[196:199], v[204:207], v[4:7]
	v_mfma_f32_16x16x32_bf16 v[0:3], v[196:199], v[212:215], v[0:3]
	s_setprio 0
	s_barrier
.Lk_seqdft:
	ds_read_b128 v[128:131], v148
	ds_read_b128 v[132:135], v148 offset:1024
	ds_read_b128 v[136:139], v148 offset:2048
	ds_read_b128 v[140:143], v148 offset:3072
	ds_read_b128 v[156:159], v149
	ds_read_b128 v[160:163], v149 offset:1024
	ds_read_b128 v[164:167], v150
	ds_read_b128 v[168:171], v150 offset:1024
	ds_read_b128 v[172:175], v151
	ds_read_b128 v[178:181], v151 offset:1024
	ds_read_b128 v[192:195], v152
	ds_read_b128 v[196:199], v152 offset:1024
	s_mov_b32 m0, s79
	s_nop 0
	global_load_lds_dwordx4 v145, s[42:43]
	s_mov_b32 m0, s80
	s_nop 0
	global_load_lds_dwordx4 v145, s[94:95]
	s_waitcnt lgkmcnt(8)
	s_barrier
	s_setprio 1
	s_waitcnt lgkmcnt(7)
	v_mfma_f32_16x16x32_bf16 v[124:127], v[156:159], v[128:131], v[124:127]
	v_mfma_f32_16x16x32_bf16 v[120:123], v[156:159], v[136:139], v[120:123]
	s_waitcnt lgkmcnt(5)
	v_mfma_f32_16x16x32_bf16 v[108:111], v[164:167], v[128:131], v[108:111]
	v_mfma_f32_16x16x32_bf16 v[104:107], v[164:167], v[136:139], v[104:107]
	s_waitcnt lgkmcnt(3)
	v_mfma_f32_16x16x32_bf16 v[92:95], v[172:175], v[128:131], v[92:95]
	v_mfma_f32_16x16x32_bf16 v[88:91], v[172:175], v[136:139], v[88:91]
	s_waitcnt lgkmcnt(1)
	v_mfma_f32_16x16x32_bf16 v[76:79], v[192:195], v[128:131], v[76:79]
	v_mfma_f32_16x16x32_bf16 v[72:75], v[192:195], v[136:139], v[72:75]
	v_mfma_f32_16x16x32_bf16 v[124:127], v[160:163], v[132:135], v[124:127]
	v_mfma_f32_16x16x32_bf16 v[120:123], v[160:163], v[140:143], v[120:123]
	v_mfma_f32_16x16x32_bf16 v[108:111], v[168:171], v[132:135], v[108:111]
	v_mfma_f32_16x16x32_bf16 v[104:107], v[168:171], v[140:143], v[104:107]
	v_mfma_f32_16x16x32_bf16 v[92:95], v[178:181], v[132:135], v[92:95]
	v_mfma_f32_16x16x32_bf16 v[88:91], v[178:181], v[140:143], v[88:91]
	s_waitcnt lgkmcnt(0)
	v_mfma_f32_16x16x32_bf16 v[76:79], v[196:199], v[132:135], v[76:79]
	v_mfma_f32_16x16x32_bf16 v[72:75], v[196:199], v[140:143], v[72:75]
	s_setprio 0
	s_barrier
; #define STAGE_A(Ak_, b, h) do { const char* _s = (Ak_) + (h) * sHA; \
;     glds16(lds0 + ((b) * 2 + (h)) * (HT * 2), voffA, _s); glds16(lds0 + ((b) * 2 + (h)) * (HT * 2) + 8192, voffA, _s + s2A); } while (0)
; #define STAGE_B(Bk_, Bkh_, vh_, b, h) do { const char* _s = (h) ? (Bkh_) : (Bk_); const unsigned _v0 = (h) ? (vh_)[0] : voffB, _v1 = (h) ? (vh_)[1] : voffB; const long _d = (h) ? s2Bh : s2B; \
;     glds16(lds0 + (4 + (b) * 2 + (h)) * (HT * 2), _v0, _s); glds16(lds0 + (4 + (b) * 2 + (h)) * (HT * 2) + 8192, _v1, _s + _d); } while (0)
; #define LDA(dst, b, h) for (int m = 0; m < 4; ++m) for (int k = 0; k < 2; ++k) \
;     dst[m][k] = *reinterpret_cast<const bf16x8*>((char*)SA(b, h) + lds_byte(wr * 64 + m * 16 + fr, k * 32 + fq * 8))
; #define LDB(dst, b, h) for (int n = 0; n < 2; ++n) for (int k = 0; k < 2; ++k) \
;     dst[n][k] = *reinterpret_cast<const bf16x8*>((char*)SB(b, h) + lds_byte(wc * 32 + n * 16 + fr, k * 32 + fq * 8))
; #define MMA(ai, bj, At_, Bt_) do { __builtin_amdgcn_s_setprio(1); \
;     for (int m = 0; m < 4; ++m) for (int n = 0; n < 2; ++n) for (int k = 0; k < 2; ++k) \
;       acc[ai][bj][m][n] = __builtin_amdgcn_mfma_f32_16x16x32_bf16(At_[m][k], Bt_[n][k], acc[ai][bj][m][n], 0, 0, 0); \
;     __builtin_amdgcn_s_setprio(0); } while (0)
; #define WAIT_V(n) asm volatile("s_waitcnt vmcnt(" #n ")" ::: "memory")
; #define WAIT_L(n) asm volatile("s_waitcnt lgkmcnt(" #n ")" ::: "memory")
; #define BAR __builtin_amdgcn_s_barrier()
; #define SCHED __builtin_amdgcn_sched_barrier(0)
; template <int EPI>
; __device__ __forceinline__ void gemm_phase(const GemmDesc d, u16* shm, unsigned sx, unsigned srank, unsigned snloc) {
;     ...
;         LDB(B1, 0, 1); STAGE_B(B2, B2h, vh, 0, 0);
;         BAR; MMA(0, 1, At, B1); BAR;
;         LDA(At, 0, 1); STAGE_A(A2, 0, 0);
;         BAR; MMA(1, 0, At, B0); BAR; SCHED;
;         STAGE_B(B2, B2h, vh, 0, 1);
;         WAIT_V(6); BAR; MMA(1, 1, At, B1); BAR;
;         LDB(B0, 1, 0); SCHED; LDA(At, 1, 0); STAGE_A(A2, 0, 1);
;         WAIT_L(8); BAR; MMA(0, 0, At, B0); BAR; SCHED;
	ds_read_b128 v[200:203], v153
	ds_read_b128 v[204:207], v153 offset:1024
	ds_read_b128 v[208:211], v153 offset:2048
	ds_read_b128 v[212:215], v153 offset:3072
	s_mov_b32 m0, s37
	s_nop 0
	global_load_lds_dwordx4 v145, s[92:93]
	s_mov_b32 m0, s38
	s_nop 0
	global_load_lds_dwordx4 v145, s[96:97]
	s_barrier
	s_setprio 1
	s_waitcnt lgkmcnt(3)
	v_mfma_f32_16x16x32_bf16 v[116:119], v[156:159], v[200:203], v[116:119]
	s_waitcnt lgkmcnt(1)
	v_mfma_f32_16x16x32_bf16 v[112:115], v[156:159], v[208:211], v[112:115]
	v_mfma_f32_16x16x32_bf16 v[100:103], v[164:167], v[200:203], v[100:103]
	v_mfma_f32_16x16x32_bf16 v[96:99], v[164:167], v[208:211], v[96:99]
	v_mfma_f32_16x16x32_bf16 v[84:87], v[172:175], v[200:203], v[84:87]
	v_mfma_f32_16x16x32_bf16 v[80:83], v[172:175], v[208:211], v[80:83]
	v_mfma_f32_16x16x32_bf16 v[68:71], v[192:195], v[200:203], v[68:71]
	v_mfma_f32_16x16x32_bf16 v[64:67], v[192:195], v[208:211], v[64:67]
	v_mfma_f32_16x16x32_bf16 v[116:119], v[160:163], v[204:207], v[116:119]
	s_waitcnt lgkmcnt(0)
	v_mfma_f32_16x16x32_bf16 v[112:115], v[160:163], v[212:215], v[112:115]
	v_mfma_f32_16x16x32_bf16 v[100:103], v[168:171], v[204:207], v[100:103]
	v_mfma_f32_16x16x32_bf16 v[96:99], v[168:171], v[212:215], v[96:99]
	v_mfma_f32_16x16x32_bf16 v[84:87], v[178:181], v[204:207], v[84:87]
	v_mfma_f32_16x16x32_bf16 v[80:83], v[178:181], v[212:215], v[80:83]
	v_mfma_f32_16x16x32_bf16 v[68:71], v[196:199], v[204:207], v[68:71]
	v_mfma_f32_16x16x32_bf16 v[64:67], v[196:199], v[212:215], v[64:67]
	s_setprio 0
	s_barrier
	ds_read_b128 v[156:159], v149 offset:16384
	ds_read_b128 v[160:163], v149 offset:17408
	ds_read_b128 v[164:167], v150 offset:16384
	ds_read_b128 v[168:171], v150 offset:17408
	ds_read_b128 v[172:175], v151 offset:16384
	ds_read_b128 v[178:181], v151 offset:17408
	ds_read_b128 v[192:195], v152 offset:16384
	ds_read_b128 v[196:199], v152 offset:17408
	s_mov_b32 m0, s3
	s_nop 0
	global_load_lds_dwordx4 v145, s[62:63]
	s_mov_b32 m0, s39
	s_nop 0
	global_load_lds_dwordx4 v145, s[64:65]
	s_barrier
	s_setprio 1
	s_waitcnt lgkmcnt(7)
	v_mfma_f32_16x16x32_bf16 v[60:63], v[156:159], v[128:131], v[60:63]
	v_mfma_f32_16x16x32_bf16 v[56:59], v[156:159], v[136:139], v[56:59]
	s_waitcnt lgkmcnt(5)
	v_mfma_f32_16x16x32_bf16 v[44:47], v[164:167], v[128:131], v[44:47]
	v_mfma_f32_16x16x32_bf16 v[40:43], v[164:167], v[136:139], v[40:43]
	s_waitcnt lgkmcnt(3)
	v_mfma_f32_16x16x32_bf16 v[28:31], v[172:175], v[128:131], v[28:31]
	v_mfma_f32_16x16x32_bf16 v[24:27], v[172:175], v[136:139], v[24:27]
	s_waitcnt lgkmcnt(1)
	v_mfma_f32_16x16x32_bf16 v[12:15], v[192:195], v[128:131], v[12:15]
	v_mfma_f32_16x16x32_bf16 v[8:11], v[192:195], v[136:139], v[8:11]
	v_mfma_f32_16x16x32_bf16 v[60:63], v[160:163], v[132:135], v[60:63]
	v_mfma_f32_16x16x32_bf16 v[56:59], v[160:163], v[140:143], v[56:59]
	v_mfma_f32_16x16x32_bf16 v[44:47], v[168:171], v[132:135], v[44:47]
	v_mfma_f32_16x16x32_bf16 v[40:43], v[168:171], v[140:143], v[40:43]
	v_mfma_f32_16x16x32_bf16 v[28:31], v[178:181], v[132:135], v[28:31]
	v_mfma_f32_16x16x32_bf16 v[24:27], v[178:181], v[140:143], v[24:27]
	s_waitcnt lgkmcnt(0)
	v_mfma_f32_16x16x32_bf16 v[12:15], v[196:199], v[132:135], v[12:15]
	v_mfma_f32_16x16x32_bf16 v[8:11], v[196:199], v[140:143], v[8:11]
	s_setprio 0
	s_barrier
	s_mov_b32 m0, s40
	s_nop 0
	global_load_lds_dwordx4 v145, s[52:53]
	s_mov_b32 m0, s41
	s_nop 0
	global_load_lds_dwordx4 v145, s[54:55]
	s_waitcnt vmcnt(6)
	s_barrier
	s_setprio 1
	v_mfma_f32_16x16x32_bf16 v[52:55], v[156:159], v[200:203], v[52:55]
	v_mfma_f32_16x16x32_bf16 v[48:51], v[156:159], v[208:211], v[48:51]
	v_mfma_f32_16x16x32_bf16 v[36:39], v[164:167], v[200:203], v[36:39]
	v_mfma_f32_16x16x32_bf16 v[32:35], v[164:167], v[208:211], v[32:35]
	v_mfma_f32_16x16x32_bf16 v[20:23], v[172:175], v[200:203], v[20:23]
	v_mfma_f32_16x16x32_bf16 v[16:19], v[172:175], v[208:211], v[16:19]
	v_mfma_f32_16x16x32_bf16 v[4:7], v[192:195], v[200:203], v[4:7]
	v_mfma_f32_16x16x32_bf16 v[0:3], v[192:195], v[208:211], v[0:3]
	v_mfma_f32_16x16x32_bf16 v[52:55], v[160:163], v[204:207], v[52:55]
	v_mfma_f32_16x16x32_bf16 v[48:51], v[160:163], v[212:215], v[48:51]
	v_mfma_f32_16x16x32_bf16 v[36:39], v[168:171], v[204:207], v[36:39]
	v_mfma_f32_16x16x32_bf16 v[32:35], v[168:171], v[212:215], v[32:35]
	v_mfma_f32_16x16x32_bf16 v[20:23], v[178:181], v[204:207], v[20:23]
	v_mfma_f32_16x16x32_bf16 v[16:19], v[178:181], v[212:215], v[16:19]
	v_mfma_f32_16x16x32_bf16 v[4:7], v[196:199], v[204:207], v[4:7]
	v_mfma_f32_16x16x32_bf16 v[0:3], v[196:199], v[212:215], v[0:3]
	s_setprio 0
	s_barrier
	ds_read_b128 v[128:131], v154
	ds_read_b128 v[132:135], v154 offset:1024
	ds_read_b128 v[136:139], v154 offset:2048
	ds_read_b128 v[140:143], v154 offset:3072
	ds_read_b128 v[156:159], v149 offset:32768
	ds_read_b128 v[160:163], v149 offset:33792
	ds_read_b128 v[164:167], v150 offset:32768
	ds_read_b128 v[168:171], v150 offset:33792
	ds_read_b128 v[172:175], v151 offset:32768
	ds_read_b128 v[178:181], v151 offset:33792
	ds_read_b128 v[192:195], v152 offset:32768
	ds_read_b128 v[196:199], v152 offset:33792
	s_mov_b32 m0, s57
	s_nop 0
	global_load_lds_dwordx4 v145, s[50:51]
	s_mov_b32 m0, s59
	s_nop 0
	global_load_lds_dwordx4 v145, s[28:29]
	s_waitcnt lgkmcnt(8)
	s_barrier
; #define STAGE_A(Ak_, b, h) do { const char* _s = (Ak_) + (h) * sHA; \
;     glds16(lds0 + ((b) * 2 + (h)) * (HT * 2), voffA, _s); glds16(lds0 + ((b) * 2 + (h)) * (HT * 2) + 8192, voffA, _s + s2A); } while (0)
; #define STAGE_B(Bk_, Bkh_, vh_, b, h) do { const char* _s = (h) ? (Bkh_) : (Bk_); const unsigned _v0 = (h) ? (vh_)[0] : voffB, _v1 = (h) ? (vh_)[1] : voffB; const long _d = (h) ? s2Bh : s2B; \
;     glds16(lds0 + (4 + (b) * 2 + (h)) * (HT * 2), _v0, _s); glds16(lds0 + (4 + (b) * 2 + (h)) * (HT * 2) + 8192, _v1, _s + _d); } while (0)
; #define LDA(dst, b, h) for (int m = 0; m < 4; ++m) for (int k = 0; k < 2; ++k) \
;     dst[m][k] = *reinterpret_cast<const bf16x8*>((char*)SA(b, h) + lds_byte(wr * 64 + m * 16 + fr, k * 32 + fq * 8))
; #define LDB(dst, b, h) for (int n = 0; n < 2; ++n) for (int k = 0; k < 2; ++k) \
;     dst[n][k] = *reinterpret_cast<const bf16x8*>((char*)SB(b, h) + lds_byte(wc * 32 + n * 16 + fr, k * 32 + fq * 8))
; #define MMA(ai, bj, At_, Bt_) do { __builtin_amdgcn_s_setprio(1); \
;     for (int m = 0; m < 4; ++m) for (int n = 0; n < 2; ++n) for (int k = 0; k < 2; ++k) \
;       acc[ai][bj][m][n] = __builtin_amdgcn_mfma_f32_16x16x32_bf16(At_[m][k], Bt_[n][k], acc[ai][bj][m][n], 0, 0, 0); \
;     __builtin_amdgcn_s_setprio(0); } while (0)
; #define WAIT_L(n) asm volatile("s_waitcnt lgkmcnt(" #n ")" ::: "memory")
; #define BAR __builtin_amdgcn_s_barrier()
; #define SCHED __builtin_amdgcn_sched_barrier(0)
; template <int EPI>
; __device__ __forceinline__ void gemm_phase(const GemmDesc d, u16* shm, unsigned sx, unsigned srank, unsigned snloc) {
;     ...
;         WAIT_L(8); BAR; MMA(0, 0, At, B0); BAR; SCHED;
;         LDB(B1, 1, 1); STAGE_B(B3, B3h, vh, 1, 0);
;         BAR; MMA(0, 1, At, B1); BAR;
;         LDA(At, 1, 1); STAGE_A(A3, 1, 0);
	s_setprio 1
	s_waitcnt lgkmcnt(7)
	v_mfma_f32_16x16x32_bf16 v[124:127], v[156:159], v[128:131], v[124:127]
	v_mfma_f32_16x16x32_bf16 v[120:123], v[156:159], v[136:139], v[120:123]
	s_waitcnt lgkmcnt(5)
	v_mfma_f32_16x16x32_bf16 v[108:111], v[164:167], v[128:131], v[108:111]
	v_mfma_f32_16x16x32_bf16 v[104:107], v[164:167], v[136:139], v[104:107]
	s_waitcnt lgkmcnt(3)
	v_mfma_f32_16x16x32_bf16 v[92:95], v[172:175], v[128:131], v[92:95]
	v_mfma_f32_16x16x32_bf16 v[88:91], v[172:175], v[136:139], v[88:91]
	s_waitcnt lgkmcnt(1)
	v_mfma_f32_16x16x32_bf16 v[76:79], v[192:195], v[128:131], v[76:79]
	v_mfma_f32_16x16x32_bf16 v[72:75], v[192:195], v[136:139], v[72:75]
	v_mfma_f32_16x16x32_bf16 v[124:127], v[160:163], v[132:135], v[124:127]
	v_mfma_f32_16x16x32_bf16 v[120:123], v[160:163], v[140:143], v[120:123]
	v_mfma_f32_16x16x32_bf16 v[108:111], v[168:171], v[132:135], v[108:111]
	v_mfma_f32_16x16x32_bf16 v[104:107], v[168:171], v[140:143], v[104:107]
	v_mfma_f32_16x16x32_bf16 v[92:95], v[178:181], v[132:135], v[92:95]
	v_mfma_f32_16x16x32_bf16 v[88:91], v[178:181], v[140:143], v[88:91]
	s_waitcnt lgkmcnt(0)
	v_mfma_f32_16x16x32_bf16 v[76:79], v[196:199], v[132:135], v[76:79]
	v_mfma_f32_16x16x32_bf16 v[72:75], v[196:199], v[140:143], v[72:75]
	s_setprio 0
	s_barrier
	ds_read_b128 v[200:203], v155
	ds_read_b128 v[204:207], v155 offset:1024
	ds_read_b128 v[208:211], v155 offset:2048
	ds_read_b128 v[212:215], v155 offset:3072
	s_mov_b32 m0, s71
	s_nop 0
	global_load_lds_dwordx4 v145, s[46:47]
	s_mov_b32 m0, s72
	s_nop 0
	global_load_lds_dwordx4 v145, s[48:49]
	s_barrier
	s_setprio 1
	s_waitcnt lgkmcnt(3)
	v_mfma_f32_16x16x32_bf16 v[116:119], v[156:159], v[200:203], v[116:119]
	s_waitcnt lgkmcnt(1)
	v_mfma_f32_16x16x32_bf16 v[112:115], v[156:159], v[208:211], v[112:115]
	v_mfma_f32_16x16x32_bf16 v[100:103], v[164:167], v[200:203], v[100:103]
	v_mfma_f32_16x16x32_bf16 v[96:99], v[164:167], v[208:211], v[96:99]
	v_mfma_f32_16x16x32_bf16 v[84:87], v[172:175], v[200:203], v[84:87]
	v_mfma_f32_16x16x32_bf16 v[80:83], v[172:175], v[208:211], v[80:83]
	v_mfma_f32_16x16x32_bf16 v[68:71], v[192:195], v[200:203], v[68:71]
	v_mfma_f32_16x16x32_bf16 v[64:67], v[192:195], v[208:211], v[64:67]
	v_mfma_f32_16x16x32_bf16 v[116:119], v[160:163], v[204:207], v[116:119]
	s_waitcnt lgkmcnt(0)
	v_mfma_f32_16x16x32_bf16 v[112:115], v[160:163], v[212:215], v[112:115]
	v_mfma_f32_16x16x32_bf16 v[100:103], v[168:171], v[204:207], v[100:103]
	v_mfma_f32_16x16x32_bf16 v[96:99], v[168:171], v[212:215], v[96:99]
	v_mfma_f32_16x16x32_bf16 v[84:87], v[178:181], v[204:207], v[84:87]
	v_mfma_f32_16x16x32_bf16 v[80:83], v[178:181], v[212:215], v[80:83]
	v_mfma_f32_16x16x32_bf16 v[68:71], v[196:199], v[204:207], v[68:71]
	v_mfma_f32_16x16x32_bf16 v[64:67], v[196:199], v[212:215], v[64:67]
	s_setprio 0
	s_barrier
	ds_read_b128 v[156:159], v149 offset:49152
	ds_read_b128 v[160:163], v149 offset:50176
	ds_read_b128 v[164:167], v150 offset:49152
	ds_read_b128 v[168:171], v150 offset:50176
	ds_read_b128 v[172:175], v151 offset:49152
	ds_read_b128 v[178:181], v151 offset:50176
	ds_read_b128 v[192:195], v152 offset:49152
	ds_read_b128 v[196:199], v152 offset:50176
	s_mov_b32 m0, s73
	s_nop 0
	global_load_lds_dwordx4 v145, s[22:23]
	s_mov_b32 m0, s76
	s_nop 0
	global_load_lds_dwordx4 v145, s[30:31]
	s_barrier
; #define STAGE_A(Ak_, b, h) do { const char* _s = (Ak_) + (h) * sHA; \
;     glds16(lds0 + ((b) * 2 + (h)) * (HT * 2), voffA, _s); glds16(lds0 + ((b) * 2 + (h)) * (HT * 2) + 8192, voffA, _s + s2A); } while (0)
; #define STAGE_B(Bk_, Bkh_, vh_, b, h) do { const char* _s = (h) ? (Bkh_) : (Bk_); const unsigned _v0 = (h) ? (vh_)[0] : voffB, _v1 = (h) ? (vh_)[1] : voffB; const long _d = (h) ? s2Bh : s2B; \
;     glds16(lds0 + (4 + (b) * 2 + (h)) * (HT * 2), _v0, _s); glds16(lds0 + (4 + (b) * 2 + (h)) * (HT * 2) + 8192, _v1, _s + _d); } while (0)
; #define LDA(dst, b, h) for (int m = 0; m < 4; ++m) for (int k = 0; k < 2; ++k) \
;     dst[m][k] = *reinterpret_cast<const bf16x8*>((char*)SA(b, h) + lds_byte(wr * 64 + m * 16 + fr, k * 32 + fq * 8))
; #define WAIT_V(n) asm volatile("s_waitcnt vmcnt(" #n ")" ::: "memory")
; #define WAIT_L(n) asm volatile("s_waitcnt lgkmcnt(" #n ")" ::: "memory")
; template <int EPI>
; __device__ __forceinline__ void gemm_phase(const GemmDesc d, u16* shm, unsigned sx, unsigned srank, unsigned snloc) {
;     ...
;       for (int kt = 0; kt < nt; kt += 2) {
;         const bool lastk = (kt + 2 >= nt);
;         const char* A1 = Au + (long)(kt + 1) * sKA;
;         const char* A2 = lastk ? Aun : Au + (long)(kt + 2) * sKA;
;         const char* B2 = lastk ? Bun : Bu + (long)(kt + 2) * sKB;
;         const char* B2h = lastk ? Bunh : Buh + (long)(kt + 2) * sKB;
;         const unsigned vh[2] = {lastk ? voffBhn[0] : voffBh[0], lastk ? voffBhn[1] : voffBh[1]};
;         const char* A3 = A2 + sKA; const char* B3 = B2 + sKB; const char* B3h = B2h + sKB;
;         LDB(B0, 0, 0); SCHED; LDA(At, 0, 0); STAGE_A(A1, 1, 1);
;         WAIT_L(8); BAR; MMA(0, 0, At, B0); BAR; SCHED;
;         LDB(B1, 0, 1); STAGE_B(B2, B2h, vh, 0, 0);
;         BAR; MMA(0, 1, At, B1); BAR;
;         LDA(At, 0, 1); STAGE_A(A2, 0, 0);
;         BAR; MMA(1, 0, At, B0); BAR; SCHED;
;         STAGE_B(B2, B2h, vh, 0, 1);
;         WAIT_V(6); BAR; MMA(1, 1, At, B1); BAR;
;         LDB(B0, 1, 0); SCHED; LDA(At, 1, 0); STAGE_A(A2, 0, 1);
;         WAIT_L(8); BAR; MMA(0, 0, At, B0); BAR; SCHED;
;         LDB(B1, 1, 1); STAGE_B(B3, B3h, vh, 1, 0);
;         BAR; MMA(0, 1, At, B1); BAR;
;         LDA(At, 1, 1); STAGE_A(A3, 1, 0);
;         BAR; MMA(1, 0, At, B0); BAR; SCHED;
;         STAGE_B(B3, B3h, vh, 1, 1);
;         WAIT_V(6); BAR; MMA(1, 1, At, B1); BAR;
;       }
	s_setprio 1
	s_waitcnt lgkmcnt(7)
	v_mfma_f32_16x16x32_bf16 v[60:63], v[156:159], v[128:131], v[60:63]
	v_mfma_f32_16x16x32_bf16 v[56:59], v[156:159], v[136:139], v[56:59]
	s_waitcnt lgkmcnt(5)
	v_mfma_f32_16x16x32_bf16 v[44:47], v[164:167], v[128:131], v[44:47]
	v_mfma_f32_16x16x32_bf16 v[40:43], v[164:167], v[136:139], v[40:43]
	s_waitcnt lgkmcnt(3)
	v_mfma_f32_16x16x32_bf16 v[28:31], v[172:175], v[128:131], v[28:31]
	v_mfma_f32_16x16x32_bf16 v[24:27], v[172:175], v[136:139], v[24:27]
	s_waitcnt lgkmcnt(1)
	v_mfma_f32_16x16x32_bf16 v[12:15], v[192:195], v[128:131], v[12:15]
	v_mfma_f32_16x16x32_bf16 v[8:11], v[192:195], v[136:139], v[8:11]
	v_mfma_f32_16x16x32_bf16 v[60:63], v[160:163], v[132:135], v[60:63]
	v_mfma_f32_16x16x32_bf16 v[56:59], v[160:163], v[140:143], v[56:59]
	v_mfma_f32_16x16x32_bf16 v[44:47], v[168:171], v[132:135], v[44:47]
	v_mfma_f32_16x16x32_bf16 v[40:43], v[168:171], v[140:143], v[40:43]
	v_mfma_f32_16x16x32_bf16 v[28:31], v[178:181], v[132:135], v[28:31]
	v_mfma_f32_16x16x32_bf16 v[24:27], v[178:181], v[140:143], v[24:27]
	s_waitcnt lgkmcnt(0)
	v_mfma_f32_16x16x32_bf16 v[12:15], v[196:199], v[132:135], v[12:15]
	v_mfma_f32_16x16x32_bf16 v[8:11], v[196:199], v[140:143], v[8:11]
	s_setprio 0
	s_barrier
	s_mov_b32 m0, s77
	s_nop 0
	global_load_lds_dwordx4 v145, s[18:19]
	s_mov_b32 m0, s78
	s_nop 0
	global_load_lds_dwordx4 v145, s[4:5]
	s_mov_b64 s[42:43], s[44:45]
	s_mov_b32 s20, s21
	s_add_i32 s21, s20, 2
	s_add_u32 s4, s42, 0xfff00080
	s_addc_u32 s5, s43, -1
	s_cmp_lt_u32 s20, 62
	s_cselect_b32 s92, s15, s16
	s_cselect_b32 s63, s5, s11
	s_cselect_b32 s62, s4, s10
	s_cselect_b32 s93, s89, s17
	s_cselect_b32 s53, s91, s25
	s_cselect_b32 s52, s90, s24
	s_add_u32 s46, s92, 0x80
	s_addc_u32 s47, s93, 0
	s_add_u32 s22, s62, 0x80
	s_addc_u32 s23, s63, 0
	s_add_u32 s94, s42, 0x80000
	s_addc_u32 s95, s43, 0
	s_add_u32 s96, s92, 0x80000
	s_addc_u32 s97, s93, 0
	s_add_u32 s64, s62, 0x80000
	s_addc_u32 s65, s63, 0
	s_add_u32 s54, s52, 0x80000
	s_addc_u32 s55, s53, 0
	s_add_u32 s50, s62, 0x100000
	s_addc_u32 s51, s63, 0
	s_add_u32 s28, s62, 0x180000
	s_addc_u32 s29, s63, 0
	s_add_u32 s48, s92, 0x80080
	s_addc_u32 s49, s93, 0
	s_add_u32 s30, s62, 0x80080
	s_addc_u32 s31, s63, 0
	s_add_u32 s18, s52, 0x80
	s_addc_u32 s19, s53, 0
	s_add_u32 s4, s52, 0x80080
	s_addc_u32 s5, s53, 0
	s_add_u32 s44, s42, 0x100
	s_addc_u32 s45, s43, 0
	s_add_u32 s15, s15, 0x100
	s_addc_u32 s89, s89, 0
	s_add_u32 s90, s90, 0x100
	s_addc_u32 s91, s91, 0
	s_waitcnt vmcnt(6)
	s_barrier
	s_setprio 1
	v_mfma_f32_16x16x32_bf16 v[52:55], v[156:159], v[200:203], v[52:55]
	v_mfma_f32_16x16x32_bf16 v[48:51], v[156:159], v[208:211], v[48:51]
	v_mfma_f32_16x16x32_bf16 v[36:39], v[164:167], v[200:203], v[36:39]
	v_mfma_f32_16x16x32_bf16 v[32:35], v[164:167], v[208:211], v[32:35]
	v_mfma_f32_16x16x32_bf16 v[20:23], v[172:175], v[200:203], v[20:23]
	v_mfma_f32_16x16x32_bf16 v[16:19], v[172:175], v[208:211], v[16:19]
	v_mfma_f32_16x16x32_bf16 v[4:7], v[192:195], v[200:203], v[4:7]
	v_mfma_f32_16x16x32_bf16 v[0:3], v[192:195], v[208:211], v[0:3]
	v_mfma_f32_16x16x32_bf16 v[52:55], v[160:163], v[204:207], v[52:55]
	v_mfma_f32_16x16x32_bf16 v[48:51], v[160:163], v[212:215], v[48:51]
	v_mfma_f32_16x16x32_bf16 v[36:39], v[168:171], v[204:207], v[36:39]
	v_mfma_f32_16x16x32_bf16 v[32:35], v[168:171], v[212:215], v[32:35]
	v_mfma_f32_16x16x32_bf16 v[20:23], v[178:181], v[204:207], v[20:23]
	v_mfma_f32_16x16x32_bf16 v[16:19], v[178:181], v[212:215], v[16:19]
	v_mfma_f32_16x16x32_bf16 v[4:7], v[196:199], v[204:207], v[4:7]
	v_mfma_f32_16x16x32_bf16 v[0:3], v[196:199], v[212:215], v[0:3]
	s_setprio 0
	s_cmp_lt_u32 s20, 64
	s_barrier
	s_cbranch_scc1 .Lk_seqdft
	s_and_saveexec_b64 s[4:5], s[8:9]
	s_cbranch_execz .LBB0_432
	s_barrier

; #define DECODE(t_, z_, pm_, pn_) do { if constexpr (EPI == E_CHDFT) { z_ = (t_) >> 5; pm_ = ((t_) >> 4) & 1; pn_ = (int)sx * 16 + ((t_) & 15); break; } \
;     int wgid = (int)sx * tq + (t_); \
;     z_ = wgid / per; int id = wgid % per; \
;     int nig = WGM * nN, gid = id / nig, fm = gid * WGM, gsz = min(nM - fm, WGM); \
;     pm_ = fm + ((id % nig) % gsz); pn_ = (id % nig) / gsz; } while (0)
; #define STAGE_A(Ak_, b, h) do { const char* _s = (Ak_) + (h) * sHA; \
;     glds16(lds0 + ((b) * 2 + (h)) * (HT * 2), voffA, _s); glds16(lds0 + ((b) * 2 + (h)) * (HT * 2) + 8192, voffA, _s + s2A); } while (0)
; #define LDA(dst, b, h) for (int m = 0; m < 4; ++m) for (int k = 0; k < 2; ++k) \
;     dst[m][k] = *reinterpret_cast<const bf16x8*>((char*)SA(b, h) + lds_byte(wr * 64 + m * 16 + fr, k * 32 + fq * 8))
; template <int EPI>
; __device__ __forceinline__ void gemm_phase(const GemmDesc d, u16* shm, unsigned sx, unsigned srank, unsigned snloc) {
;     ...
;       f32x4 acc[2][2][4][2] = {};
;       bf16x8 At[4][2], B0[2][2], B1[2][2];
;       const int tn = t + (int)snloc;
;       const bool has_next = tn < tq;
;       int zn = z, pmn = pm, pnn = pn; const char *Aun = Au, *Bun = Bu, *Bunh = Buh; unsigned voffBhn[2] = {voffBh[0], voffBh[1]};
;       if (has_next) { DECODE(tn, zn, pmn, pnn); BASES(zn, pmn, pnn, Aun, Bun, Bunh, voffBhn); }
; #pragma unroll 1
;       for (int kt = 0; kt < nt; kt += 2) {
;         const bool lastk = (kt + 2 >= nt);
;         const char* A1 = Au + (long)(kt + 1) * sKA;
;         const char* A2 = lastk ? Aun : Au + (long)(kt + 2) * sKA;
;         const char* B2 = lastk ? Bun : Bu + (long)(kt + 2) * sKB;
;         const char* B2h = lastk ? Bunh : Buh + (long)(kt + 2) * sKB;
;         const unsigned vh[2] = {lastk ? voffBhn[0] : voffBh[0], lastk ? voffBhn[1] : voffBh[1]};
;         const char* A3 = A2 + sKA; const char* B3 = B2 + sKB; const char* B3h = B2h + sKB;
;         LDB(B0, 0, 0); SCHED; LDA(At, 0, 0); STAGE_A(A1, 1, 1);
;         WAIT_L(8); BAR; MMA(0, 0, At, B0); BAR; SCHED;
;         LDB(B1, 0, 1); STAGE_B(B2, B2h, vh, 0, 0);
;         BAR; MMA(0, 1, At, B1); BAR;
;         LDA(At, 0, 1); STAGE_A(A2, 0, 0);
;         BAR; MMA(1, 0, At, B0); BAR; SCHED;
;         STAGE_B(B2, B2h, vh, 0, 1);
;         WAIT_V(6); BAR; MMA(1, 1, At, B1); BAR;
;         LDB(B0, 1, 0); SCHED; LDA(At, 1, 0); STAGE_A(A2, 0, 1);
.LBB0_589:
	s_add_u32 s10, s10, 0x40080
	s_addc_u32 s11, s11, 0
	s_add_u32 s90, s18, 0x100
	s_addc_u32 s91, s19, 0
	s_add_u32 s92, s4, 0x100
	s_addc_u32 s93, s5, 0
	s_mov_b32 s20, 0
	s_waitcnt lgkmcnt(0)
.LBB0_590:
	s_add_i32 s21, s20, 2
	s_add_u32 s0, s10, 0xfffc0080
	s_addc_u32 s1, s11, -1
	s_cmp_lt_u32 s20, 14
	s_cselect_b32 s94, s90, s24
	s_cselect_b32 s55, s1, s17
	s_cselect_b32 s54, s0, s16
	s_cselect_b32 s95, s91, s25
	s_cselect_b32 s51, s93, s27
	s_cselect_b32 s50, s92, s26
	s_add_u32 s44, s94, 0x80
	s_addc_u32 s45, s95, 0
	s_add_u32 s22, s54, 0x80
	s_addc_u32 s23, s55, 0
	s_add_u32 s96, s10, 0x20000
	s_addc_u32 s97, s11, 0
	s_add_u32 s0, s94, 0x20000
	s_addc_u32 s1, s95, 0
	s_add_u32 s62, s54, 0x20000
	s_addc_u32 s63, s55, 0
	s_add_u32 s52, s50, 0x20000
	s_addc_u32 s53, s51, 0
	s_add_u32 s48, s54, 0x40000
	s_addc_u32 s49, s55, 0
	s_add_u32 s28, s54, 0x60000
	s_addc_u32 s29, s55, 0
	s_add_u32 s46, s94, 0x20080
	s_addc_u32 s47, s95, 0
	s_add_u32 s30, s54, 0x20080
	s_addc_u32 s31, s55, 0
	s_add_u32 s18, s50, 0x80
	s_addc_u32 s19, s51, 0
	s_add_u32 s4, s50, 0x20080
	s_addc_u32 s5, s51, 0
	s_add_u32 s42, s10, 0x100
	s_addc_u32 s43, s11, 0
	s_add_u32 s90, s90, 0x100
	s_addc_u32 s91, s91, 0
	s_add_u32 s92, s92, 0x100
	s_addc_u32 s93, s93, 0
	ds_read_b128 v[80:83], v151
	ds_read_b128 v[84:87], v151 offset:1024
	ds_read_b128 v[88:91], v151 offset:2048
	ds_read_b128 v[92:95], v151 offset:3072
	ds_read_b128 v[144:147], v152
	ds_read_b128 v[160:163], v152 offset:1024
	ds_read_b128 v[164:167], v153
	ds_read_b128 v[168:171], v153 offset:1024
	ds_read_b128 v[172:175], v154
	ds_read_b128 v[178:181], v154 offset:1024
	ds_read_b128 v[192:195], v155
	ds_read_b128 v[196:199], v155 offset:1024
	s_mov_b32 m0, s79
	s_nop 0
	global_load_lds_dwordx4 v150, s[10:11]
	s_mov_b32 m0, s80
	s_nop 0
	global_load_lds_dwordx4 v150, s[96:97]
	s_waitcnt lgkmcnt(8)
	s_barrier
	s_setprio 1
	s_waitcnt lgkmcnt(7)
	v_mfma_f32_16x16x32_bf16 v[140:143], v[144:147], v[80:83], 0
	v_mfma_f32_16x16x32_bf16 v[136:139], v[144:147], v[88:91], 0
	s_waitcnt lgkmcnt(5)
	v_mfma_f32_16x16x32_bf16 v[124:127], v[164:167], v[80:83], 0
	v_mfma_f32_16x16x32_bf16 v[120:123], v[164:167], v[88:91], 0
	s_waitcnt lgkmcnt(3)
	v_mfma_f32_16x16x32_bf16 v[108:111], v[172:175], v[80:83], 0
	v_mfma_f32_16x16x32_bf16 v[104:107], v[172:175], v[88:91], 0
	s_waitcnt lgkmcnt(1)
	v_mfma_f32_16x16x32_bf16 v[76:79], v[192:195], v[80:83], 0
	v_mfma_f32_16x16x32_bf16 v[72:75], v[192:195], v[88:91], 0
	v_mfma_f32_16x16x32_bf16 v[140:143], v[160:163], v[84:87], v[140:143]
	v_mfma_f32_16x16x32_bf16 v[136:139], v[160:163], v[92:95], v[136:139]
	v_mfma_f32_16x16x32_bf16 v[124:127], v[168:171], v[84:87], v[124:127]
	v_mfma_f32_16x16x32_bf16 v[120:123], v[168:171], v[92:95], v[120:123]
	v_mfma_f32_16x16x32_bf16 v[108:111], v[178:181], v[84:87], v[108:111]
	v_mfma_f32_16x16x32_bf16 v[104:107], v[178:181], v[92:95], v[104:107]
	s_waitcnt lgkmcnt(0)
	v_mfma_f32_16x16x32_bf16 v[76:79], v[196:199], v[84:87], v[76:79]
	v_mfma_f32_16x16x32_bf16 v[72:75], v[196:199], v[92:95], v[72:75]
	s_setprio 0
	s_barrier
	ds_read_b128 v[200:203], v156
	ds_read_b128 v[204:207], v156 offset:1024
	ds_read_b128 v[208:211], v156 offset:2048
	ds_read_b128 v[212:215], v156 offset:3072
	s_mov_b32 m0, s39
	s_nop 0
	global_load_lds_dwordx4 v150, s[94:95]
	s_mov_b32 m0, s40
	s_nop 0
	global_load_lds_dwordx4 v150, s[0:1]
	s_barrier
	s_setprio 1
	s_waitcnt lgkmcnt(3)
	v_mfma_f32_16x16x32_bf16 v[132:135], v[144:147], v[200:203], 0
	s_waitcnt lgkmcnt(1)
	v_mfma_f32_16x16x32_bf16 v[128:131], v[144:147], v[208:211], 0
	v_mfma_f32_16x16x32_bf16 v[116:119], v[164:167], v[200:203], 0
	v_mfma_f32_16x16x32_bf16 v[112:115], v[164:167], v[208:211], 0
	v_mfma_f32_16x16x32_bf16 v[100:103], v[172:175], v[200:203], 0
	v_mfma_f32_16x16x32_bf16 v[96:99], v[172:175], v[208:211], 0
	v_mfma_f32_16x16x32_bf16 v[68:71], v[192:195], v[200:203], 0
	v_mfma_f32_16x16x32_bf16 v[64:67], v[192:195], v[208:211], 0
	v_mfma_f32_16x16x32_bf16 v[132:135], v[160:163], v[204:207], v[132:135]
	s_waitcnt lgkmcnt(0)
	v_mfma_f32_16x16x32_bf16 v[128:131], v[160:163], v[212:215], v[128:131]
	v_mfma_f32_16x16x32_bf16 v[116:119], v[168:171], v[204:207], v[116:119]
	v_mfma_f32_16x16x32_bf16 v[112:115], v[168:171], v[212:215], v[112:115]
	v_mfma_f32_16x16x32_bf16 v[100:103], v[178:181], v[204:207], v[100:103]
	v_mfma_f32_16x16x32_bf16 v[96:99], v[178:181], v[212:215], v[96:99]
	v_mfma_f32_16x16x32_bf16 v[68:71], v[196:199], v[204:207], v[68:71]
	v_mfma_f32_16x16x32_bf16 v[64:67], v[196:199], v[212:215], v[64:67]
	s_setprio 0
	s_barrier
	ds_read_b128 v[144:147], v152 offset:16384
	ds_read_b128 v[160:163], v152 offset:17408
	ds_read_b128 v[164:167], v153 offset:16384
	ds_read_b128 v[168:171], v153 offset:17408
	ds_read_b128 v[172:175], v154 offset:16384
	ds_read_b128 v[178:181], v154 offset:17408
	ds_read_b128 v[192:195], v155 offset:16384
	ds_read_b128 v[196:199], v155 offset:17408
	s_mov_b32 m0, s38
	s_nop 0
	global_load_lds_dwordx4 v150, s[54:55]
	s_mov_b32 m0, s41
	s_nop 0
	global_load_lds_dwordx4 v150, s[62:63]
	s_barrier
; #define STAGE_A(Ak_, b, h) do { const char* _s = (Ak_) + (h) * sHA; \
;     glds16(lds0 + ((b) * 2 + (h)) * (HT * 2), voffA, _s); glds16(lds0 + ((b) * 2 + (h)) * (HT * 2) + 8192, voffA, _s + s2A); } while (0)
; #define STAGE_B(Bk_, Bkh_, vh_, b, h) do { const char* _s = (h) ? (Bkh_) : (Bk_); const unsigned _v0 = (h) ? (vh_)[0] : voffB, _v1 = (h) ? (vh_)[1] : voffB; const long _d = (h) ? s2Bh : s2B; \
;     glds16(lds0 + (4 + (b) * 2 + (h)) * (HT * 2), _v0, _s); glds16(lds0 + (4 + (b) * 2 + (h)) * (HT * 2) + 8192, _v1, _s + _d); } while (0)
; #define LDA(dst, b, h) for (int m = 0; m < 4; ++m) for (int k = 0; k < 2; ++k) \
;     dst[m][k] = *reinterpret_cast<const bf16x8*>((char*)SA(b, h) + lds_byte(wr * 64 + m * 16 + fr, k * 32 + fq * 8))
; #define LDB(dst, b, h) for (int n = 0; n < 2; ++n) for (int k = 0; k < 2; ++k) \
;     dst[n][k] = *reinterpret_cast<const bf16x8*>((char*)SB(b, h) + lds_byte(wc * 32 + n * 16 + fr, k * 32 + fq * 8))
; #define WAIT_V(n) asm volatile("s_waitcnt vmcnt(" #n ")" ::: "memory")
; #define WAIT_L(n) asm volatile("s_waitcnt lgkmcnt(" #n ")" ::: "memory")
; template <int EPI>
; __device__ __forceinline__ void gemm_phase(const GemmDesc d, u16* shm, unsigned sx, unsigned srank, unsigned snloc) {
;     ...
;       for (int kt = 0; kt < nt; kt += 2) {
;         const bool lastk = (kt + 2 >= nt);
;         const char* A1 = Au + (long)(kt + 1) * sKA;
;         const char* A2 = lastk ? Aun : Au + (long)(kt + 2) * sKA;
;         const char* B2 = lastk ? Bun : Bu + (long)(kt + 2) * sKB;
;         const char* B2h = lastk ? Bunh : Buh + (long)(kt + 2) * sKB;
;         const unsigned vh[2] = {lastk ? voffBhn[0] : voffBh[0], lastk ? voffBhn[1] : voffBh[1]};
;         const char* A3 = A2 + sKA; const char* B3 = B2 + sKB; const char* B3h = B2h + sKB;
;         LDB(B0, 0, 0); SCHED; LDA(At, 0, 0); STAGE_A(A1, 1, 1);
;         WAIT_L(8); BAR; MMA(0, 0, At, B0); BAR; SCHED;
;         LDB(B1, 0, 1); STAGE_B(B2, B2h, vh, 0, 0);
;         BAR; MMA(0, 1, At, B1); BAR;
;         LDA(At, 0, 1); STAGE_A(A2, 0, 0);
;         BAR; MMA(1, 0, At, B0); BAR; SCHED;
;         STAGE_B(B2, B2h, vh, 0, 1);
;         WAIT_V(6); BAR; MMA(1, 1, At, B1); BAR;
;         LDB(B0, 1, 0); SCHED; LDA(At, 1, 0); STAGE_A(A2, 0, 1);
;         WAIT_L(8); BAR; MMA(0, 0, At, B0); BAR; SCHED;
;         LDB(B1, 1, 1); STAGE_B(B3, B3h, vh, 1, 0);
;         BAR; MMA(0, 1, At, B1); BAR;
	s_setprio 1
	s_waitcnt lgkmcnt(7)
	v_mfma_f32_16x16x32_bf16 v[60:63], v[144:147], v[80:83], 0
	v_mfma_f32_16x16x32_bf16 v[56:59], v[144:147], v[88:91], 0
	s_waitcnt lgkmcnt(5)
	v_mfma_f32_16x16x32_bf16 v[44:47], v[164:167], v[80:83], 0
	v_mfma_f32_16x16x32_bf16 v[40:43], v[164:167], v[88:91], 0
	s_waitcnt lgkmcnt(3)
	v_mfma_f32_16x16x32_bf16 v[28:31], v[172:175], v[80:83], 0
	v_mfma_f32_16x16x32_bf16 v[24:27], v[172:175], v[88:91], 0
	s_waitcnt lgkmcnt(1)
	v_mfma_f32_16x16x32_bf16 v[12:15], v[192:195], v[80:83], 0
	v_mfma_f32_16x16x32_bf16 v[8:11], v[192:195], v[88:91], 0
	v_mfma_f32_16x16x32_bf16 v[60:63], v[160:163], v[84:87], v[60:63]
	v_mfma_f32_16x16x32_bf16 v[56:59], v[160:163], v[92:95], v[56:59]
	v_mfma_f32_16x16x32_bf16 v[44:47], v[168:171], v[84:87], v[44:47]
	v_mfma_f32_16x16x32_bf16 v[40:43], v[168:171], v[92:95], v[40:43]
	v_mfma_f32_16x16x32_bf16 v[28:31], v[178:181], v[84:87], v[28:31]
	v_mfma_f32_16x16x32_bf16 v[24:27], v[178:181], v[92:95], v[24:27]
	s_waitcnt lgkmcnt(0)
	v_mfma_f32_16x16x32_bf16 v[12:15], v[196:199], v[84:87], v[12:15]
	v_mfma_f32_16x16x32_bf16 v[8:11], v[196:199], v[92:95], v[8:11]
	s_setprio 0
	s_barrier
	s_mov_b32 m0, s57
	s_nop 0
	global_load_lds_dwordx4 v150, s[50:51]
	s_mov_b32 m0, s59
	s_nop 0
	global_load_lds_dwordx4 v150, s[52:53]
	s_waitcnt vmcnt(6)
	s_barrier
	s_setprio 1
	v_mfma_f32_16x16x32_bf16 v[52:55], v[144:147], v[200:203], 0
	v_mfma_f32_16x16x32_bf16 v[48:51], v[144:147], v[208:211], 0
	v_mfma_f32_16x16x32_bf16 v[36:39], v[164:167], v[200:203], 0
	v_mfma_f32_16x16x32_bf16 v[32:35], v[164:167], v[208:211], 0
	v_mfma_f32_16x16x32_bf16 v[20:23], v[172:175], v[200:203], 0
	v_mfma_f32_16x16x32_bf16 v[16:19], v[172:175], v[208:211], 0
	v_mfma_f32_16x16x32_bf16 v[4:7], v[192:195], v[200:203], 0
	v_mfma_f32_16x16x32_bf16 v[0:3], v[192:195], v[208:211], 0
	v_mfma_f32_16x16x32_bf16 v[52:55], v[160:163], v[204:207], v[52:55]
	v_mfma_f32_16x16x32_bf16 v[48:51], v[160:163], v[212:215], v[48:51]
	v_mfma_f32_16x16x32_bf16 v[36:39], v[168:171], v[204:207], v[36:39]
	v_mfma_f32_16x16x32_bf16 v[32:35], v[168:171], v[212:215], v[32:35]
	v_mfma_f32_16x16x32_bf16 v[20:23], v[178:181], v[204:207], v[20:23]
	v_mfma_f32_16x16x32_bf16 v[16:19], v[178:181], v[212:215], v[16:19]
	v_mfma_f32_16x16x32_bf16 v[4:7], v[196:199], v[204:207], v[4:7]
	v_mfma_f32_16x16x32_bf16 v[0:3], v[196:199], v[212:215], v[0:3]
	s_setprio 0
	s_barrier
	ds_read_b128 v[80:83], v157
	ds_read_b128 v[84:87], v157 offset:1024
	ds_read_b128 v[88:91], v157 offset:2048
	ds_read_b128 v[92:95], v157 offset:3072
	ds_read_b128 v[144:147], v152 offset:32768
	ds_read_b128 v[160:163], v152 offset:33792
	ds_read_b128 v[164:167], v153 offset:32768
	ds_read_b128 v[168:171], v153 offset:33792
	ds_read_b128 v[172:175], v154 offset:32768
	ds_read_b128 v[178:181], v154 offset:33792
	ds_read_b128 v[192:195], v155 offset:32768
	ds_read_b128 v[196:199], v155 offset:33792
	s_mov_b32 m0, s64
	s_nop 0
	global_load_lds_dwordx4 v150, s[48:49]
	s_mov_b32 m0, s65
	s_nop 0
	global_load_lds_dwordx4 v150, s[28:29]
	s_waitcnt lgkmcnt(8)
	s_barrier
	s_setprio 1
	s_waitcnt lgkmcnt(7)
	v_mfma_f32_16x16x32_bf16 v[140:143], v[144:147], v[80:83], v[140:143]
	v_mfma_f32_16x16x32_bf16 v[136:139], v[144:147], v[88:91], v[136:139]
	s_waitcnt lgkmcnt(5)
	v_mfma_f32_16x16x32_bf16 v[124:127], v[164:167], v[80:83], v[124:127]
	v_mfma_f32_16x16x32_bf16 v[120:123], v[164:167], v[88:91], v[120:123]
	s_waitcnt lgkmcnt(3)
	v_mfma_f32_16x16x32_bf16 v[108:111], v[172:175], v[80:83], v[108:111]
	v_mfma_f32_16x16x32_bf16 v[104:107], v[172:175], v[88:91], v[104:107]
	s_waitcnt lgkmcnt(1)
	v_mfma_f32_16x16x32_bf16 v[76:79], v[192:195], v[80:83], v[76:79]
	v_mfma_f32_16x16x32_bf16 v[72:75], v[192:195], v[88:91], v[72:75]
	v_mfma_f32_16x16x32_bf16 v[140:143], v[160:163], v[84:87], v[140:143]
	v_mfma_f32_16x16x32_bf16 v[136:139], v[160:163], v[92:95], v[136:139]
	v_mfma_f32_16x16x32_bf16 v[124:127], v[168:171], v[84:87], v[124:127]
	v_mfma_f32_16x16x32_bf16 v[120:123], v[168:171], v[92:95], v[120:123]
	v_mfma_f32_16x16x32_bf16 v[108:111], v[178:181], v[84:87], v[108:111]
	v_mfma_f32_16x16x32_bf16 v[104:107], v[178:181], v[92:95], v[104:107]
	s_waitcnt lgkmcnt(0)
	v_mfma_f32_16x16x32_bf16 v[76:79], v[196:199], v[84:87], v[76:79]
	v_mfma_f32_16x16x32_bf16 v[72:75], v[196:199], v[92:95], v[72:75]
	s_setprio 0
	s_barrier
	ds_read_b128 v[200:203], v158
	ds_read_b128 v[204:207], v158 offset:1024
	ds_read_b128 v[208:211], v158 offset:2048
	ds_read_b128 v[212:215], v158 offset:3072
	s_mov_b32 m0, s71
	s_nop 0
	global_load_lds_dwordx4 v150, s[44:45]
	s_mov_b32 m0, s72
	s_nop 0
	global_load_lds_dwordx4 v150, s[46:47]
	s_barrier
	s_setprio 1
	s_waitcnt lgkmcnt(3)
	v_mfma_f32_16x16x32_bf16 v[132:135], v[144:147], v[200:203], v[132:135]
	s_waitcnt lgkmcnt(1)
	v_mfma_f32_16x16x32_bf16 v[128:131], v[144:147], v[208:211], v[128:131]
	v_mfma_f32_16x16x32_bf16 v[116:119], v[164:167], v[200:203], v[116:119]
	v_mfma_f32_16x16x32_bf16 v[112:115], v[164:167], v[208:211], v[112:115]
	v_mfma_f32_16x16x32_bf16 v[100:103], v[172:175], v[200:203], v[100:103]
	v_mfma_f32_16x16x32_bf16 v[96:99], v[172:175], v[208:211], v[96:99]
	v_mfma_f32_16x16x32_bf16 v[68:71], v[192:195], v[200:203], v[68:71]
	v_mfma_f32_16x16x32_bf16 v[64:67], v[192:195], v[208:211], v[64:67]
	v_mfma_f32_16x16x32_bf16 v[132:135], v[160:163], v[204:207], v[132:135]
	s_waitcnt lgkmcnt(0)
	v_mfma_f32_16x16x32_bf16 v[128:131], v[160:163], v[212:215], v[128:131]
	v_mfma_f32_16x16x32_bf16 v[116:119], v[168:171], v[204:207], v[116:119]
	v_mfma_f32_16x16x32_bf16 v[112:115], v[168:171], v[212:215], v[112:115]
	v_mfma_f32_16x16x32_bf16 v[100:103], v[178:181], v[204:207], v[100:103]
	v_mfma_f32_16x16x32_bf16 v[96:99], v[178:181], v[212:215], v[96:99]
	v_mfma_f32_16x16x32_bf16 v[68:71], v[196:199], v[204:207], v[68:71]
	v_mfma_f32_16x16x32_bf16 v[64:67], v[196:199], v[212:215], v[64:67]
	s_setprio 0
	s_barrier
; #define STAGE_A(Ak_, b, h) do { const char* _s = (Ak_) + (h) * sHA; \
;     glds16(lds0 + ((b) * 2 + (h)) * (HT * 2), voffA, _s); glds16(lds0 + ((b) * 2 + (h)) * (HT * 2) + 8192, voffA, _s + s2A); } while (0)
; #define STAGE_B(Bk_, Bkh_, vh_, b, h) do { const char* _s = (h) ? (Bkh_) : (Bk_); const unsigned _v0 = (h) ? (vh_)[0] : voffB, _v1 = (h) ? (vh_)[1] : voffB; const long _d = (h) ? s2Bh : s2B; \
;     glds16(lds0 + (4 + (b) * 2 + (h)) * (HT * 2), _v0, _s); glds16(lds0 + (4 + (b) * 2 + (h)) * (HT * 2) + 8192, _v1, _s + _d); } while (0)
; #define LDA(dst, b, h) for (int m = 0; m < 4; ++m) for (int k = 0; k < 2; ++k) \
;     dst[m][k] = *reinterpret_cast<const bf16x8*>((char*)SA(b, h) + lds_byte(wr * 64 + m * 16 + fr, k * 32 + fq * 8))
; #define WAIT_V(n) asm volatile("s_waitcnt vmcnt(" #n ")" ::: "memory")
; #define WAIT_L(n) asm volatile("s_waitcnt lgkmcnt(" #n ")" ::: "memory")
; template <int EPI>
; __device__ __forceinline__ void gemm_phase(const GemmDesc d, u16* shm, unsigned sx, unsigned srank, unsigned snloc) {
;     ...
;       for (int kt = 0; kt < nt; kt += 2) {
;         const bool lastk = (kt + 2 >= nt);
;         const char* A1 = Au + (long)(kt + 1) * sKA;
;         const char* A2 = lastk ? Aun : Au + (long)(kt + 2) * sKA;
;         const char* B2 = lastk ? Bun : Bu + (long)(kt + 2) * sKB;
;         const char* B2h = lastk ? Bunh : Buh + (long)(kt + 2) * sKB;
;         const unsigned vh[2] = {lastk ? voffBhn[0] : voffBh[0], lastk ? voffBhn[1] : voffBh[1]};
;         const char* A3 = A2 + sKA; const char* B3 = B2 + sKB; const char* B3h = B2h + sKB;
;         LDB(B0, 0, 0); SCHED; LDA(At, 0, 0); STAGE_A(A1, 1, 1);
;         WAIT_L(8); BAR; MMA(0, 0, At, B0); BAR; SCHED;
;         LDB(B1, 0, 1); STAGE_B(B2, B2h, vh, 0, 0);
;         BAR; MMA(0, 1, At, B1); BAR;
;         LDA(At, 0, 1); STAGE_A(A2, 0, 0);
;         BAR; MMA(1, 0, At, B0); BAR; SCHED;
;         STAGE_B(B2, B2h, vh, 0, 1);
;         WAIT_V(6); BAR; MMA(1, 1, At, B1); BAR;
;         LDB(B0, 1, 0); SCHED; LDA(At, 1, 0); STAGE_A(A2, 0, 1);
;         WAIT_L(8); BAR; MMA(0, 0, At, B0); BAR; SCHED;
;         LDB(B1, 1, 1); STAGE_B(B3, B3h, vh, 1, 0);
;         BAR; MMA(0, 1, At, B1); BAR;
;         LDA(At, 1, 1); STAGE_A(A3, 1, 0);
;         BAR; MMA(1, 0, At, B0); BAR; SCHED;
;         STAGE_B(B3, B3h, vh, 1, 1);
;         WAIT_V(6); BAR; MMA(1, 1, At, B1); BAR;
;       }
	ds_read_b128 v[144:147], v152 offset:49152
	ds_read_b128 v[160:163], v152 offset:50176
	ds_read_b128 v[164:167], v153 offset:49152
	ds_read_b128 v[168:171], v153 offset:50176
	ds_read_b128 v[172:175], v154 offset:49152
	ds_read_b128 v[178:181], v154 offset:50176
	ds_read_b128 v[192:195], v155 offset:49152
	ds_read_b128 v[196:199], v155 offset:50176
	s_mov_b32 m0, s73
	s_nop 0
	global_load_lds_dwordx4 v150, s[22:23]
	s_mov_b32 m0, s76
	s_nop 0
	global_load_lds_dwordx4 v150, s[30:31]
	s_barrier
	s_setprio 1
	s_waitcnt lgkmcnt(7)
	v_mfma_f32_16x16x32_bf16 v[60:63], v[144:147], v[80:83], v[60:63]
	v_mfma_f32_16x16x32_bf16 v[56:59], v[144:147], v[88:91], v[56:59]
	s_waitcnt lgkmcnt(5)
	v_mfma_f32_16x16x32_bf16 v[44:47], v[164:167], v[80:83], v[44:47]
	v_mfma_f32_16x16x32_bf16 v[40:43], v[164:167], v[88:91], v[40:43]
	s_waitcnt lgkmcnt(3)
	v_mfma_f32_16x16x32_bf16 v[28:31], v[172:175], v[80:83], v[28:31]
	v_mfma_f32_16x16x32_bf16 v[24:27], v[172:175], v[88:91], v[24:27]
	s_waitcnt lgkmcnt(1)
	v_mfma_f32_16x16x32_bf16 v[12:15], v[192:195], v[80:83], v[12:15]
	v_mfma_f32_16x16x32_bf16 v[8:11], v[192:195], v[88:91], v[8:11]
	v_mfma_f32_16x16x32_bf16 v[60:63], v[160:163], v[84:87], v[60:63]
	v_mfma_f32_16x16x32_bf16 v[56:59], v[160:163], v[92:95], v[56:59]
	v_mfma_f32_16x16x32_bf16 v[44:47], v[168:171], v[84:87], v[44:47]
	v_mfma_f32_16x16x32_bf16 v[40:43], v[168:171], v[92:95], v[40:43]
	v_mfma_f32_16x16x32_bf16 v[28:31], v[178:181], v[84:87], v[28:31]
	v_mfma_f32_16x16x32_bf16 v[24:27], v[178:181], v[92:95], v[24:27]
	s_waitcnt lgkmcnt(0)
	v_mfma_f32_16x16x32_bf16 v[12:15], v[196:199], v[84:87], v[12:15]
	v_mfma_f32_16x16x32_bf16 v[8:11], v[196:199], v[92:95], v[8:11]
	s_setprio 0
	s_barrier
	s_mov_b32 m0, s77
	s_nop 0
	global_load_lds_dwordx4 v150, s[18:19]
	s_mov_b32 m0, s78
	s_nop 0
	global_load_lds_dwordx4 v150, s[4:5]
	s_mov_b64 s[10:11], s[42:43]
	s_mov_b32 s20, s21
	s_add_i32 s21, s20, 2
	s_add_u32 s0, s10, 0xfffc0080
	s_addc_u32 s1, s11, -1
	s_cmp_lt_u32 s20, 14
	s_cselect_b32 s94, s90, s24
	s_cselect_b32 s55, s1, s17
	s_cselect_b32 s54, s0, s16
	s_cselect_b32 s95, s91, s25
	s_cselect_b32 s51, s93, s27
	s_cselect_b32 s50, s92, s26
	s_add_u32 s44, s94, 0x80
	s_addc_u32 s45, s95, 0
	s_add_u32 s22, s54, 0x80
	s_addc_u32 s23, s55, 0
	s_add_u32 s96, s10, 0x20000
	s_addc_u32 s97, s11, 0
	s_add_u32 s0, s94, 0x20000
	s_addc_u32 s1, s95, 0
	s_add_u32 s62, s54, 0x20000
	s_addc_u32 s63, s55, 0
	s_add_u32 s52, s50, 0x20000
	s_addc_u32 s53, s51, 0
	s_add_u32 s48, s54, 0x40000
	s_addc_u32 s49, s55, 0
	s_add_u32 s28, s54, 0x60000
	s_addc_u32 s29, s55, 0
	s_add_u32 s46, s94, 0x20080
	s_addc_u32 s47, s95, 0
	s_add_u32 s30, s54, 0x20080
	s_addc_u32 s31, s55, 0
	s_add_u32 s18, s50, 0x80
	s_addc_u32 s19, s51, 0
	s_add_u32 s4, s50, 0x20080
	s_addc_u32 s5, s51, 0
	s_add_u32 s42, s10, 0x100
	s_addc_u32 s43, s11, 0
	s_add_u32 s90, s90, 0x100
	s_addc_u32 s91, s91, 0
	s_add_u32 s92, s92, 0x100
	s_addc_u32 s93, s93, 0
	s_waitcnt vmcnt(6)
	s_barrier
	s_setprio 1
	v_mfma_f32_16x16x32_bf16 v[52:55], v[144:147], v[200:203], v[52:55]
	v_mfma_f32_16x16x32_bf16 v[48:51], v[144:147], v[208:211], v[48:51]
	v_mfma_f32_16x16x32_bf16 v[36:39], v[164:167], v[200:203], v[36:39]
	v_mfma_f32_16x16x32_bf16 v[32:35], v[164:167], v[208:211], v[32:35]
	v_mfma_f32_16x16x32_bf16 v[20:23], v[172:175], v[200:203], v[20:23]
	v_mfma_f32_16x16x32_bf16 v[16:19], v[172:175], v[208:211], v[16:19]
	v_mfma_f32_16x16x32_bf16 v[4:7], v[192:195], v[200:203], v[4:7]
	v_mfma_f32_16x16x32_bf16 v[0:3], v[192:195], v[208:211], v[0:3]
	v_mfma_f32_16x16x32_bf16 v[52:55], v[160:163], v[204:207], v[52:55]
	v_mfma_f32_16x16x32_bf16 v[48:51], v[160:163], v[212:215], v[48:51]
	v_mfma_f32_16x16x32_bf16 v[36:39], v[168:171], v[204:207], v[36:39]
	v_mfma_f32_16x16x32_bf16 v[32:35], v[168:171], v[212:215], v[32:35]
	v_mfma_f32_16x16x32_bf16 v[20:23], v[178:181], v[204:207], v[20:23]
	v_mfma_f32_16x16x32_bf16 v[16:19], v[178:181], v[212:215], v[16:19]
	v_mfma_f32_16x16x32_bf16 v[4:7], v[196:199], v[204:207], v[4:7]
	v_mfma_f32_16x16x32_bf16 v[0:3], v[196:199], v[212:215], v[0:3]
	s_setprio 0
	s_barrier
.Lk_fout:
	ds_read_b128 v[80:83], v151
	ds_read_b128 v[84:87], v151 offset:1024
	ds_read_b128 v[88:91], v151 offset:2048
	ds_read_b128 v[92:95], v151 offset:3072
	ds_read_b128 v[144:147], v152
	ds_read_b128 v[160:163], v152 offset:1024
	ds_read_b128 v[164:167], v153
	ds_read_b128 v[168:171], v153 offset:1024
	ds_read_b128 v[172:175], v154
	ds_read_b128 v[178:181], v154 offset:1024
	ds_read_b128 v[192:195], v155
	ds_read_b128 v[196:199], v155 offset:1024
	s_mov_b32 m0, s79
	s_nop 0
	global_load_lds_dwordx4 v150, s[10:11]
	s_mov_b32 m0, s80
	s_nop 0
	global_load_lds_dwordx4 v150, s[96:97]
	s_waitcnt lgkmcnt(8)
	s_barrier
	s_setprio 1
	s_waitcnt lgkmcnt(7)
	v_mfma_f32_16x16x32_bf16 v[140:143], v[144:147], v[80:83], v[140:143]
	v_mfma_f32_16x16x32_bf16 v[136:139], v[144:147], v[88:91], v[136:139]
	s_waitcnt lgkmcnt(5)
	v_mfma_f32_16x16x32_bf16 v[124:127], v[164:167], v[80:83], v[124:127]
	v_mfma_f32_16x16x32_bf16 v[120:123], v[164:167], v[88:91], v[120:123]
	s_waitcnt lgkmcnt(3)
	v_mfma_f32_16x16x32_bf16 v[108:111], v[172:175], v[80:83], v[108:111]
	v_mfma_f32_16x16x32_bf16 v[104:107], v[172:175], v[88:91], v[104:107]
	s_waitcnt lgkmcnt(1)
	v_mfma_f32_16x16x32_bf16 v[76:79], v[192:195], v[80:83], v[76:79]
	v_mfma_f32_16x16x32_bf16 v[72:75], v[192:195], v[88:91], v[72:75]
	v_mfma_f32_16x16x32_bf16 v[140:143], v[160:163], v[84:87], v[140:143]
	v_mfma_f32_16x16x32_bf16 v[136:139], v[160:163], v[92:95], v[136:139]
	v_mfma_f32_16x16x32_bf16 v[124:127], v[168:171], v[84:87], v[124:127]
	v_mfma_f32_16x16x32_bf16 v[120:123], v[168:171], v[92:95], v[120:123]
	v_mfma_f32_16x16x32_bf16 v[108:111], v[178:181], v[84:87], v[108:111]
	v_mfma_f32_16x16x32_bf16 v[104:107], v[178:181], v[92:95], v[104:107]
	s_waitcnt lgkmcnt(0)
	v_mfma_f32_16x16x32_bf16 v[76:79], v[196:199], v[84:87], v[76:79]
	v_mfma_f32_16x16x32_bf16 v[72:75], v[196:199], v[92:95], v[72:75]
	s_setprio 0
	s_barrier
; #define STAGE_A(Ak_, b, h) do { const char* _s = (Ak_) + (h) * sHA; \
;     glds16(lds0 + ((b) * 2 + (h)) * (HT * 2), voffA, _s); glds16(lds0 + ((b) * 2 + (h)) * (HT * 2) + 8192, voffA, _s + s2A); } while (0)
; #define STAGE_B(Bk_, Bkh_, vh_, b, h) do { const char* _s = (h) ? (Bkh_) : (Bk_); const unsigned _v0 = (h) ? (vh_)[0] : voffB, _v1 = (h) ? (vh_)[1] : voffB; const long _d = (h) ? s2Bh : s2B; \
;     glds16(lds0 + (4 + (b) * 2 + (h)) * (HT * 2), _v0, _s); glds16(lds0 + (4 + (b) * 2 + (h)) * (HT * 2) + 8192, _v1, _s + _d); } while (0)
; #define LDA(dst, b, h) for (int m = 0; m < 4; ++m) for (int k = 0; k < 2; ++k) \
;     dst[m][k] = *reinterpret_cast<const bf16x8*>((char*)SA(b, h) + lds_byte(wr * 64 + m * 16 + fr, k * 32 + fq * 8))
; #define LDB(dst, b, h) for (int n = 0; n < 2; ++n) for (int k = 0; k < 2; ++k) \
;     dst[n][k] = *reinterpret_cast<const bf16x8*>((char*)SB(b, h) + lds_byte(wc * 32 + n * 16 + fr, k * 32 + fq * 8))
; #define MMA(ai, bj, At_, Bt_) do { __builtin_amdgcn_s_setprio(1); \
;     for (int m = 0; m < 4; ++m) for (int n = 0; n < 2; ++n) for (int k = 0; k < 2; ++k) \
;       acc[ai][bj][m][n] = __builtin_amdgcn_mfma_f32_16x16x32_bf16(At_[m][k], Bt_[n][k], acc[ai][bj][m][n], 0, 0, 0); \
;     __builtin_amdgcn_s_setprio(0); } while (0)
; #define WAIT_V(n) asm volatile("s_waitcnt vmcnt(" #n ")" ::: "memory")
; #define WAIT_L(n) asm volatile("s_waitcnt lgkmcnt(" #n ")" ::: "memory")
; #define BAR __builtin_amdgcn_s_barrier()
; #define SCHED __builtin_amdgcn_sched_barrier(0)
; template <int EPI>
; __device__ __forceinline__ void gemm_phase(const GemmDesc d, u16* shm, unsigned sx, unsigned srank, unsigned snloc) {
;     ...
;         LDB(B1, 0, 1); STAGE_B(B2, B2h, vh, 0, 0);
;         BAR; MMA(0, 1, At, B1); BAR;
;         LDA(At, 0, 1); STAGE_A(A2, 0, 0);
;         BAR; MMA(1, 0, At, B0); BAR; SCHED;
;         STAGE_B(B2, B2h, vh, 0, 1);
;         WAIT_V(6); BAR; MMA(1, 1, At, B1); BAR;
;         LDB(B0, 1, 0); SCHED; LDA(At, 1, 0); STAGE_A(A2, 0, 1);
;         WAIT_L(8); BAR; MMA(0, 0, At, B0); BAR; SCHED;
;         LDB(B1, 1, 1); STAGE_B(B3, B3h, vh, 1, 0);
	ds_read_b128 v[200:203], v156
	ds_read_b128 v[204:207], v156 offset:1024
	ds_read_b128 v[208:211], v156 offset:2048
	ds_read_b128 v[212:215], v156 offset:3072
	s_mov_b32 m0, s39
	s_nop 0
	global_load_lds_dwordx4 v150, s[94:95]
	s_mov_b32 m0, s40
	s_nop 0
	global_load_lds_dwordx4 v150, s[0:1]
	s_barrier
	s_setprio 1
	s_waitcnt lgkmcnt(3)
	v_mfma_f32_16x16x32_bf16 v[132:135], v[144:147], v[200:203], v[132:135]
	s_waitcnt lgkmcnt(1)
	v_mfma_f32_16x16x32_bf16 v[128:131], v[144:147], v[208:211], v[128:131]
	v_mfma_f32_16x16x32_bf16 v[116:119], v[164:167], v[200:203], v[116:119]
	v_mfma_f32_16x16x32_bf16 v[112:115], v[164:167], v[208:211], v[112:115]
	v_mfma_f32_16x16x32_bf16 v[100:103], v[172:175], v[200:203], v[100:103]
	v_mfma_f32_16x16x32_bf16 v[96:99], v[172:175], v[208:211], v[96:99]
	v_mfma_f32_16x16x32_bf16 v[68:71], v[192:195], v[200:203], v[68:71]
	v_mfma_f32_16x16x32_bf16 v[64:67], v[192:195], v[208:211], v[64:67]
	v_mfma_f32_16x16x32_bf16 v[132:135], v[160:163], v[204:207], v[132:135]
	s_waitcnt lgkmcnt(0)
	v_mfma_f32_16x16x32_bf16 v[128:131], v[160:163], v[212:215], v[128:131]
	v_mfma_f32_16x16x32_bf16 v[116:119], v[168:171], v[204:207], v[116:119]
	v_mfma_f32_16x16x32_bf16 v[112:115], v[168:171], v[212:215], v[112:115]
	v_mfma_f32_16x16x32_bf16 v[100:103], v[178:181], v[204:207], v[100:103]
	v_mfma_f32_16x16x32_bf16 v[96:99], v[178:181], v[212:215], v[96:99]
	v_mfma_f32_16x16x32_bf16 v[68:71], v[196:199], v[204:207], v[68:71]
	v_mfma_f32_16x16x32_bf16 v[64:67], v[196:199], v[212:215], v[64:67]
	s_setprio 0
	s_barrier
	ds_read_b128 v[144:147], v152 offset:16384
	ds_read_b128 v[160:163], v152 offset:17408
	ds_read_b128 v[164:167], v153 offset:16384
	ds_read_b128 v[168:171], v153 offset:17408
	ds_read_b128 v[172:175], v154 offset:16384
	ds_read_b128 v[178:181], v154 offset:17408
	ds_read_b128 v[192:195], v155 offset:16384
	ds_read_b128 v[196:199], v155 offset:17408
	s_mov_b32 m0, s38
	s_nop 0
	global_load_lds_dwordx4 v150, s[54:55]
	s_mov_b32 m0, s41
	s_nop 0
	global_load_lds_dwordx4 v150, s[62:63]
	s_barrier
	s_setprio 1
	s_waitcnt lgkmcnt(7)
	v_mfma_f32_16x16x32_bf16 v[60:63], v[144:147], v[80:83], v[60:63]
	v_mfma_f32_16x16x32_bf16 v[56:59], v[144:147], v[88:91], v[56:59]
	s_waitcnt lgkmcnt(5)
	v_mfma_f32_16x16x32_bf16 v[44:47], v[164:167], v[80:83], v[44:47]
	v_mfma_f32_16x16x32_bf16 v[40:43], v[164:167], v[88:91], v[40:43]
	s_waitcnt lgkmcnt(3)
	v_mfma_f32_16x16x32_bf16 v[28:31], v[172:175], v[80:83], v[28:31]
	v_mfma_f32_16x16x32_bf16 v[24:27], v[172:175], v[88:91], v[24:27]
	s_waitcnt lgkmcnt(1)
	v_mfma_f32_16x16x32_bf16 v[12:15], v[192:195], v[80:83], v[12:15]
	v_mfma_f32_16x16x32_bf16 v[8:11], v[192:195], v[88:91], v[8:11]
	v_mfma_f32_16x16x32_bf16 v[60:63], v[160:163], v[84:87], v[60:63]
	v_mfma_f32_16x16x32_bf16 v[56:59], v[160:163], v[92:95], v[56:59]
	v_mfma_f32_16x16x32_bf16 v[44:47], v[168:171], v[84:87], v[44:47]
	v_mfma_f32_16x16x32_bf16 v[40:43], v[168:171], v[92:95], v[40:43]
	v_mfma_f32_16x16x32_bf16 v[28:31], v[178:181], v[84:87], v[28:31]
	v_mfma_f32_16x16x32_bf16 v[24:27], v[178:181], v[92:95], v[24:27]
	s_waitcnt lgkmcnt(0)
	v_mfma_f32_16x16x32_bf16 v[12:15], v[196:199], v[84:87], v[12:15]
	v_mfma_f32_16x16x32_bf16 v[8:11], v[196:199], v[92:95], v[8:11]
	s_setprio 0
	s_barrier
	s_mov_b32 m0, s57
	s_nop 0
	global_load_lds_dwordx4 v150, s[50:51]
	s_mov_b32 m0, s59
	s_nop 0
	global_load_lds_dwordx4 v150, s[52:53]
	s_waitcnt vmcnt(6)
	s_barrier
	s_setprio 1
	v_mfma_f32_16x16x32_bf16 v[52:55], v[144:147], v[200:203], v[52:55]
	v_mfma_f32_16x16x32_bf16 v[48:51], v[144:147], v[208:211], v[48:51]
	v_mfma_f32_16x16x32_bf16 v[36:39], v[164:167], v[200:203], v[36:39]
	v_mfma_f32_16x16x32_bf16 v[32:35], v[164:167], v[208:211], v[32:35]
	v_mfma_f32_16x16x32_bf16 v[20:23], v[172:175], v[200:203], v[20:23]
	v_mfma_f32_16x16x32_bf16 v[16:19], v[172:175], v[208:211], v[16:19]
	v_mfma_f32_16x16x32_bf16 v[4:7], v[192:195], v[200:203], v[4:7]
	v_mfma_f32_16x16x32_bf16 v[0:3], v[192:195], v[208:211], v[0:3]
	v_mfma_f32_16x16x32_bf16 v[52:55], v[160:163], v[204:207], v[52:55]
	v_mfma_f32_16x16x32_bf16 v[48:51], v[160:163], v[212:215], v[48:51]
	v_mfma_f32_16x16x32_bf16 v[36:39], v[168:171], v[204:207], v[36:39]
	v_mfma_f32_16x16x32_bf16 v[32:35], v[168:171], v[212:215], v[32:35]
	v_mfma_f32_16x16x32_bf16 v[20:23], v[178:181], v[204:207], v[20:23]
	v_mfma_f32_16x16x32_bf16 v[16:19], v[178:181], v[212:215], v[16:19]
	v_mfma_f32_16x16x32_bf16 v[4:7], v[196:199], v[204:207], v[4:7]
	v_mfma_f32_16x16x32_bf16 v[0:3], v[196:199], v[212:215], v[0:3]
	s_setprio 0
	s_barrier
	ds_read_b128 v[80:83], v157
	ds_read_b128 v[84:87], v157 offset:1024
	ds_read_b128 v[88:91], v157 offset:2048
	ds_read_b128 v[92:95], v157 offset:3072
	ds_read_b128 v[144:147], v152 offset:32768
	ds_read_b128 v[160:163], v152 offset:33792
	ds_read_b128 v[164:167], v153 offset:32768
	ds_read_b128 v[168:171], v153 offset:33792
	ds_read_b128 v[172:175], v154 offset:32768
	ds_read_b128 v[178:181], v154 offset:33792
	ds_read_b128 v[192:195], v155 offset:32768
	ds_read_b128 v[196:199], v155 offset:33792
	s_mov_b32 m0, s64
	s_nop 0
	global_load_lds_dwordx4 v150, s[48:49]
	s_mov_b32 m0, s65
	s_nop 0
	global_load_lds_dwordx4 v150, s[28:29]
	s_waitcnt lgkmcnt(8)
	s_barrier
; #define STAGE_A(Ak_, b, h) do { const char* _s = (Ak_) + (h) * sHA; \
;     glds16(lds0 + ((b) * 2 + (h)) * (HT * 2), voffA, _s); glds16(lds0 + ((b) * 2 + (h)) * (HT * 2) + 8192, voffA, _s + s2A); } while (0)
; #define STAGE_B(Bk_, Bkh_, vh_, b, h) do { const char* _s = (h) ? (Bkh_) : (Bk_); const unsigned _v0 = (h) ? (vh_)[0] : voffB, _v1 = (h) ? (vh_)[1] : voffB; const long _d = (h) ? s2Bh : s2B; \
;     glds16(lds0 + (4 + (b) * 2 + (h)) * (HT * 2), _v0, _s); glds16(lds0 + (4 + (b) * 2 + (h)) * (HT * 2) + 8192, _v1, _s + _d); } while (0)
; #define LDA(dst, b, h) for (int m = 0; m < 4; ++m) for (int k = 0; k < 2; ++k) \
;     dst[m][k] = *reinterpret_cast<const bf16x8*>((char*)SA(b, h) + lds_byte(wr * 64 + m * 16 + fr, k * 32 + fq * 8))
; #define LDB(dst, b, h) for (int n = 0; n < 2; ++n) for (int k = 0; k < 2; ++k) \
;     dst[n][k] = *reinterpret_cast<const bf16x8*>((char*)SB(b, h) + lds_byte(wc * 32 + n * 16 + fr, k * 32 + fq * 8))
; #define MMA(ai, bj, At_, Bt_) do { __builtin_amdgcn_s_setprio(1); \
;     for (int m = 0; m < 4; ++m) for (int n = 0; n < 2; ++n) for (int k = 0; k < 2; ++k) \
;       acc[ai][bj][m][n] = __builtin_amdgcn_mfma_f32_16x16x32_bf16(At_[m][k], Bt_[n][k], acc[ai][bj][m][n], 0, 0, 0); \
;     __builtin_amdgcn_s_setprio(0); } while (0)
; #define WAIT_V(n) asm volatile("s_waitcnt vmcnt(" #n ")" ::: "memory")
; #define WAIT_L(n) asm volatile("s_waitcnt lgkmcnt(" #n ")" ::: "memory")
; #define BAR __builtin_amdgcn_s_barrier()
; #define SCHED __builtin_amdgcn_sched_barrier(0)
; template <int EPI>
; __device__ __forceinline__ void gemm_phase(const GemmDesc d, u16* shm, unsigned sx, unsigned srank, unsigned snloc) {
;     ...
;         LDB(B0, 1, 0); SCHED; LDA(At, 1, 0); STAGE_A(A2, 0, 1);
;         WAIT_L(8); BAR; MMA(0, 0, At, B0); BAR; SCHED;
;         LDB(B1, 1, 1); STAGE_B(B3, B3h, vh, 1, 0);
;         BAR; MMA(0, 1, At, B1); BAR;
;         LDA(At, 1, 1); STAGE_A(A3, 1, 0);
;         BAR; MMA(1, 0, At, B0); BAR; SCHED;
;         STAGE_B(B3, B3h, vh, 1, 1);
;         WAIT_V(6); BAR; MMA(1, 1, At, B1); BAR;
;       }
	s_setprio 1
	s_waitcnt lgkmcnt(7)
	v_mfma_f32_16x16x32_bf16 v[140:143], v[144:147], v[80:83], v[140:143]
	v_mfma_f32_16x16x32_bf16 v[136:139], v[144:147], v[88:91], v[136:139]
	s_waitcnt lgkmcnt(5)
	v_mfma_f32_16x16x32_bf16 v[124:127], v[164:167], v[80:83], v[124:127]
	v_mfma_f32_16x16x32_bf16 v[120:123], v[164:167], v[88:91], v[120:123]
	s_waitcnt lgkmcnt(3)
	v_mfma_f32_16x16x32_bf16 v[108:111], v[172:175], v[80:83], v[108:111]
	v_mfma_f32_16x16x32_bf16 v[104:107], v[172:175], v[88:91], v[104:107]
	s_waitcnt lgkmcnt(1)
	v_mfma_f32_16x16x32_bf16 v[76:79], v[192:195], v[80:83], v[76:79]
	v_mfma_f32_16x16x32_bf16 v[72:75], v[192:195], v[88:91], v[72:75]
	v_mfma_f32_16x16x32_bf16 v[140:143], v[160:163], v[84:87], v[140:143]
	v_mfma_f32_16x16x32_bf16 v[136:139], v[160:163], v[92:95], v[136:139]
	v_mfma_f32_16x16x32_bf16 v[124:127], v[168:171], v[84:87], v[124:127]
	v_mfma_f32_16x16x32_bf16 v[120:123], v[168:171], v[92:95], v[120:123]
	v_mfma_f32_16x16x32_bf16 v[108:111], v[178:181], v[84:87], v[108:111]
	v_mfma_f32_16x16x32_bf16 v[104:107], v[178:181], v[92:95], v[104:107]
	s_waitcnt lgkmcnt(0)
	v_mfma_f32_16x16x32_bf16 v[76:79], v[196:199], v[84:87], v[76:79]
	v_mfma_f32_16x16x32_bf16 v[72:75], v[196:199], v[92:95], v[72:75]
	s_setprio 0
	s_barrier
	ds_read_b128 v[200:203], v158
	ds_read_b128 v[204:207], v158 offset:1024
	ds_read_b128 v[208:211], v158 offset:2048
	ds_read_b128 v[212:215], v158 offset:3072
	s_mov_b32 m0, s71
	s_nop 0
	global_load_lds_dwordx4 v150, s[44:45]
	s_mov_b32 m0, s72
	s_nop 0
	global_load_lds_dwordx4 v150, s[46:47]
	s_barrier
	s_setprio 1
	s_waitcnt lgkmcnt(3)
	v_mfma_f32_16x16x32_bf16 v[132:135], v[144:147], v[200:203], v[132:135]
	s_waitcnt lgkmcnt(1)
	v_mfma_f32_16x16x32_bf16 v[128:131], v[144:147], v[208:211], v[128:131]
	v_mfma_f32_16x16x32_bf16 v[116:119], v[164:167], v[200:203], v[116:119]
	v_mfma_f32_16x16x32_bf16 v[112:115], v[164:167], v[208:211], v[112:115]
	v_mfma_f32_16x16x32_bf16 v[100:103], v[172:175], v[200:203], v[100:103]
	v_mfma_f32_16x16x32_bf16 v[96:99], v[172:175], v[208:211], v[96:99]
	v_mfma_f32_16x16x32_bf16 v[68:71], v[192:195], v[200:203], v[68:71]
	v_mfma_f32_16x16x32_bf16 v[64:67], v[192:195], v[208:211], v[64:67]
	v_mfma_f32_16x16x32_bf16 v[132:135], v[160:163], v[204:207], v[132:135]
	s_waitcnt lgkmcnt(0)
	v_mfma_f32_16x16x32_bf16 v[128:131], v[160:163], v[212:215], v[128:131]
	v_mfma_f32_16x16x32_bf16 v[116:119], v[168:171], v[204:207], v[116:119]
	v_mfma_f32_16x16x32_bf16 v[112:115], v[168:171], v[212:215], v[112:115]
	v_mfma_f32_16x16x32_bf16 v[100:103], v[178:181], v[204:207], v[100:103]
	v_mfma_f32_16x16x32_bf16 v[96:99], v[178:181], v[212:215], v[96:99]
	v_mfma_f32_16x16x32_bf16 v[68:71], v[196:199], v[204:207], v[68:71]
	v_mfma_f32_16x16x32_bf16 v[64:67], v[196:199], v[212:215], v[64:67]
	s_setprio 0
	s_barrier
	ds_read_b128 v[144:147], v152 offset:49152
	ds_read_b128 v[160:163], v152 offset:50176
	ds_read_b128 v[164:167], v153 offset:49152
	ds_read_b128 v[168:171], v153 offset:50176
	ds_read_b128 v[172:175], v154 offset:49152
	ds_read_b128 v[178:181], v154 offset:50176
	ds_read_b128 v[192:195], v155 offset:49152
	ds_read_b128 v[196:199], v155 offset:50176
	s_mov_b32 m0, s73
	s_nop 0
	global_load_lds_dwordx4 v150, s[22:23]
	s_mov_b32 m0, s76
	s_nop 0
	global_load_lds_dwordx4 v150, s[30:31]
	s_barrier
	s_setprio 1
	s_waitcnt lgkmcnt(7)
	v_mfma_f32_16x16x32_bf16 v[60:63], v[144:147], v[80:83], v[60:63]
	v_mfma_f32_16x16x32_bf16 v[56:59], v[144:147], v[88:91], v[56:59]
	s_waitcnt lgkmcnt(5)
	v_mfma_f32_16x16x32_bf16 v[44:47], v[164:167], v[80:83], v[44:47]
	v_mfma_f32_16x16x32_bf16 v[40:43], v[164:167], v[88:91], v[40:43]
	s_waitcnt lgkmcnt(3)
	v_mfma_f32_16x16x32_bf16 v[28:31], v[172:175], v[80:83], v[28:31]
	v_mfma_f32_16x16x32_bf16 v[24:27], v[172:175], v[88:91], v[24:27]
	s_waitcnt lgkmcnt(1)
	v_mfma_f32_16x16x32_bf16 v[12:15], v[192:195], v[80:83], v[12:15]
	v_mfma_f32_16x16x32_bf16 v[8:11], v[192:195], v[88:91], v[8:11]
	v_mfma_f32_16x16x32_bf16 v[60:63], v[160:163], v[84:87], v[60:63]
	v_mfma_f32_16x16x32_bf16 v[56:59], v[160:163], v[92:95], v[56:59]
	v_mfma_f32_16x16x32_bf16 v[44:47], v[168:171], v[84:87], v[44:47]
	v_mfma_f32_16x16x32_bf16 v[40:43], v[168:171], v[92:95], v[40:43]
	v_mfma_f32_16x16x32_bf16 v[28:31], v[178:181], v[84:87], v[28:31]
	v_mfma_f32_16x16x32_bf16 v[24:27], v[178:181], v[92:95], v[24:27]
	s_waitcnt lgkmcnt(0)
	v_mfma_f32_16x16x32_bf16 v[12:15], v[196:199], v[84:87], v[12:15]
	v_mfma_f32_16x16x32_bf16 v[8:11], v[196:199], v[92:95], v[8:11]
	s_setprio 0
	s_barrier
	s_mov_b32 m0, s77
	s_nop 0
	global_load_lds_dwordx4 v150, s[18:19]
	s_mov_b32 m0, s78
	s_nop 0
	global_load_lds_dwordx4 v150, s[4:5]
	s_mov_b64 s[10:11], s[42:43]
	s_mov_b32 s20, s21
	s_add_i32 s21, s20, 2
	s_add_u32 s0, s10, 0xfffc0080
	s_addc_u32 s1, s11, -1
	s_cmp_lt_u32 s20, 14
	s_cselect_b32 s94, s90, s24
	s_cselect_b32 s55, s1, s17
	s_cselect_b32 s54, s0, s16
	s_cselect_b32 s95, s91, s25
	s_cselect_b32 s51, s93, s27
	s_cselect_b32 s50, s92, s26
	s_add_u32 s44, s94, 0x80
	s_addc_u32 s45, s95, 0
	s_add_u32 s22, s54, 0x80
	s_addc_u32 s23, s55, 0
	s_add_u32 s96, s10, 0x20000
	s_addc_u32 s97, s11, 0
	s_add_u32 s0, s94, 0x20000
	s_addc_u32 s1, s95, 0
	s_add_u32 s62, s54, 0x20000
	s_addc_u32 s63, s55, 0
	s_add_u32 s52, s50, 0x20000
	s_addc_u32 s53, s51, 0
	s_add_u32 s48, s54, 0x40000
	s_addc_u32 s49, s55, 0
	s_add_u32 s28, s54, 0x60000
	s_addc_u32 s29, s55, 0
	s_add_u32 s46, s94, 0x20080
	s_addc_u32 s47, s95, 0
	s_add_u32 s30, s54, 0x20080
	s_addc_u32 s31, s55, 0
	s_add_u32 s18, s50, 0x80
	s_addc_u32 s19, s51, 0
	s_add_u32 s4, s50, 0x20080
	s_addc_u32 s5, s51, 0
	s_add_u32 s42, s10, 0x100
	s_addc_u32 s43, s11, 0
	s_add_u32 s90, s90, 0x100
	s_addc_u32 s91, s91, 0
	s_add_u32 s92, s92, 0x100
	s_addc_u32 s93, s93, 0
	s_waitcnt vmcnt(6)
	s_barrier
	s_setprio 1
	v_mfma_f32_16x16x32_bf16 v[52:55], v[144:147], v[200:203], v[52:55]
	v_mfma_f32_16x16x32_bf16 v[48:51], v[144:147], v[208:211], v[48:51]
	v_mfma_f32_16x16x32_bf16 v[36:39], v[164:167], v[200:203], v[36:39]
	v_mfma_f32_16x16x32_bf16 v[32:35], v[164:167], v[208:211], v[32:35]
	v_mfma_f32_16x16x32_bf16 v[20:23], v[172:175], v[200:203], v[20:23]
	v_mfma_f32_16x16x32_bf16 v[16:19], v[172:175], v[208:211], v[16:19]
	v_mfma_f32_16x16x32_bf16 v[4:7], v[192:195], v[200:203], v[4:7]
	v_mfma_f32_16x16x32_bf16 v[0:3], v[192:195], v[208:211], v[0:3]
	v_mfma_f32_16x16x32_bf16 v[52:55], v[160:163], v[204:207], v[52:55]
	v_mfma_f32_16x16x32_bf16 v[48:51], v[160:163], v[212:215], v[48:51]
	v_mfma_f32_16x16x32_bf16 v[36:39], v[168:171], v[204:207], v[36:39]
	v_mfma_f32_16x16x32_bf16 v[32:35], v[168:171], v[212:215], v[32:35]
	v_mfma_f32_16x16x32_bf16 v[20:23], v[178:181], v[204:207], v[20:23]
	v_mfma_f32_16x16x32_bf16 v[16:19], v[178:181], v[212:215], v[16:19]
	v_mfma_f32_16x16x32_bf16 v[4:7], v[196:199], v[204:207], v[4:7]
	v_mfma_f32_16x16x32_bf16 v[0:3], v[196:199], v[212:215], v[0:3]
	s_setprio 0
	s_cmp_lt_u32 s20, 16
	s_barrier
	s_cbranch_scc1 .Lk_fout
	s_and_saveexec_b64 s[4:5], s[8:9]
	s_cbranch_execz .LBB0_593
	s_barrier

; #define DECODE(t_, z_, pm_, pn_) do { if constexpr (EPI == E_CHDFT) { z_ = (t_) >> 5; pm_ = ((t_) >> 4) & 1; pn_ = (int)sx * 16 + ((t_) & 15); break; } \
;     int wgid = (int)sx * tq + (t_); \
;     z_ = wgid / per; int id = wgid % per; \
;     int nig = WGM * nN, gid = id / nig, fm = gid * WGM, gsz = min(nM - fm, WGM); \
;     pm_ = fm + ((id % nig) % gsz); pn_ = (id % nig) / gsz; } while (0)
; #define STAGE_A(Ak_, b, h) do { const char* _s = (Ak_) + (h) * sHA; \
;     glds16(lds0 + ((b) * 2 + (h)) * (HT * 2), voffA, _s); glds16(lds0 + ((b) * 2 + (h)) * (HT * 2) + 8192, voffA, _s + s2A); } while (0)
; #define LDA(dst, b, h) for (int m = 0; m < 4; ++m) for (int k = 0; k < 2; ++k) \
;     dst[m][k] = *reinterpret_cast<const bf16x8*>((char*)SA(b, h) + lds_byte(wr * 64 + m * 16 + fr, k * 32 + fq * 8))
; template <int EPI>
; __device__ __forceinline__ void gemm_phase(const GemmDesc d, u16* shm, unsigned sx, unsigned srank, unsigned snloc) {
;     ...
;       f32x4 acc[2][2][4][2] = {};
;       bf16x8 At[4][2], B0[2][2], B1[2][2];
;       const int tn = t + (int)snloc;
;       const bool has_next = tn < tq;
;       int zn = z, pmn = pm, pnn = pn; const char *Aun = Au, *Bun = Bu, *Bunh = Buh; unsigned voffBhn[2] = {voffBh[0], voffBh[1]};
;       if (has_next) { DECODE(tn, zn, pmn, pnn); BASES(zn, pmn, pnn, Aun, Bun, Bunh, voffBhn); }
; #pragma unroll 1
;       for (int kt = 0; kt < nt; kt += 2) {
;         const bool lastk = (kt + 2 >= nt);
;         const char* A1 = Au + (long)(kt + 1) * sKA;
;         const char* A2 = lastk ? Aun : Au + (long)(kt + 2) * sKA;
;         const char* B2 = lastk ? Bun : Bu + (long)(kt + 2) * sKB;
;         const char* B2h = lastk ? Bunh : Buh + (long)(kt + 2) * sKB;
;         const unsigned vh[2] = {lastk ? voffBhn[0] : voffBh[0], lastk ? voffBhn[1] : voffBh[1]};
;         const char* A3 = A2 + sKA; const char* B3 = B2 + sKB; const char* B3h = B2h + sKB;
;         LDB(B0, 0, 0); SCHED; LDA(At, 0, 0); STAGE_A(A1, 1, 1);
;         WAIT_L(8); BAR; MMA(0, 0, At, B0); BAR; SCHED;
;         LDB(B1, 0, 1); STAGE_B(B2, B2h, vh, 0, 0);
;         BAR; MMA(0, 1, At, B1); BAR;
;         LDA(At, 0, 1); STAGE_A(A2, 0, 0);
;         BAR; MMA(1, 0, At, B0); BAR; SCHED;
;         STAGE_B(B2, B2h, vh, 0, 1);
;         WAIT_V(6); BAR; MMA(1, 1, At, B1); BAR;
;         LDB(B0, 1, 0); SCHED; LDA(At, 1, 0); STAGE_A(A2, 0, 1);
.LBB0_703:
	s_add_u32 s38, s38, 0x40080
	s_addc_u32 s39, s39, 0
	s_add_u32 s88, s40, 0x100
	s_addc_u32 s89, s41, 0
	s_add_u32 s90, s4, 0x100
	s_addc_u32 s91, s5, 0
	s_mov_b32 s20, 0
.LBB0_704:
	s_add_i32 s21, s20, 2
	s_add_u32 s4, s38, 0xfffc0080
	s_addc_u32 s5, s39, -1
	s_cmp_lt_u32 s20, 14
	s_cselect_b32 s92, s88, s24
	s_cselect_b32 s53, s5, s17
	s_cselect_b32 s52, s4, s16
	s_cselect_b32 s93, s89, s25
	s_cselect_b32 s49, s91, s27
	s_cselect_b32 s48, s90, s26
	s_add_u32 s42, s92, 0x80
	s_addc_u32 s43, s93, 0
	s_add_u32 s22, s52, 0x80
	s_addc_u32 s23, s53, 0
	s_add_u32 s94, s38, 0x20000
	s_addc_u32 s95, s39, 0
	s_add_u32 s96, s92, 0x20000
	s_addc_u32 s97, s93, 0
	s_add_u32 s54, s52, 0x20000
	s_addc_u32 s55, s53, 0
	s_add_u32 s50, s48, 0x20000
	s_addc_u32 s51, s49, 0
	s_add_u32 s46, s52, 0x40000
	s_addc_u32 s47, s53, 0
	s_add_u32 s28, s52, 0x60000
	s_addc_u32 s29, s53, 0
	s_add_u32 s44, s92, 0x20080
	s_addc_u32 s45, s93, 0
	s_add_u32 s30, s52, 0x20080
	s_addc_u32 s31, s53, 0
	s_add_u32 s18, s48, 0x80
	s_addc_u32 s19, s49, 0
	s_add_u32 s4, s48, 0x20080
	s_addc_u32 s5, s49, 0
	s_add_u32 s40, s38, 0x100
	s_addc_u32 s41, s39, 0
	s_add_u32 s88, s88, 0x100
	s_addc_u32 s89, s89, 0
	s_add_u32 s90, s90, 0x100
	s_addc_u32 s91, s91, 0
	ds_read_b128 v[138:141], v129
	ds_read_b128 v[142:145], v129 offset:1024
	ds_read_b128 v[146:149], v129 offset:2048
	ds_read_b128 v[150:153], v129 offset:3072
	ds_read_b128 v[154:157], v130
	ds_read_b128 v[158:161], v130 offset:1024
	ds_read_b128 v[162:165], v131
	ds_read_b128 v[166:169], v131 offset:1024
	ds_read_b128 v[170:173], v132
	ds_read_b128 v[178:181], v132 offset:1024
	ds_read_b128 v[190:193], v133
	ds_read_b128 v[194:197], v133 offset:1024
	s_mov_b32 m0, s77
	s_nop 0
	global_load_lds_dwordx4 v128, s[38:39]
	s_mov_b32 m0, s78
	s_nop 0
	global_load_lds_dwordx4 v128, s[94:95]
	s_waitcnt lgkmcnt(8)
	s_barrier
	s_setprio 1
	s_waitcnt lgkmcnt(7)
	v_mfma_f32_16x16x32_bf16 v[124:127], v[154:157], v[138:141], 0
	v_mfma_f32_16x16x32_bf16 v[120:123], v[154:157], v[146:149], 0
	s_waitcnt lgkmcnt(5)
	v_mfma_f32_16x16x32_bf16 v[108:111], v[162:165], v[138:141], 0
	v_mfma_f32_16x16x32_bf16 v[104:107], v[162:165], v[146:149], 0
	s_waitcnt lgkmcnt(3)
	v_mfma_f32_16x16x32_bf16 v[92:95], v[170:173], v[138:141], 0
	v_mfma_f32_16x16x32_bf16 v[88:91], v[170:173], v[146:149], 0
	s_waitcnt lgkmcnt(1)
	v_mfma_f32_16x16x32_bf16 v[76:79], v[190:193], v[138:141], 0
	v_mfma_f32_16x16x32_bf16 v[72:75], v[190:193], v[146:149], 0
	v_mfma_f32_16x16x32_bf16 v[124:127], v[158:161], v[142:145], v[124:127]
	v_mfma_f32_16x16x32_bf16 v[120:123], v[158:161], v[150:153], v[120:123]
	v_mfma_f32_16x16x32_bf16 v[108:111], v[166:169], v[142:145], v[108:111]
	v_mfma_f32_16x16x32_bf16 v[104:107], v[166:169], v[150:153], v[104:107]
	v_mfma_f32_16x16x32_bf16 v[92:95], v[178:181], v[142:145], v[92:95]
	v_mfma_f32_16x16x32_bf16 v[88:91], v[178:181], v[150:153], v[88:91]
	s_waitcnt lgkmcnt(0)
	v_mfma_f32_16x16x32_bf16 v[76:79], v[194:197], v[142:145], v[76:79]
	v_mfma_f32_16x16x32_bf16 v[72:75], v[194:197], v[150:153], v[72:75]
	s_setprio 0
	s_barrier
	ds_read_b128 v[198:201], v134
	ds_read_b128 v[202:205], v134 offset:1024
	ds_read_b128 v[206:209], v134 offset:2048
	ds_read_b128 v[210:213], v134 offset:3072
	s_mov_b32 m0, s3
	s_nop 0
	global_load_lds_dwordx4 v128, s[92:93]
	s_mov_b32 m0, s37
	s_nop 0
	global_load_lds_dwordx4 v128, s[96:97]
	s_barrier
	s_setprio 1
	s_waitcnt lgkmcnt(3)
	v_mfma_f32_16x16x32_bf16 v[116:119], v[154:157], v[198:201], 0
	s_waitcnt lgkmcnt(1)
	v_mfma_f32_16x16x32_bf16 v[112:115], v[154:157], v[206:209], 0
	v_mfma_f32_16x16x32_bf16 v[100:103], v[162:165], v[198:201], 0
	v_mfma_f32_16x16x32_bf16 v[96:99], v[162:165], v[206:209], 0
	v_mfma_f32_16x16x32_bf16 v[84:87], v[170:173], v[198:201], 0
	v_mfma_f32_16x16x32_bf16 v[80:83], v[170:173], v[206:209], 0
	v_mfma_f32_16x16x32_bf16 v[68:71], v[190:193], v[198:201], 0
	v_mfma_f32_16x16x32_bf16 v[64:67], v[190:193], v[206:209], 0
	v_mfma_f32_16x16x32_bf16 v[116:119], v[158:161], v[202:205], v[116:119]
	s_waitcnt lgkmcnt(0)
	v_mfma_f32_16x16x32_bf16 v[112:115], v[158:161], v[210:213], v[112:115]
	v_mfma_f32_16x16x32_bf16 v[100:103], v[166:169], v[202:205], v[100:103]
	v_mfma_f32_16x16x32_bf16 v[96:99], v[166:169], v[210:213], v[96:99]
	v_mfma_f32_16x16x32_bf16 v[84:87], v[178:181], v[202:205], v[84:87]
	v_mfma_f32_16x16x32_bf16 v[80:83], v[178:181], v[210:213], v[80:83]
	v_mfma_f32_16x16x32_bf16 v[68:71], v[194:197], v[202:205], v[68:71]
	v_mfma_f32_16x16x32_bf16 v[64:67], v[194:197], v[210:213], v[64:67]
	s_setprio 0
	s_barrier
	ds_read_b128 v[154:157], v130 offset:16384
	ds_read_b128 v[158:161], v130 offset:17408
	ds_read_b128 v[162:165], v131 offset:16384
	ds_read_b128 v[166:169], v131 offset:17408
	ds_read_b128 v[170:173], v132 offset:16384
	ds_read_b128 v[178:181], v132 offset:17408
	ds_read_b128 v[190:193], v133 offset:16384
	ds_read_b128 v[194:197], v133 offset:17408
	s_mov_b32 m0, s2
	s_nop 0
	global_load_lds_dwordx4 v128, s[52:53]
	s_mov_b32 m0, s57
	s_nop 0
	global_load_lds_dwordx4 v128, s[54:55]
	s_barrier
; #define STAGE_A(Ak_, b, h) do { const char* _s = (Ak_) + (h) * sHA; \
;     glds16(lds0 + ((b) * 2 + (h)) * (HT * 2), voffA, _s); glds16(lds0 + ((b) * 2 + (h)) * (HT * 2) + 8192, voffA, _s + s2A); } while (0)
; #define STAGE_B(Bk_, Bkh_, vh_, b, h) do { const char* _s = (h) ? (Bkh_) : (Bk_); const unsigned _v0 = (h) ? (vh_)[0] : voffB, _v1 = (h) ? (vh_)[1] : voffB; const long _d = (h) ? s2Bh : s2B; \
;     glds16(lds0 + (4 + (b) * 2 + (h)) * (HT * 2), _v0, _s); glds16(lds0 + (4 + (b) * 2 + (h)) * (HT * 2) + 8192, _v1, _s + _d); } while (0)
; #define LDA(dst, b, h) for (int m = 0; m < 4; ++m) for (int k = 0; k < 2; ++k) \
;     dst[m][k] = *reinterpret_cast<const bf16x8*>((char*)SA(b, h) + lds_byte(wr * 64 + m * 16 + fr, k * 32 + fq * 8))
; #define LDB(dst, b, h) for (int n = 0; n < 2; ++n) for (int k = 0; k < 2; ++k) \
;     dst[n][k] = *reinterpret_cast<const bf16x8*>((char*)SB(b, h) + lds_byte(wc * 32 + n * 16 + fr, k * 32 + fq * 8))
; #define WAIT_V(n) asm volatile("s_waitcnt vmcnt(" #n ")" ::: "memory")
; #define WAIT_L(n) asm volatile("s_waitcnt lgkmcnt(" #n ")" ::: "memory")
; template <int EPI>
; __device__ __forceinline__ void gemm_phase(const GemmDesc d, u16* shm, unsigned sx, unsigned srank, unsigned snloc) {
;     ...
;       for (int kt = 0; kt < nt; kt += 2) {
;         const bool lastk = (kt + 2 >= nt);
;         const char* A1 = Au + (long)(kt + 1) * sKA;
;         const char* A2 = lastk ? Aun : Au + (long)(kt + 2) * sKA;
;         const char* B2 = lastk ? Bun : Bu + (long)(kt + 2) * sKB;
;         const char* B2h = lastk ? Bunh : Buh + (long)(kt + 2) * sKB;
;         const unsigned vh[2] = {lastk ? voffBhn[0] : voffBh[0], lastk ? voffBhn[1] : voffBh[1]};
;         const char* A3 = A2 + sKA; const char* B3 = B2 + sKB; const char* B3h = B2h + sKB;
;         LDB(B0, 0, 0); SCHED; LDA(At, 0, 0); STAGE_A(A1, 1, 1);
;         WAIT_L(8); BAR; MMA(0, 0, At, B0); BAR; SCHED;
;         LDB(B1, 0, 1); STAGE_B(B2, B2h, vh, 0, 0);
;         BAR; MMA(0, 1, At, B1); BAR;
;         LDA(At, 0, 1); STAGE_A(A2, 0, 0);
;         BAR; MMA(1, 0, At, B0); BAR; SCHED;
;         STAGE_B(B2, B2h, vh, 0, 1);
;         WAIT_V(6); BAR; MMA(1, 1, At, B1); BAR;
;         LDB(B0, 1, 0); SCHED; LDA(At, 1, 0); STAGE_A(A2, 0, 1);
;         WAIT_L(8); BAR; MMA(0, 0, At, B0); BAR; SCHED;
;         LDB(B1, 1, 1); STAGE_B(B3, B3h, vh, 1, 0);
;         BAR; MMA(0, 1, At, B1); BAR;
	s_setprio 1
	s_waitcnt lgkmcnt(7)
	v_mfma_f32_16x16x32_bf16 v[60:63], v[154:157], v[138:141], 0
	v_mfma_f32_16x16x32_bf16 v[56:59], v[154:157], v[146:149], 0
	s_waitcnt lgkmcnt(5)
	v_mfma_f32_16x16x32_bf16 v[44:47], v[162:165], v[138:141], 0
	v_mfma_f32_16x16x32_bf16 v[40:43], v[162:165], v[146:149], 0
	s_waitcnt lgkmcnt(3)
	v_mfma_f32_16x16x32_bf16 v[28:31], v[170:173], v[138:141], 0
	v_mfma_f32_16x16x32_bf16 v[24:27], v[170:173], v[146:149], 0
	s_waitcnt lgkmcnt(1)
	v_mfma_f32_16x16x32_bf16 v[12:15], v[190:193], v[138:141], 0
	v_mfma_f32_16x16x32_bf16 v[8:11], v[190:193], v[146:149], 0
	v_mfma_f32_16x16x32_bf16 v[60:63], v[158:161], v[142:145], v[60:63]
	v_mfma_f32_16x16x32_bf16 v[56:59], v[158:161], v[150:153], v[56:59]
	v_mfma_f32_16x16x32_bf16 v[44:47], v[166:169], v[142:145], v[44:47]
	v_mfma_f32_16x16x32_bf16 v[40:43], v[166:169], v[150:153], v[40:43]
	v_mfma_f32_16x16x32_bf16 v[28:31], v[178:181], v[142:145], v[28:31]
	v_mfma_f32_16x16x32_bf16 v[24:27], v[178:181], v[150:153], v[24:27]
	s_waitcnt lgkmcnt(0)
	v_mfma_f32_16x16x32_bf16 v[12:15], v[194:197], v[142:145], v[12:15]
	v_mfma_f32_16x16x32_bf16 v[8:11], v[194:197], v[150:153], v[8:11]
	s_setprio 0
	s_barrier
	s_mov_b32 m0, s59
	s_nop 0
	global_load_lds_dwordx4 v128, s[48:49]
	s_mov_b32 m0, s62
	s_nop 0
	global_load_lds_dwordx4 v128, s[50:51]
	s_waitcnt vmcnt(6)
	s_barrier
	s_setprio 1
	v_mfma_f32_16x16x32_bf16 v[52:55], v[154:157], v[198:201], 0
	v_mfma_f32_16x16x32_bf16 v[48:51], v[154:157], v[206:209], 0
	v_mfma_f32_16x16x32_bf16 v[36:39], v[162:165], v[198:201], 0
	v_mfma_f32_16x16x32_bf16 v[32:35], v[162:165], v[206:209], 0
	v_mfma_f32_16x16x32_bf16 v[20:23], v[170:173], v[198:201], 0
	v_mfma_f32_16x16x32_bf16 v[16:19], v[170:173], v[206:209], 0
	v_mfma_f32_16x16x32_bf16 v[4:7], v[190:193], v[198:201], 0
	v_mfma_f32_16x16x32_bf16 v[0:3], v[190:193], v[206:209], 0
	v_mfma_f32_16x16x32_bf16 v[52:55], v[158:161], v[202:205], v[52:55]
	v_mfma_f32_16x16x32_bf16 v[48:51], v[158:161], v[210:213], v[48:51]
	v_mfma_f32_16x16x32_bf16 v[36:39], v[166:169], v[202:205], v[36:39]
	v_mfma_f32_16x16x32_bf16 v[32:35], v[166:169], v[210:213], v[32:35]
	v_mfma_f32_16x16x32_bf16 v[20:23], v[178:181], v[202:205], v[20:23]
	v_mfma_f32_16x16x32_bf16 v[16:19], v[178:181], v[210:213], v[16:19]
	v_mfma_f32_16x16x32_bf16 v[4:7], v[194:197], v[202:205], v[4:7]
	v_mfma_f32_16x16x32_bf16 v[0:3], v[194:197], v[210:213], v[0:3]
	s_setprio 0
	s_barrier
	ds_read_b128 v[138:141], v135
	ds_read_b128 v[142:145], v135 offset:1024
	ds_read_b128 v[146:149], v135 offset:2048
	ds_read_b128 v[150:153], v135 offset:3072
	ds_read_b128 v[154:157], v130 offset:32768
	ds_read_b128 v[158:161], v130 offset:33792
	ds_read_b128 v[162:165], v131 offset:32768
	ds_read_b128 v[166:169], v131 offset:33792
	ds_read_b128 v[170:173], v132 offset:32768
	ds_read_b128 v[178:181], v132 offset:33792
	ds_read_b128 v[190:193], v133 offset:32768
	ds_read_b128 v[194:197], v133 offset:33792
	s_mov_b32 m0, s63
	s_nop 0
	global_load_lds_dwordx4 v128, s[46:47]
	s_mov_b32 m0, s64
	s_nop 0
	global_load_lds_dwordx4 v128, s[28:29]
	s_waitcnt lgkmcnt(8)
	s_barrier
	s_setprio 1
	s_waitcnt lgkmcnt(7)
	v_mfma_f32_16x16x32_bf16 v[124:127], v[154:157], v[138:141], v[124:127]
	v_mfma_f32_16x16x32_bf16 v[120:123], v[154:157], v[146:149], v[120:123]
	s_waitcnt lgkmcnt(5)
	v_mfma_f32_16x16x32_bf16 v[108:111], v[162:165], v[138:141], v[108:111]
	v_mfma_f32_16x16x32_bf16 v[104:107], v[162:165], v[146:149], v[104:107]
	s_waitcnt lgkmcnt(3)
	v_mfma_f32_16x16x32_bf16 v[92:95], v[170:173], v[138:141], v[92:95]
	v_mfma_f32_16x16x32_bf16 v[88:91], v[170:173], v[146:149], v[88:91]
	s_waitcnt lgkmcnt(1)
	v_mfma_f32_16x16x32_bf16 v[76:79], v[190:193], v[138:141], v[76:79]
	v_mfma_f32_16x16x32_bf16 v[72:75], v[190:193], v[146:149], v[72:75]
	v_mfma_f32_16x16x32_bf16 v[124:127], v[158:161], v[142:145], v[124:127]
	v_mfma_f32_16x16x32_bf16 v[120:123], v[158:161], v[150:153], v[120:123]
	v_mfma_f32_16x16x32_bf16 v[108:111], v[166:169], v[142:145], v[108:111]
	v_mfma_f32_16x16x32_bf16 v[104:107], v[166:169], v[150:153], v[104:107]
	v_mfma_f32_16x16x32_bf16 v[92:95], v[178:181], v[142:145], v[92:95]
	v_mfma_f32_16x16x32_bf16 v[88:91], v[178:181], v[150:153], v[88:91]
	s_waitcnt lgkmcnt(0)
	v_mfma_f32_16x16x32_bf16 v[76:79], v[194:197], v[142:145], v[76:79]
	v_mfma_f32_16x16x32_bf16 v[72:75], v[194:197], v[150:153], v[72:75]
	s_setprio 0
	s_barrier
	ds_read_b128 v[198:201], v136
	ds_read_b128 v[202:205], v136 offset:1024
	ds_read_b128 v[206:209], v136 offset:2048
	ds_read_b128 v[210:213], v136 offset:3072
	s_mov_b32 m0, s69
	s_nop 0
	global_load_lds_dwordx4 v128, s[42:43]
	s_mov_b32 m0, s70
	s_nop 0
	global_load_lds_dwordx4 v128, s[44:45]
	s_barrier
	s_setprio 1
	s_waitcnt lgkmcnt(3)
	v_mfma_f32_16x16x32_bf16 v[116:119], v[154:157], v[198:201], v[116:119]
	s_waitcnt lgkmcnt(1)
	v_mfma_f32_16x16x32_bf16 v[112:115], v[154:157], v[206:209], v[112:115]
	v_mfma_f32_16x16x32_bf16 v[100:103], v[162:165], v[198:201], v[100:103]
	v_mfma_f32_16x16x32_bf16 v[96:99], v[162:165], v[206:209], v[96:99]
	v_mfma_f32_16x16x32_bf16 v[84:87], v[170:173], v[198:201], v[84:87]
	v_mfma_f32_16x16x32_bf16 v[80:83], v[170:173], v[206:209], v[80:83]
	v_mfma_f32_16x16x32_bf16 v[68:71], v[190:193], v[198:201], v[68:71]
	v_mfma_f32_16x16x32_bf16 v[64:67], v[190:193], v[206:209], v[64:67]
	v_mfma_f32_16x16x32_bf16 v[116:119], v[158:161], v[202:205], v[116:119]
	s_waitcnt lgkmcnt(0)
	v_mfma_f32_16x16x32_bf16 v[112:115], v[158:161], v[210:213], v[112:115]
	v_mfma_f32_16x16x32_bf16 v[100:103], v[166:169], v[202:205], v[100:103]
	v_mfma_f32_16x16x32_bf16 v[96:99], v[166:169], v[210:213], v[96:99]
	v_mfma_f32_16x16x32_bf16 v[84:87], v[178:181], v[202:205], v[84:87]
	v_mfma_f32_16x16x32_bf16 v[80:83], v[178:181], v[210:213], v[80:83]
	v_mfma_f32_16x16x32_bf16 v[68:71], v[194:197], v[202:205], v[68:71]
	v_mfma_f32_16x16x32_bf16 v[64:67], v[194:197], v[210:213], v[64:67]
	s_setprio 0
	s_barrier
; #define STAGE_A(Ak_, b, h) do { const char* _s = (Ak_) + (h) * sHA; \
;     glds16(lds0 + ((b) * 2 + (h)) * (HT * 2), voffA, _s); glds16(lds0 + ((b) * 2 + (h)) * (HT * 2) + 8192, voffA, _s + s2A); } while (0)
; #define STAGE_B(Bk_, Bkh_, vh_, b, h) do { const char* _s = (h) ? (Bkh_) : (Bk_); const unsigned _v0 = (h) ? (vh_)[0] : voffB, _v1 = (h) ? (vh_)[1] : voffB; const long _d = (h) ? s2Bh : s2B; \
;     glds16(lds0 + (4 + (b) * 2 + (h)) * (HT * 2), _v0, _s); glds16(lds0 + (4 + (b) * 2 + (h)) * (HT * 2) + 8192, _v1, _s + _d); } while (0)
; #define LDA(dst, b, h) for (int m = 0; m < 4; ++m) for (int k = 0; k < 2; ++k) \
;     dst[m][k] = *reinterpret_cast<const bf16x8*>((char*)SA(b, h) + lds_byte(wr * 64 + m * 16 + fr, k * 32 + fq * 8))
; #define WAIT_V(n) asm volatile("s_waitcnt vmcnt(" #n ")" ::: "memory")
; #define WAIT_L(n) asm volatile("s_waitcnt lgkmcnt(" #n ")" ::: "memory")
; template <int EPI>
; __device__ __forceinline__ void gemm_phase(const GemmDesc d, u16* shm, unsigned sx, unsigned srank, unsigned snloc) {
;     ...
;       for (int kt = 0; kt < nt; kt += 2) {
;         const bool lastk = (kt + 2 >= nt);
;         const char* A1 = Au + (long)(kt + 1) * sKA;
;         const char* A2 = lastk ? Aun : Au + (long)(kt + 2) * sKA;
;         const char* B2 = lastk ? Bun : Bu + (long)(kt + 2) * sKB;
;         const char* B2h = lastk ? Bunh : Buh + (long)(kt + 2) * sKB;
;         const unsigned vh[2] = {lastk ? voffBhn[0] : voffBh[0], lastk ? voffBhn[1] : voffBh[1]};
;         const char* A3 = A2 + sKA; const char* B3 = B2 + sKB; const char* B3h = B2h + sKB;
;         LDB(B0, 0, 0); SCHED; LDA(At, 0, 0); STAGE_A(A1, 1, 1);
;         WAIT_L(8); BAR; MMA(0, 0, At, B0); BAR; SCHED;
;         LDB(B1, 0, 1); STAGE_B(B2, B2h, vh, 0, 0);
;         BAR; MMA(0, 1, At, B1); BAR;
;         LDA(At, 0, 1); STAGE_A(A2, 0, 0);
;         BAR; MMA(1, 0, At, B0); BAR; SCHED;
;         STAGE_B(B2, B2h, vh, 0, 1);
;         WAIT_V(6); BAR; MMA(1, 1, At, B1); BAR;
;         LDB(B0, 1, 0); SCHED; LDA(At, 1, 0); STAGE_A(A2, 0, 1);
;         WAIT_L(8); BAR; MMA(0, 0, At, B0); BAR; SCHED;
;         LDB(B1, 1, 1); STAGE_B(B3, B3h, vh, 1, 0);
;         BAR; MMA(0, 1, At, B1); BAR;
;         LDA(At, 1, 1); STAGE_A(A3, 1, 0);
;         BAR; MMA(1, 0, At, B0); BAR; SCHED;
;         STAGE_B(B3, B3h, vh, 1, 1);
;         WAIT_V(6); BAR; MMA(1, 1, At, B1); BAR;
;       }
	ds_read_b128 v[154:157], v130 offset:49152
	ds_read_b128 v[158:161], v130 offset:50176
	ds_read_b128 v[162:165], v131 offset:49152
	ds_read_b128 v[166:169], v131 offset:50176
	ds_read_b128 v[170:173], v132 offset:49152
	ds_read_b128 v[178:181], v132 offset:50176
	ds_read_b128 v[190:193], v133 offset:49152
	ds_read_b128 v[194:197], v133 offset:50176
	s_mov_b32 m0, s71
	s_nop 0
	global_load_lds_dwordx4 v128, s[22:23]
	s_mov_b32 m0, s72
	s_nop 0
	global_load_lds_dwordx4 v128, s[30:31]
	s_barrier
	s_setprio 1
	s_waitcnt lgkmcnt(7)
	v_mfma_f32_16x16x32_bf16 v[60:63], v[154:157], v[138:141], v[60:63]
	v_mfma_f32_16x16x32_bf16 v[56:59], v[154:157], v[146:149], v[56:59]
	s_waitcnt lgkmcnt(5)
	v_mfma_f32_16x16x32_bf16 v[44:47], v[162:165], v[138:141], v[44:47]
	v_mfma_f32_16x16x32_bf16 v[40:43], v[162:165], v[146:149], v[40:43]
	s_waitcnt lgkmcnt(3)
	v_mfma_f32_16x16x32_bf16 v[28:31], v[170:173], v[138:141], v[28:31]
	v_mfma_f32_16x16x32_bf16 v[24:27], v[170:173], v[146:149], v[24:27]
	s_waitcnt lgkmcnt(1)
	v_mfma_f32_16x16x32_bf16 v[12:15], v[190:193], v[138:141], v[12:15]
	v_mfma_f32_16x16x32_bf16 v[8:11], v[190:193], v[146:149], v[8:11]
	v_mfma_f32_16x16x32_bf16 v[60:63], v[158:161], v[142:145], v[60:63]
	v_mfma_f32_16x16x32_bf16 v[56:59], v[158:161], v[150:153], v[56:59]
	v_mfma_f32_16x16x32_bf16 v[44:47], v[166:169], v[142:145], v[44:47]
	v_mfma_f32_16x16x32_bf16 v[40:43], v[166:169], v[150:153], v[40:43]
	v_mfma_f32_16x16x32_bf16 v[28:31], v[178:181], v[142:145], v[28:31]
	v_mfma_f32_16x16x32_bf16 v[24:27], v[178:181], v[150:153], v[24:27]
	s_waitcnt lgkmcnt(0)
	v_mfma_f32_16x16x32_bf16 v[12:15], v[194:197], v[142:145], v[12:15]
	v_mfma_f32_16x16x32_bf16 v[8:11], v[194:197], v[150:153], v[8:11]
	s_setprio 0
	s_barrier
	s_mov_b32 m0, s73
	s_nop 0
	global_load_lds_dwordx4 v128, s[18:19]
	s_mov_b32 m0, s76
	s_nop 0
	global_load_lds_dwordx4 v128, s[4:5]
	s_mov_b64 s[38:39], s[40:41]
	s_mov_b32 s20, s21
	s_add_i32 s21, s20, 2
	s_add_u32 s4, s38, 0xfffc0080
	s_addc_u32 s5, s39, -1
	s_cmp_lt_u32 s20, 14
	s_cselect_b32 s92, s88, s24
	s_cselect_b32 s53, s5, s17
	s_cselect_b32 s52, s4, s16
	s_cselect_b32 s93, s89, s25
	s_cselect_b32 s49, s91, s27
	s_cselect_b32 s48, s90, s26
	s_add_u32 s42, s92, 0x80
	s_addc_u32 s43, s93, 0
	s_add_u32 s22, s52, 0x80
	s_addc_u32 s23, s53, 0
	s_add_u32 s94, s38, 0x20000
	s_addc_u32 s95, s39, 0
	s_add_u32 s96, s92, 0x20000
	s_addc_u32 s97, s93, 0
	s_add_u32 s54, s52, 0x20000
	s_addc_u32 s55, s53, 0
	s_add_u32 s50, s48, 0x20000
	s_addc_u32 s51, s49, 0
	s_add_u32 s46, s52, 0x40000
	s_addc_u32 s47, s53, 0
	s_add_u32 s28, s52, 0x60000
	s_addc_u32 s29, s53, 0
	s_add_u32 s44, s92, 0x20080
	s_addc_u32 s45, s93, 0
	s_add_u32 s30, s52, 0x20080
	s_addc_u32 s31, s53, 0
	s_add_u32 s18, s48, 0x80
	s_addc_u32 s19, s49, 0
	s_add_u32 s4, s48, 0x20080
	s_addc_u32 s5, s49, 0
	s_add_u32 s40, s38, 0x100
	s_addc_u32 s41, s39, 0
	s_add_u32 s88, s88, 0x100
	s_addc_u32 s89, s89, 0
	s_add_u32 s90, s90, 0x100
	s_addc_u32 s91, s91, 0
	s_waitcnt vmcnt(6)
	s_barrier
	s_setprio 1
	v_mfma_f32_16x16x32_bf16 v[52:55], v[154:157], v[198:201], v[52:55]
	v_mfma_f32_16x16x32_bf16 v[48:51], v[154:157], v[206:209], v[48:51]
	v_mfma_f32_16x16x32_bf16 v[36:39], v[162:165], v[198:201], v[36:39]
	v_mfma_f32_16x16x32_bf16 v[32:35], v[162:165], v[206:209], v[32:35]
	v_mfma_f32_16x16x32_bf16 v[20:23], v[170:173], v[198:201], v[20:23]
	v_mfma_f32_16x16x32_bf16 v[16:19], v[170:173], v[206:209], v[16:19]
	v_mfma_f32_16x16x32_bf16 v[4:7], v[190:193], v[198:201], v[4:7]
	v_mfma_f32_16x16x32_bf16 v[0:3], v[190:193], v[206:209], v[0:3]
	v_mfma_f32_16x16x32_bf16 v[52:55], v[158:161], v[202:205], v[52:55]
	v_mfma_f32_16x16x32_bf16 v[48:51], v[158:161], v[210:213], v[48:51]
	v_mfma_f32_16x16x32_bf16 v[36:39], v[166:169], v[202:205], v[36:39]
	v_mfma_f32_16x16x32_bf16 v[32:35], v[166:169], v[210:213], v[32:35]
	v_mfma_f32_16x16x32_bf16 v[20:23], v[178:181], v[202:205], v[20:23]
	v_mfma_f32_16x16x32_bf16 v[16:19], v[178:181], v[210:213], v[16:19]
	v_mfma_f32_16x16x32_bf16 v[4:7], v[194:197], v[202:205], v[4:7]
	v_mfma_f32_16x16x32_bf16 v[0:3], v[194:197], v[210:213], v[0:3]
	s_setprio 0
	s_barrier
.Lk_qkv:
	ds_read_b128 v[138:141], v129
	ds_read_b128 v[142:145], v129 offset:1024
	ds_read_b128 v[146:149], v129 offset:2048
	ds_read_b128 v[150:153], v129 offset:3072
	ds_read_b128 v[154:157], v130
	ds_read_b128 v[158:161], v130 offset:1024
	ds_read_b128 v[162:165], v131
	ds_read_b128 v[166:169], v131 offset:1024
	ds_read_b128 v[170:173], v132
	ds_read_b128 v[178:181], v132 offset:1024
	ds_read_b128 v[190:193], v133
	ds_read_b128 v[194:197], v133 offset:1024
	s_mov_b32 m0, s77
	s_nop 0
	global_load_lds_dwordx4 v128, s[38:39]
	s_mov_b32 m0, s78
	s_nop 0
	global_load_lds_dwordx4 v128, s[94:95]
	s_waitcnt lgkmcnt(8)
	s_barrier
	s_setprio 1
	s_waitcnt lgkmcnt(7)
	v_mfma_f32_16x16x32_bf16 v[124:127], v[154:157], v[138:141], v[124:127]
	v_mfma_f32_16x16x32_bf16 v[120:123], v[154:157], v[146:149], v[120:123]
	s_waitcnt lgkmcnt(5)
	v_mfma_f32_16x16x32_bf16 v[108:111], v[162:165], v[138:141], v[108:111]
	v_mfma_f32_16x16x32_bf16 v[104:107], v[162:165], v[146:149], v[104:107]
	s_waitcnt lgkmcnt(3)
	v_mfma_f32_16x16x32_bf16 v[92:95], v[170:173], v[138:141], v[92:95]
	v_mfma_f32_16x16x32_bf16 v[88:91], v[170:173], v[146:149], v[88:91]
	s_waitcnt lgkmcnt(1)
	v_mfma_f32_16x16x32_bf16 v[76:79], v[190:193], v[138:141], v[76:79]
	v_mfma_f32_16x16x32_bf16 v[72:75], v[190:193], v[146:149], v[72:75]
	v_mfma_f32_16x16x32_bf16 v[124:127], v[158:161], v[142:145], v[124:127]
	v_mfma_f32_16x16x32_bf16 v[120:123], v[158:161], v[150:153], v[120:123]
	v_mfma_f32_16x16x32_bf16 v[108:111], v[166:169], v[142:145], v[108:111]
	v_mfma_f32_16x16x32_bf16 v[104:107], v[166:169], v[150:153], v[104:107]
	v_mfma_f32_16x16x32_bf16 v[92:95], v[178:181], v[142:145], v[92:95]
	v_mfma_f32_16x16x32_bf16 v[88:91], v[178:181], v[150:153], v[88:91]
	s_waitcnt lgkmcnt(0)
	v_mfma_f32_16x16x32_bf16 v[76:79], v[194:197], v[142:145], v[76:79]
	v_mfma_f32_16x16x32_bf16 v[72:75], v[194:197], v[150:153], v[72:75]
	s_setprio 0
	s_barrier
; #define STAGE_A(Ak_, b, h) do { const char* _s = (Ak_) + (h) * sHA; \
;     glds16(lds0 + ((b) * 2 + (h)) * (HT * 2), voffA, _s); glds16(lds0 + ((b) * 2 + (h)) * (HT * 2) + 8192, voffA, _s + s2A); } while (0)
; #define STAGE_B(Bk_, Bkh_, vh_, b, h) do { const char* _s = (h) ? (Bkh_) : (Bk_); const unsigned _v0 = (h) ? (vh_)[0] : voffB, _v1 = (h) ? (vh_)[1] : voffB; const long _d = (h) ? s2Bh : s2B; \
;     glds16(lds0 + (4 + (b) * 2 + (h)) * (HT * 2), _v0, _s); glds16(lds0 + (4 + (b) * 2 + (h)) * (HT * 2) + 8192, _v1, _s + _d); } while (0)
; #define LDA(dst, b, h) for (int m = 0; m < 4; ++m) for (int k = 0; k < 2; ++k) \
;     dst[m][k] = *reinterpret_cast<const bf16x8*>((char*)SA(b, h) + lds_byte(wr * 64 + m * 16 + fr, k * 32 + fq * 8))
; #define LDB(dst, b, h) for (int n = 0; n < 2; ++n) for (int k = 0; k < 2; ++k) \
;     dst[n][k] = *reinterpret_cast<const bf16x8*>((char*)SB(b, h) + lds_byte(wc * 32 + n * 16 + fr, k * 32 + fq * 8))
; #define MMA(ai, bj, At_, Bt_) do { __builtin_amdgcn_s_setprio(1); \
;     for (int m = 0; m < 4; ++m) for (int n = 0; n < 2; ++n) for (int k = 0; k < 2; ++k) \
;       acc[ai][bj][m][n] = __builtin_amdgcn_mfma_f32_16x16x32_bf16(At_[m][k], Bt_[n][k], acc[ai][bj][m][n], 0, 0, 0); \
;     __builtin_amdgcn_s_setprio(0); } while (0)
; #define WAIT_V(n) asm volatile("s_waitcnt vmcnt(" #n ")" ::: "memory")
; #define WAIT_L(n) asm volatile("s_waitcnt lgkmcnt(" #n ")" ::: "memory")
; #define BAR __builtin_amdgcn_s_barrier()
; #define SCHED __builtin_amdgcn_sched_barrier(0)
; template <int EPI>
; __device__ __forceinline__ void gemm_phase(const GemmDesc d, u16* shm, unsigned sx, unsigned srank, unsigned snloc) {
;     ...
;         LDB(B1, 0, 1); STAGE_B(B2, B2h, vh, 0, 0);
;         BAR; MMA(0, 1, At, B1); BAR;
;         LDA(At, 0, 1); STAGE_A(A2, 0, 0);
;         BAR; MMA(1, 0, At, B0); BAR; SCHED;
;         STAGE_B(B2, B2h, vh, 0, 1);
;         WAIT_V(6); BAR; MMA(1, 1, At, B1); BAR;
;         LDB(B0, 1, 0); SCHED; LDA(At, 1, 0); STAGE_A(A2, 0, 1);
;         WAIT_L(8); BAR; MMA(0, 0, At, B0); BAR; SCHED;
;         LDB(B1, 1, 1); STAGE_B(B3, B3h, vh, 1, 0);
	ds_read_b128 v[198:201], v134
	ds_read_b128 v[202:205], v134 offset:1024
	ds_read_b128 v[206:209], v134 offset:2048
	ds_read_b128 v[210:213], v134 offset:3072
	s_mov_b32 m0, s3
	s_nop 0
	global_load_lds_dwordx4 v128, s[92:93]
	s_mov_b32 m0, s37
	s_nop 0
	global_load_lds_dwordx4 v128, s[96:97]
	s_barrier
	s_setprio 1
	s_waitcnt lgkmcnt(3)
	v_mfma_f32_16x16x32_bf16 v[116:119], v[154:157], v[198:201], v[116:119]
	s_waitcnt lgkmcnt(1)
	v_mfma_f32_16x16x32_bf16 v[112:115], v[154:157], v[206:209], v[112:115]
	v_mfma_f32_16x16x32_bf16 v[100:103], v[162:165], v[198:201], v[100:103]
	v_mfma_f32_16x16x32_bf16 v[96:99], v[162:165], v[206:209], v[96:99]
	v_mfma_f32_16x16x32_bf16 v[84:87], v[170:173], v[198:201], v[84:87]
	v_mfma_f32_16x16x32_bf16 v[80:83], v[170:173], v[206:209], v[80:83]
	v_mfma_f32_16x16x32_bf16 v[68:71], v[190:193], v[198:201], v[68:71]
	v_mfma_f32_16x16x32_bf16 v[64:67], v[190:193], v[206:209], v[64:67]
	v_mfma_f32_16x16x32_bf16 v[116:119], v[158:161], v[202:205], v[116:119]
	s_waitcnt lgkmcnt(0)
	v_mfma_f32_16x16x32_bf16 v[112:115], v[158:161], v[210:213], v[112:115]
	v_mfma_f32_16x16x32_bf16 v[100:103], v[166:169], v[202:205], v[100:103]
	v_mfma_f32_16x16x32_bf16 v[96:99], v[166:169], v[210:213], v[96:99]
	v_mfma_f32_16x16x32_bf16 v[84:87], v[178:181], v[202:205], v[84:87]
	v_mfma_f32_16x16x32_bf16 v[80:83], v[178:181], v[210:213], v[80:83]
	v_mfma_f32_16x16x32_bf16 v[68:71], v[194:197], v[202:205], v[68:71]
	v_mfma_f32_16x16x32_bf16 v[64:67], v[194:197], v[210:213], v[64:67]
	s_setprio 0
	s_barrier
	ds_read_b128 v[154:157], v130 offset:16384
	ds_read_b128 v[158:161], v130 offset:17408
	ds_read_b128 v[162:165], v131 offset:16384
	ds_read_b128 v[166:169], v131 offset:17408
	ds_read_b128 v[170:173], v132 offset:16384
	ds_read_b128 v[178:181], v132 offset:17408
	ds_read_b128 v[190:193], v133 offset:16384
	ds_read_b128 v[194:197], v133 offset:17408
	s_mov_b32 m0, s2
	s_nop 0
	global_load_lds_dwordx4 v128, s[52:53]
	s_mov_b32 m0, s57
	s_nop 0
	global_load_lds_dwordx4 v128, s[54:55]
	s_barrier
	s_setprio 1
	s_waitcnt lgkmcnt(7)
	v_mfma_f32_16x16x32_bf16 v[60:63], v[154:157], v[138:141], v[60:63]
	v_mfma_f32_16x16x32_bf16 v[56:59], v[154:157], v[146:149], v[56:59]
	s_waitcnt lgkmcnt(5)
	v_mfma_f32_16x16x32_bf16 v[44:47], v[162:165], v[138:141], v[44:47]
	v_mfma_f32_16x16x32_bf16 v[40:43], v[162:165], v[146:149], v[40:43]
	s_waitcnt lgkmcnt(3)
	v_mfma_f32_16x16x32_bf16 v[28:31], v[170:173], v[138:141], v[28:31]
	v_mfma_f32_16x16x32_bf16 v[24:27], v[170:173], v[146:149], v[24:27]
	s_waitcnt lgkmcnt(1)
	v_mfma_f32_16x16x32_bf16 v[12:15], v[190:193], v[138:141], v[12:15]
	v_mfma_f32_16x16x32_bf16 v[8:11], v[190:193], v[146:149], v[8:11]
	v_mfma_f32_16x16x32_bf16 v[60:63], v[158:161], v[142:145], v[60:63]
	v_mfma_f32_16x16x32_bf16 v[56:59], v[158:161], v[150:153], v[56:59]
	v_mfma_f32_16x16x32_bf16 v[44:47], v[166:169], v[142:145], v[44:47]
	v_mfma_f32_16x16x32_bf16 v[40:43], v[166:169], v[150:153], v[40:43]
	v_mfma_f32_16x16x32_bf16 v[28:31], v[178:181], v[142:145], v[28:31]
	v_mfma_f32_16x16x32_bf16 v[24:27], v[178:181], v[150:153], v[24:27]
	s_waitcnt lgkmcnt(0)
	v_mfma_f32_16x16x32_bf16 v[12:15], v[194:197], v[142:145], v[12:15]
	v_mfma_f32_16x16x32_bf16 v[8:11], v[194:197], v[150:153], v[8:11]
	s_setprio 0
	s_barrier
	s_mov_b32 m0, s59
	s_nop 0
	global_load_lds_dwordx4 v128, s[48:49]
	s_mov_b32 m0, s62
	s_nop 0
	global_load_lds_dwordx4 v128, s[50:51]
	s_waitcnt vmcnt(6)
	s_barrier
	s_setprio 1
	v_mfma_f32_16x16x32_bf16 v[52:55], v[154:157], v[198:201], v[52:55]
	v_mfma_f32_16x16x32_bf16 v[48:51], v[154:157], v[206:209], v[48:51]
	v_mfma_f32_16x16x32_bf16 v[36:39], v[162:165], v[198:201], v[36:39]
	v_mfma_f32_16x16x32_bf16 v[32:35], v[162:165], v[206:209], v[32:35]
	v_mfma_f32_16x16x32_bf16 v[20:23], v[170:173], v[198:201], v[20:23]
	v_mfma_f32_16x16x32_bf16 v[16:19], v[170:173], v[206:209], v[16:19]
	v_mfma_f32_16x16x32_bf16 v[4:7], v[190:193], v[198:201], v[4:7]
	v_mfma_f32_16x16x32_bf16 v[0:3], v[190:193], v[206:209], v[0:3]
	v_mfma_f32_16x16x32_bf16 v[52:55], v[158:161], v[202:205], v[52:55]
	v_mfma_f32_16x16x32_bf16 v[48:51], v[158:161], v[210:213], v[48:51]
	v_mfma_f32_16x16x32_bf16 v[36:39], v[166:169], v[202:205], v[36:39]
	v_mfma_f32_16x16x32_bf16 v[32:35], v[166:169], v[210:213], v[32:35]
	v_mfma_f32_16x16x32_bf16 v[20:23], v[178:181], v[202:205], v[20:23]
	v_mfma_f32_16x16x32_bf16 v[16:19], v[178:181], v[210:213], v[16:19]
	v_mfma_f32_16x16x32_bf16 v[4:7], v[194:197], v[202:205], v[4:7]
	v_mfma_f32_16x16x32_bf16 v[0:3], v[194:197], v[210:213], v[0:3]
	s_setprio 0
	s_barrier
	ds_read_b128 v[138:141], v135
	ds_read_b128 v[142:145], v135 offset:1024
	ds_read_b128 v[146:149], v135 offset:2048
	ds_read_b128 v[150:153], v135 offset:3072
	ds_read_b128 v[154:157], v130 offset:32768
	ds_read_b128 v[158:161], v130 offset:33792
	ds_read_b128 v[162:165], v131 offset:32768
	ds_read_b128 v[166:169], v131 offset:33792
	ds_read_b128 v[170:173], v132 offset:32768
	ds_read_b128 v[178:181], v132 offset:33792
	ds_read_b128 v[190:193], v133 offset:32768
	ds_read_b128 v[194:197], v133 offset:33792
	s_mov_b32 m0, s63
	s_nop 0
	global_load_lds_dwordx4 v128, s[46:47]
	s_mov_b32 m0, s64
	s_nop 0
	global_load_lds_dwordx4 v128, s[28:29]
	s_waitcnt lgkmcnt(8)
	s_barrier
; #define STAGE_A(Ak_, b, h) do { const char* _s = (Ak_) + (h) * sHA; \
;     glds16(lds0 + ((b) * 2 + (h)) * (HT * 2), voffA, _s); glds16(lds0 + ((b) * 2 + (h)) * (HT * 2) + 8192, voffA, _s + s2A); } while (0)
; #define STAGE_B(Bk_, Bkh_, vh_, b, h) do { const char* _s = (h) ? (Bkh_) : (Bk_); const unsigned _v0 = (h) ? (vh_)[0] : voffB, _v1 = (h) ? (vh_)[1] : voffB; const long _d = (h) ? s2Bh : s2B; \
;     glds16(lds0 + (4 + (b) * 2 + (h)) * (HT * 2), _v0, _s); glds16(lds0 + (4 + (b) * 2 + (h)) * (HT * 2) + 8192, _v1, _s + _d); } while (0)
; #define LDA(dst, b, h) for (int m = 0; m < 4; ++m) for (int k = 0; k < 2; ++k) \
;     dst[m][k] = *reinterpret_cast<const bf16x8*>((char*)SA(b, h) + lds_byte(wr * 64 + m * 16 + fr, k * 32 + fq * 8))
; #define LDB(dst, b, h) for (int n = 0; n < 2; ++n) for (int k = 0; k < 2; ++k) \
;     dst[n][k] = *reinterpret_cast<const bf16x8*>((char*)SB(b, h) + lds_byte(wc * 32 + n * 16 + fr, k * 32 + fq * 8))
; #define MMA(ai, bj, At_, Bt_) do { __builtin_amdgcn_s_setprio(1); \
;     for (int m = 0; m < 4; ++m) for (int n = 0; n < 2; ++n) for (int k = 0; k < 2; ++k) \
;       acc[ai][bj][m][n] = __builtin_amdgcn_mfma_f32_16x16x32_bf16(At_[m][k], Bt_[n][k], acc[ai][bj][m][n], 0, 0, 0); \
;     __builtin_amdgcn_s_setprio(0); } while (0)
; #define WAIT_L(n) asm volatile("s_waitcnt lgkmcnt(" #n ")" ::: "memory")
; #define BAR __builtin_amdgcn_s_barrier()
; #define SCHED __builtin_amdgcn_sched_barrier(0)
; template <int EPI>
; __device__ __forceinline__ void gemm_phase(const GemmDesc d, u16* shm, unsigned sx, unsigned srank, unsigned snloc) {
;     ...
;         WAIT_L(8); BAR; MMA(0, 0, At, B0); BAR; SCHED;
;         LDB(B1, 1, 1); STAGE_B(B3, B3h, vh, 1, 0);
;         BAR; MMA(0, 1, At, B1); BAR;
;         LDA(At, 1, 1); STAGE_A(A3, 1, 0);
;         BAR; MMA(1, 0, At, B0); BAR; SCHED;
	s_setprio 1
	s_waitcnt lgkmcnt(7)
	v_mfma_f32_16x16x32_bf16 v[124:127], v[154:157], v[138:141], v[124:127]
	v_mfma_f32_16x16x32_bf16 v[120:123], v[154:157], v[146:149], v[120:123]
	s_waitcnt lgkmcnt(5)
	v_mfma_f32_16x16x32_bf16 v[108:111], v[162:165], v[138:141], v[108:111]
	v_mfma_f32_16x16x32_bf16 v[104:107], v[162:165], v[146:149], v[104:107]
	s_waitcnt lgkmcnt(3)
	v_mfma_f32_16x16x32_bf16 v[92:95], v[170:173], v[138:141], v[92:95]
	v_mfma_f32_16x16x32_bf16 v[88:91], v[170:173], v[146:149], v[88:91]
	s_waitcnt lgkmcnt(1)
	v_mfma_f32_16x16x32_bf16 v[76:79], v[190:193], v[138:141], v[76:79]
	v_mfma_f32_16x16x32_bf16 v[72:75], v[190:193], v[146:149], v[72:75]
	v_mfma_f32_16x16x32_bf16 v[124:127], v[158:161], v[142:145], v[124:127]
	v_mfma_f32_16x16x32_bf16 v[120:123], v[158:161], v[150:153], v[120:123]
	v_mfma_f32_16x16x32_bf16 v[108:111], v[166:169], v[142:145], v[108:111]
	v_mfma_f32_16x16x32_bf16 v[104:107], v[166:169], v[150:153], v[104:107]
	v_mfma_f32_16x16x32_bf16 v[92:95], v[178:181], v[142:145], v[92:95]
	v_mfma_f32_16x16x32_bf16 v[88:91], v[178:181], v[150:153], v[88:91]
	s_waitcnt lgkmcnt(0)
	v_mfma_f32_16x16x32_bf16 v[76:79], v[194:197], v[142:145], v[76:79]
	v_mfma_f32_16x16x32_bf16 v[72:75], v[194:197], v[150:153], v[72:75]
	s_setprio 0
	s_barrier
	ds_read_b128 v[198:201], v136
	ds_read_b128 v[202:205], v136 offset:1024
	ds_read_b128 v[206:209], v136 offset:2048
	ds_read_b128 v[210:213], v136 offset:3072
	s_mov_b32 m0, s69
	s_nop 0
	global_load_lds_dwordx4 v128, s[42:43]
	s_mov_b32 m0, s70
	s_nop 0
	global_load_lds_dwordx4 v128, s[44:45]
	s_barrier
	s_setprio 1
	s_waitcnt lgkmcnt(3)
	v_mfma_f32_16x16x32_bf16 v[116:119], v[154:157], v[198:201], v[116:119]
	s_waitcnt lgkmcnt(1)
	v_mfma_f32_16x16x32_bf16 v[112:115], v[154:157], v[206:209], v[112:115]
	v_mfma_f32_16x16x32_bf16 v[100:103], v[162:165], v[198:201], v[100:103]
	v_mfma_f32_16x16x32_bf16 v[96:99], v[162:165], v[206:209], v[96:99]
	v_mfma_f32_16x16x32_bf16 v[84:87], v[170:173], v[198:201], v[84:87]
	v_mfma_f32_16x16x32_bf16 v[80:83], v[170:173], v[206:209], v[80:83]
	v_mfma_f32_16x16x32_bf16 v[68:71], v[190:193], v[198:201], v[68:71]
	v_mfma_f32_16x16x32_bf16 v[64:67], v[190:193], v[206:209], v[64:67]
	v_mfma_f32_16x16x32_bf16 v[116:119], v[158:161], v[202:205], v[116:119]
	s_waitcnt lgkmcnt(0)
	v_mfma_f32_16x16x32_bf16 v[112:115], v[158:161], v[210:213], v[112:115]
	v_mfma_f32_16x16x32_bf16 v[100:103], v[166:169], v[202:205], v[100:103]
	v_mfma_f32_16x16x32_bf16 v[96:99], v[166:169], v[210:213], v[96:99]
	v_mfma_f32_16x16x32_bf16 v[84:87], v[178:181], v[202:205], v[84:87]
	v_mfma_f32_16x16x32_bf16 v[80:83], v[178:181], v[210:213], v[80:83]
	v_mfma_f32_16x16x32_bf16 v[68:71], v[194:197], v[202:205], v[68:71]
	v_mfma_f32_16x16x32_bf16 v[64:67], v[194:197], v[210:213], v[64:67]
	s_setprio 0
	s_barrier
	ds_read_b128 v[154:157], v130 offset:49152
	ds_read_b128 v[158:161], v130 offset:50176
	ds_read_b128 v[162:165], v131 offset:49152
	ds_read_b128 v[166:169], v131 offset:50176
	ds_read_b128 v[170:173], v132 offset:49152
	ds_read_b128 v[178:181], v132 offset:50176
	ds_read_b128 v[190:193], v133 offset:49152
	ds_read_b128 v[194:197], v133 offset:50176
	s_mov_b32 m0, s71
	s_nop 0
	global_load_lds_dwordx4 v128, s[22:23]
	s_mov_b32 m0, s72
	s_nop 0
	global_load_lds_dwordx4 v128, s[30:31]
	s_barrier
; #define STAGE_B(Bk_, Bkh_, vh_, b, h) do { const char* _s = (h) ? (Bkh_) : (Bk_); const unsigned _v0 = (h) ? (vh_)[0] : voffB, _v1 = (h) ? (vh_)[1] : voffB; const long _d = (h) ? s2Bh : s2B; \
;     glds16(lds0 + (4 + (b) * 2 + (h)) * (HT * 2), _v0, _s); glds16(lds0 + (4 + (b) * 2 + (h)) * (HT * 2) + 8192, _v1, _s + _d); } while (0)
; #define MMA(ai, bj, At_, Bt_) do { __builtin_amdgcn_s_setprio(1); \
;     for (int m = 0; m < 4; ++m) for (int n = 0; n < 2; ++n) for (int k = 0; k < 2; ++k) \
;       acc[ai][bj][m][n] = __builtin_amdgcn_mfma_f32_16x16x32_bf16(At_[m][k], Bt_[n][k], acc[ai][bj][m][n], 0, 0, 0); \
;     __builtin_amdgcn_s_setprio(0); } while (0)
; #define WAIT_V(n) asm volatile("s_waitcnt vmcnt(" #n ")" ::: "memory")
; #define BAR __builtin_amdgcn_s_barrier()
; #define SCHED __builtin_amdgcn_sched_barrier(0)
; template <int EPI>
; __device__ __forceinline__ void gemm_phase(const GemmDesc d, u16* shm, unsigned sx, unsigned srank, unsigned snloc) {
;     ...
;         BAR; MMA(1, 0, At, B0); BAR; SCHED;
;         STAGE_B(B3, B3h, vh, 1, 1);
;         WAIT_V(6); BAR; MMA(1, 1, At, B1); BAR;
;       }
	s_setprio 1
	s_waitcnt lgkmcnt(7)
	v_mfma_f32_16x16x32_bf16 v[60:63], v[154:157], v[138:141], v[60:63]
	v_mfma_f32_16x16x32_bf16 v[56:59], v[154:157], v[146:149], v[56:59]
	s_waitcnt lgkmcnt(5)
	v_mfma_f32_16x16x32_bf16 v[44:47], v[162:165], v[138:141], v[44:47]
	v_mfma_f32_16x16x32_bf16 v[40:43], v[162:165], v[146:149], v[40:43]
	s_waitcnt lgkmcnt(3)
	v_mfma_f32_16x16x32_bf16 v[28:31], v[170:173], v[138:141], v[28:31]
	v_mfma_f32_16x16x32_bf16 v[24:27], v[170:173], v[146:149], v[24:27]
	s_waitcnt lgkmcnt(1)
	v_mfma_f32_16x16x32_bf16 v[12:15], v[190:193], v[138:141], v[12:15]
	v_mfma_f32_16x16x32_bf16 v[8:11], v[190:193], v[146:149], v[8:11]
	v_mfma_f32_16x16x32_bf16 v[60:63], v[158:161], v[142:145], v[60:63]
	v_mfma_f32_16x16x32_bf16 v[56:59], v[158:161], v[150:153], v[56:59]
	v_mfma_f32_16x16x32_bf16 v[44:47], v[166:169], v[142:145], v[44:47]
	v_mfma_f32_16x16x32_bf16 v[40:43], v[166:169], v[150:153], v[40:43]
	v_mfma_f32_16x16x32_bf16 v[28:31], v[178:181], v[142:145], v[28:31]
	v_mfma_f32_16x16x32_bf16 v[24:27], v[178:181], v[150:153], v[24:27]
	s_waitcnt lgkmcnt(0)
	v_mfma_f32_16x16x32_bf16 v[12:15], v[194:197], v[142:145], v[12:15]
	v_mfma_f32_16x16x32_bf16 v[8:11], v[194:197], v[150:153], v[8:11]
	s_setprio 0
	s_barrier
	s_mov_b32 m0, s73
	s_nop 0
	global_load_lds_dwordx4 v128, s[18:19]
	s_mov_b32 m0, s76
	s_nop 0
	global_load_lds_dwordx4 v128, s[4:5]
	s_mov_b64 s[38:39], s[40:41]
	s_mov_b32 s20, s21
	s_add_i32 s21, s20, 2
	s_add_u32 s4, s38, 0xfffc0080
	s_addc_u32 s5, s39, -1
	s_cmp_lt_u32 s20, 14
	s_cselect_b32 s92, s88, s24
	s_cselect_b32 s53, s5, s17
	s_cselect_b32 s52, s4, s16
	s_cselect_b32 s93, s89, s25
	s_cselect_b32 s49, s91, s27
	s_cselect_b32 s48, s90, s26
	s_add_u32 s42, s92, 0x80
	s_addc_u32 s43, s93, 0
	s_add_u32 s22, s52, 0x80
	s_addc_u32 s23, s53, 0
	s_add_u32 s94, s38, 0x20000
	s_addc_u32 s95, s39, 0
	s_add_u32 s96, s92, 0x20000
	s_addc_u32 s97, s93, 0
	s_add_u32 s54, s52, 0x20000
	s_addc_u32 s55, s53, 0
	s_add_u32 s50, s48, 0x20000
	s_addc_u32 s51, s49, 0
	s_add_u32 s46, s52, 0x40000
	s_addc_u32 s47, s53, 0
	s_add_u32 s28, s52, 0x60000
	s_addc_u32 s29, s53, 0
	s_add_u32 s44, s92, 0x20080
	s_addc_u32 s45, s93, 0
	s_add_u32 s30, s52, 0x20080
	s_addc_u32 s31, s53, 0
	s_add_u32 s18, s48, 0x80
	s_addc_u32 s19, s49, 0
	s_add_u32 s4, s48, 0x20080
	s_addc_u32 s5, s49, 0
	s_add_u32 s40, s38, 0x100
	s_addc_u32 s41, s39, 0
	s_add_u32 s88, s88, 0x100
	s_addc_u32 s89, s89, 0
	s_add_u32 s90, s90, 0x100
	s_addc_u32 s91, s91, 0
	s_waitcnt vmcnt(6)
	s_barrier
	s_setprio 1
	v_mfma_f32_16x16x32_bf16 v[52:55], v[154:157], v[198:201], v[52:55]
	v_mfma_f32_16x16x32_bf16 v[48:51], v[154:157], v[206:209], v[48:51]
	v_mfma_f32_16x16x32_bf16 v[36:39], v[162:165], v[198:201], v[36:39]
	v_mfma_f32_16x16x32_bf16 v[32:35], v[162:165], v[206:209], v[32:35]
	v_mfma_f32_16x16x32_bf16 v[20:23], v[170:173], v[198:201], v[20:23]
	v_mfma_f32_16x16x32_bf16 v[16:19], v[170:173], v[206:209], v[16:19]
	v_mfma_f32_16x16x32_bf16 v[4:7], v[190:193], v[198:201], v[4:7]
	v_mfma_f32_16x16x32_bf16 v[0:3], v[190:193], v[206:209], v[0:3]
	v_mfma_f32_16x16x32_bf16 v[52:55], v[158:161], v[202:205], v[52:55]
	v_mfma_f32_16x16x32_bf16 v[48:51], v[158:161], v[210:213], v[48:51]
	v_mfma_f32_16x16x32_bf16 v[36:39], v[166:169], v[202:205], v[36:39]
	v_mfma_f32_16x16x32_bf16 v[32:35], v[166:169], v[210:213], v[32:35]
	v_mfma_f32_16x16x32_bf16 v[20:23], v[178:181], v[202:205], v[20:23]
	v_mfma_f32_16x16x32_bf16 v[16:19], v[178:181], v[210:213], v[16:19]
	v_mfma_f32_16x16x32_bf16 v[4:7], v[194:197], v[202:205], v[4:7]
	v_mfma_f32_16x16x32_bf16 v[0:3], v[194:197], v[210:213], v[0:3]
	s_setprio 0
	s_cmp_lt_u32 s20, 16
	s_barrier
	s_cbranch_scc1 .Lk_qkv
	s_and_saveexec_b64 s[4:5], s[10:11]
	s_cbranch_execz .LBB0_707
	s_barrier

; #define DECODE(t_, z_, pm_, pn_) do { if constexpr (EPI == E_CHDFT) { z_ = (t_) >> 5; pm_ = ((t_) >> 4) & 1; pn_ = (int)sx * 16 + ((t_) & 15); break; } \
;     int wgid = (int)sx * tq + (t_); \
;     z_ = wgid / per; int id = wgid % per; \
;     int nig = WGM * nN, gid = id / nig, fm = gid * WGM, gsz = min(nM - fm, WGM); \
;     pm_ = fm + ((id % nig) % gsz); pn_ = (id % nig) / gsz; } while (0)
; #define STAGE_A(Ak_, b, h) do { const char* _s = (Ak_) + (h) * sHA; \
;     glds16(lds0 + ((b) * 2 + (h)) * (HT * 2), voffA, _s); glds16(lds0 + ((b) * 2 + (h)) * (HT * 2) + 8192, voffA, _s + s2A); } while (0)
; #define LDA(dst, b, h) for (int m = 0; m < 4; ++m) for (int k = 0; k < 2; ++k) \
;     dst[m][k] = *reinterpret_cast<const bf16x8*>((char*)SA(b, h) + lds_byte(wr * 64 + m * 16 + fr, k * 32 + fq * 8))
; template <int EPI>
; __device__ __forceinline__ void gemm_phase(const GemmDesc d, u16* shm, unsigned sx, unsigned srank, unsigned snloc) {
;     ...
;       f32x4 acc[2][2][4][2] = {};
;       bf16x8 At[4][2], B0[2][2], B1[2][2];
;       const int tn = t + (int)snloc;
;       const bool has_next = tn < tq;
;       int zn = z, pmn = pm, pnn = pn; const char *Aun = Au, *Bun = Bu, *Bunh = Buh; unsigned voffBhn[2] = {voffBh[0], voffBh[1]};
;       if (has_next) { DECODE(tn, zn, pmn, pnn); BASES(zn, pmn, pnn, Aun, Bun, Bunh, voffBhn); }
; #pragma unroll 1
;       for (int kt = 0; kt < nt; kt += 2) {
;         const bool lastk = (kt + 2 >= nt);
;         const char* A1 = Au + (long)(kt + 1) * sKA;
;         const char* A2 = lastk ? Aun : Au + (long)(kt + 2) * sKA;
;         const char* B2 = lastk ? Bun : Bu + (long)(kt + 2) * sKB;
;         const char* B2h = lastk ? Bunh : Buh + (long)(kt + 2) * sKB;
;         const unsigned vh[2] = {lastk ? voffBhn[0] : voffBh[0], lastk ? voffBhn[1] : voffBh[1]};
;         const char* A3 = A2 + sKA; const char* B3 = B2 + sKB; const char* B3h = B2h + sKB;
;         LDB(B0, 0, 0); SCHED; LDA(At, 0, 0); STAGE_A(A1, 1, 1);
;         WAIT_L(8); BAR; MMA(0, 0, At, B0); BAR; SCHED;
;         LDB(B1, 0, 1); STAGE_B(B2, B2h, vh, 0, 0);
;         BAR; MMA(0, 1, At, B1); BAR;
;         LDA(At, 0, 1); STAGE_A(A2, 0, 0);
;         BAR; MMA(1, 0, At, B0); BAR; SCHED;
;         STAGE_B(B2, B2h, vh, 0, 1);
;         WAIT_V(6); BAR; MMA(1, 1, At, B1); BAR;
;         LDB(B0, 1, 0); SCHED; LDA(At, 1, 0); STAGE_A(A2, 0, 1);
.LBB0_954:
	s_add_u32 s12, s12, 0x40080
	s_addc_u32 s13, s13, 0
	s_add_u32 s88, s18, 0x100
	s_addc_u32 s89, s19, 0
	s_add_u32 s90, s4, 0x100
	s_addc_u32 s91, s5, 0
	s_mov_b32 s20, 0
	s_waitcnt lgkmcnt(0)
.LBB0_955:
	s_add_i32 s21, s20, 2
	s_add_u32 s4, s12, 0xfffc0080
	s_addc_u32 s5, s13, -1
	s_cmp_lt_u32 s20, 14
	s_cselect_b32 s92, s88, s24
	s_cselect_b32 s51, s5, s17
	s_cselect_b32 s50, s4, s16
	s_cselect_b32 s93, s89, s25
	s_cselect_b32 s47, s91, s35
	s_cselect_b32 s46, s90, s34
	s_add_u32 s40, s92, 0x80
	s_addc_u32 s41, s93, 0
	s_add_u32 s22, s50, 0x80
	s_addc_u32 s23, s51, 0
	s_add_u32 s94, s12, 0x20000
	s_addc_u32 s95, s13, 0
	s_add_u32 s96, s92, 0x20000
	s_addc_u32 s97, s93, 0
	s_add_u32 s52, s50, 0x20000
	s_addc_u32 s53, s51, 0
	s_add_u32 s48, s46, 0x20000
	s_addc_u32 s49, s47, 0
	s_add_u32 s44, s50, 0x40000
	s_addc_u32 s45, s51, 0
	s_add_u32 s28, s50, 0x60000
	s_addc_u32 s29, s51, 0
	s_add_u32 s42, s92, 0x20080
	s_addc_u32 s43, s93, 0
	s_add_u32 s30, s50, 0x20080
	s_addc_u32 s31, s51, 0
	s_add_u32 s18, s46, 0x80
	s_addc_u32 s19, s47, 0
	s_add_u32 s4, s46, 0x20080
	s_addc_u32 s5, s47, 0
	s_add_u32 s38, s12, 0x100
	s_addc_u32 s39, s13, 0
	s_add_u32 s88, s88, 0x100
	s_addc_u32 s89, s89, 0
	s_add_u32 s90, s90, 0x100
	s_addc_u32 s91, s91, 0
	ds_read_b128 v[128:131], v135
	ds_read_b128 v[144:147], v135 offset:1024
	ds_read_b128 v[148:151], v135 offset:2048
	ds_read_b128 v[152:155], v135 offset:3072
	ds_read_b128 v[156:159], v136
	ds_read_b128 v[160:163], v136 offset:1024
	ds_read_b128 v[164:167], v137
	ds_read_b128 v[168:171], v137 offset:1024
	ds_read_b128 v[172:175], v138
	ds_read_b128 v[178:181], v138 offset:1024
	ds_read_b128 v[192:195], v139
	ds_read_b128 v[196:199], v139 offset:1024
	s_mov_b32 m0, s77
	s_nop 0
	global_load_lds_dwordx4 v134, s[12:13]
	s_mov_b32 m0, s78
	s_nop 0
	global_load_lds_dwordx4 v134, s[94:95]
	s_waitcnt lgkmcnt(8)
	s_barrier
	s_setprio 1
	s_waitcnt lgkmcnt(7)
	v_mfma_f32_16x16x32_bf16 v[124:127], v[156:159], v[128:131], 0
	v_mfma_f32_16x16x32_bf16 v[120:123], v[156:159], v[148:151], 0
	s_waitcnt lgkmcnt(5)
	v_mfma_f32_16x16x32_bf16 v[108:111], v[164:167], v[128:131], 0
	v_mfma_f32_16x16x32_bf16 v[104:107], v[164:167], v[148:151], 0
	s_waitcnt lgkmcnt(3)
	v_mfma_f32_16x16x32_bf16 v[92:95], v[172:175], v[128:131], 0
	v_mfma_f32_16x16x32_bf16 v[88:91], v[172:175], v[148:151], 0
	s_waitcnt lgkmcnt(1)
	v_mfma_f32_16x16x32_bf16 v[76:79], v[192:195], v[128:131], 0
	v_mfma_f32_16x16x32_bf16 v[72:75], v[192:195], v[148:151], 0
	v_mfma_f32_16x16x32_bf16 v[124:127], v[160:163], v[144:147], v[124:127]
	v_mfma_f32_16x16x32_bf16 v[120:123], v[160:163], v[152:155], v[120:123]
	v_mfma_f32_16x16x32_bf16 v[108:111], v[168:171], v[144:147], v[108:111]
	v_mfma_f32_16x16x32_bf16 v[104:107], v[168:171], v[152:155], v[104:107]
	v_mfma_f32_16x16x32_bf16 v[92:95], v[178:181], v[144:147], v[92:95]
	v_mfma_f32_16x16x32_bf16 v[88:91], v[178:181], v[152:155], v[88:91]
	s_waitcnt lgkmcnt(0)
	v_mfma_f32_16x16x32_bf16 v[76:79], v[196:199], v[144:147], v[76:79]
	v_mfma_f32_16x16x32_bf16 v[72:75], v[196:199], v[152:155], v[72:75]
	s_setprio 0
	s_barrier
	ds_read_b128 v[200:203], v140
	ds_read_b128 v[204:207], v140 offset:1024
	ds_read_b128 v[208:211], v140 offset:2048
	ds_read_b128 v[212:215], v140 offset:3072
	s_mov_b32 m0, s55
	s_nop 0
	global_load_lds_dwordx4 v134, s[92:93]
	s_mov_b32 m0, s57
	s_nop 0
	global_load_lds_dwordx4 v134, s[96:97]
	s_barrier
	s_setprio 1
	s_waitcnt lgkmcnt(3)
	v_mfma_f32_16x16x32_bf16 v[116:119], v[156:159], v[200:203], 0
	s_waitcnt lgkmcnt(1)
	v_mfma_f32_16x16x32_bf16 v[112:115], v[156:159], v[208:211], 0
	v_mfma_f32_16x16x32_bf16 v[100:103], v[164:167], v[200:203], 0
	v_mfma_f32_16x16x32_bf16 v[96:99], v[164:167], v[208:211], 0
	v_mfma_f32_16x16x32_bf16 v[84:87], v[172:175], v[200:203], 0
	v_mfma_f32_16x16x32_bf16 v[80:83], v[172:175], v[208:211], 0
	v_mfma_f32_16x16x32_bf16 v[68:71], v[192:195], v[200:203], 0
	v_mfma_f32_16x16x32_bf16 v[64:67], v[192:195], v[208:211], 0
	v_mfma_f32_16x16x32_bf16 v[116:119], v[160:163], v[204:207], v[116:119]
	s_waitcnt lgkmcnt(0)
	v_mfma_f32_16x16x32_bf16 v[112:115], v[160:163], v[212:215], v[112:115]
	v_mfma_f32_16x16x32_bf16 v[100:103], v[168:171], v[204:207], v[100:103]
	v_mfma_f32_16x16x32_bf16 v[96:99], v[168:171], v[212:215], v[96:99]
	v_mfma_f32_16x16x32_bf16 v[84:87], v[178:181], v[204:207], v[84:87]
	v_mfma_f32_16x16x32_bf16 v[80:83], v[178:181], v[212:215], v[80:83]
	v_mfma_f32_16x16x32_bf16 v[68:71], v[196:199], v[204:207], v[68:71]
	v_mfma_f32_16x16x32_bf16 v[64:67], v[196:199], v[212:215], v[64:67]
	s_setprio 0
	s_barrier
	ds_read_b128 v[156:159], v136 offset:16384
	ds_read_b128 v[160:163], v136 offset:17408
	ds_read_b128 v[164:167], v137 offset:16384
	ds_read_b128 v[168:171], v137 offset:17408
	ds_read_b128 v[172:175], v138 offset:16384
	ds_read_b128 v[178:181], v138 offset:17408
	ds_read_b128 v[192:195], v139 offset:16384
	ds_read_b128 v[196:199], v139 offset:17408
	s_mov_b32 m0, s54
	s_nop 0
	global_load_lds_dwordx4 v134, s[50:51]
	s_mov_b32 m0, s59
	s_nop 0
	global_load_lds_dwordx4 v134, s[52:53]
	s_barrier
; #define STAGE_A(Ak_, b, h) do { const char* _s = (Ak_) + (h) * sHA; \
;     glds16(lds0 + ((b) * 2 + (h)) * (HT * 2), voffA, _s); glds16(lds0 + ((b) * 2 + (h)) * (HT * 2) + 8192, voffA, _s + s2A); } while (0)
; #define STAGE_B(Bk_, Bkh_, vh_, b, h) do { const char* _s = (h) ? (Bkh_) : (Bk_); const unsigned _v0 = (h) ? (vh_)[0] : voffB, _v1 = (h) ? (vh_)[1] : voffB; const long _d = (h) ? s2Bh : s2B; \
;     glds16(lds0 + (4 + (b) * 2 + (h)) * (HT * 2), _v0, _s); glds16(lds0 + (4 + (b) * 2 + (h)) * (HT * 2) + 8192, _v1, _s + _d); } while (0)
; #define LDA(dst, b, h) for (int m = 0; m < 4; ++m) for (int k = 0; k < 2; ++k) \
;     dst[m][k] = *reinterpret_cast<const bf16x8*>((char*)SA(b, h) + lds_byte(wr * 64 + m * 16 + fr, k * 32 + fq * 8))
; #define LDB(dst, b, h) for (int n = 0; n < 2; ++n) for (int k = 0; k < 2; ++k) \
;     dst[n][k] = *reinterpret_cast<const bf16x8*>((char*)SB(b, h) + lds_byte(wc * 32 + n * 16 + fr, k * 32 + fq * 8))
; #define WAIT_V(n) asm volatile("s_waitcnt vmcnt(" #n ")" ::: "memory")
; #define WAIT_L(n) asm volatile("s_waitcnt lgkmcnt(" #n ")" ::: "memory")
; template <int EPI>
; __device__ __forceinline__ void gemm_phase(const GemmDesc d, u16* shm, unsigned sx, unsigned srank, unsigned snloc) {
;     ...
;       for (int kt = 0; kt < nt; kt += 2) {
;         const bool lastk = (kt + 2 >= nt);
;         const char* A1 = Au + (long)(kt + 1) * sKA;
;         const char* A2 = lastk ? Aun : Au + (long)(kt + 2) * sKA;
;         const char* B2 = lastk ? Bun : Bu + (long)(kt + 2) * sKB;
;         const char* B2h = lastk ? Bunh : Buh + (long)(kt + 2) * sKB;
;         const unsigned vh[2] = {lastk ? voffBhn[0] : voffBh[0], lastk ? voffBhn[1] : voffBh[1]};
;         const char* A3 = A2 + sKA; const char* B3 = B2 + sKB; const char* B3h = B2h + sKB;
;         LDB(B0, 0, 0); SCHED; LDA(At, 0, 0); STAGE_A(A1, 1, 1);
;         WAIT_L(8); BAR; MMA(0, 0, At, B0); BAR; SCHED;
;         LDB(B1, 0, 1); STAGE_B(B2, B2h, vh, 0, 0);
;         BAR; MMA(0, 1, At, B1); BAR;
;         LDA(At, 0, 1); STAGE_A(A2, 0, 0);
;         BAR; MMA(1, 0, At, B0); BAR; SCHED;
;         STAGE_B(B2, B2h, vh, 0, 1);
;         WAIT_V(6); BAR; MMA(1, 1, At, B1); BAR;
;         LDB(B0, 1, 0); SCHED; LDA(At, 1, 0); STAGE_A(A2, 0, 1);
;         WAIT_L(8); BAR; MMA(0, 0, At, B0); BAR; SCHED;
;         LDB(B1, 1, 1); STAGE_B(B3, B3h, vh, 1, 0);
;         BAR; MMA(0, 1, At, B1); BAR;
	s_setprio 1
	s_waitcnt lgkmcnt(7)
	v_mfma_f32_16x16x32_bf16 v[60:63], v[156:159], v[128:131], 0
	v_mfma_f32_16x16x32_bf16 v[56:59], v[156:159], v[148:151], 0
	s_waitcnt lgkmcnt(5)
	v_mfma_f32_16x16x32_bf16 v[44:47], v[164:167], v[128:131], 0
	v_mfma_f32_16x16x32_bf16 v[40:43], v[164:167], v[148:151], 0
	s_waitcnt lgkmcnt(3)
	v_mfma_f32_16x16x32_bf16 v[28:31], v[172:175], v[128:131], 0
	v_mfma_f32_16x16x32_bf16 v[24:27], v[172:175], v[148:151], 0
	s_waitcnt lgkmcnt(1)
	v_mfma_f32_16x16x32_bf16 v[12:15], v[192:195], v[128:131], 0
	v_mfma_f32_16x16x32_bf16 v[8:11], v[192:195], v[148:151], 0
	v_mfma_f32_16x16x32_bf16 v[60:63], v[160:163], v[144:147], v[60:63]
	v_mfma_f32_16x16x32_bf16 v[56:59], v[160:163], v[152:155], v[56:59]
	v_mfma_f32_16x16x32_bf16 v[44:47], v[168:171], v[144:147], v[44:47]
	v_mfma_f32_16x16x32_bf16 v[40:43], v[168:171], v[152:155], v[40:43]
	v_mfma_f32_16x16x32_bf16 v[28:31], v[178:181], v[144:147], v[28:31]
	v_mfma_f32_16x16x32_bf16 v[24:27], v[178:181], v[152:155], v[24:27]
	s_waitcnt lgkmcnt(0)
	v_mfma_f32_16x16x32_bf16 v[12:15], v[196:199], v[144:147], v[12:15]
	v_mfma_f32_16x16x32_bf16 v[8:11], v[196:199], v[152:155], v[8:11]
	s_setprio 0
	s_barrier
	s_mov_b32 m0, s62
	s_nop 0
	global_load_lds_dwordx4 v134, s[46:47]
	s_mov_b32 m0, s63
	s_nop 0
	global_load_lds_dwordx4 v134, s[48:49]
	s_waitcnt vmcnt(6)
	s_barrier
	s_setprio 1
	v_mfma_f32_16x16x32_bf16 v[52:55], v[156:159], v[200:203], 0
	v_mfma_f32_16x16x32_bf16 v[48:51], v[156:159], v[208:211], 0
	v_mfma_f32_16x16x32_bf16 v[36:39], v[164:167], v[200:203], 0
	v_mfma_f32_16x16x32_bf16 v[32:35], v[164:167], v[208:211], 0
	v_mfma_f32_16x16x32_bf16 v[20:23], v[172:175], v[200:203], 0
	v_mfma_f32_16x16x32_bf16 v[16:19], v[172:175], v[208:211], 0
	v_mfma_f32_16x16x32_bf16 v[4:7], v[192:195], v[200:203], 0
	v_mfma_f32_16x16x32_bf16 v[0:3], v[192:195], v[208:211], 0
	v_mfma_f32_16x16x32_bf16 v[52:55], v[160:163], v[204:207], v[52:55]
	v_mfma_f32_16x16x32_bf16 v[48:51], v[160:163], v[212:215], v[48:51]
	v_mfma_f32_16x16x32_bf16 v[36:39], v[168:171], v[204:207], v[36:39]
	v_mfma_f32_16x16x32_bf16 v[32:35], v[168:171], v[212:215], v[32:35]
	v_mfma_f32_16x16x32_bf16 v[20:23], v[178:181], v[204:207], v[20:23]
	v_mfma_f32_16x16x32_bf16 v[16:19], v[178:181], v[212:215], v[16:19]
	v_mfma_f32_16x16x32_bf16 v[4:7], v[196:199], v[204:207], v[4:7]
	v_mfma_f32_16x16x32_bf16 v[0:3], v[196:199], v[212:215], v[0:3]
	s_setprio 0
	s_barrier
	ds_read_b128 v[128:131], v141
	ds_read_b128 v[144:147], v141 offset:1024
	ds_read_b128 v[148:151], v141 offset:2048
	ds_read_b128 v[152:155], v141 offset:3072
	ds_read_b128 v[156:159], v136 offset:32768
	ds_read_b128 v[160:163], v136 offset:33792
	ds_read_b128 v[164:167], v137 offset:32768
	ds_read_b128 v[168:171], v137 offset:33792
	ds_read_b128 v[172:175], v138 offset:32768
	ds_read_b128 v[178:181], v138 offset:33792
	ds_read_b128 v[192:195], v139 offset:32768
	ds_read_b128 v[196:199], v139 offset:33792
	s_mov_b32 m0, s64
	s_nop 0
	global_load_lds_dwordx4 v134, s[44:45]
	s_mov_b32 m0, s65
	s_nop 0
	global_load_lds_dwordx4 v134, s[28:29]
	s_waitcnt lgkmcnt(8)
	s_barrier
	s_setprio 1
	s_waitcnt lgkmcnt(7)
	v_mfma_f32_16x16x32_bf16 v[124:127], v[156:159], v[128:131], v[124:127]
	v_mfma_f32_16x16x32_bf16 v[120:123], v[156:159], v[148:151], v[120:123]
	s_waitcnt lgkmcnt(5)
	v_mfma_f32_16x16x32_bf16 v[108:111], v[164:167], v[128:131], v[108:111]
	v_mfma_f32_16x16x32_bf16 v[104:107], v[164:167], v[148:151], v[104:107]
	s_waitcnt lgkmcnt(3)
	v_mfma_f32_16x16x32_bf16 v[92:95], v[172:175], v[128:131], v[92:95]
	v_mfma_f32_16x16x32_bf16 v[88:91], v[172:175], v[148:151], v[88:91]
	s_waitcnt lgkmcnt(1)
	v_mfma_f32_16x16x32_bf16 v[76:79], v[192:195], v[128:131], v[76:79]
	v_mfma_f32_16x16x32_bf16 v[72:75], v[192:195], v[148:151], v[72:75]
	v_mfma_f32_16x16x32_bf16 v[124:127], v[160:163], v[144:147], v[124:127]
	v_mfma_f32_16x16x32_bf16 v[120:123], v[160:163], v[152:155], v[120:123]
	v_mfma_f32_16x16x32_bf16 v[108:111], v[168:171], v[144:147], v[108:111]
	v_mfma_f32_16x16x32_bf16 v[104:107], v[168:171], v[152:155], v[104:107]
	v_mfma_f32_16x16x32_bf16 v[92:95], v[178:181], v[144:147], v[92:95]
	v_mfma_f32_16x16x32_bf16 v[88:91], v[178:181], v[152:155], v[88:91]
	s_waitcnt lgkmcnt(0)
	v_mfma_f32_16x16x32_bf16 v[76:79], v[196:199], v[144:147], v[76:79]
	v_mfma_f32_16x16x32_bf16 v[72:75], v[196:199], v[152:155], v[72:75]
	s_setprio 0
	s_barrier
	ds_read_b128 v[200:203], v142
	ds_read_b128 v[204:207], v142 offset:1024
	ds_read_b128 v[208:211], v142 offset:2048
	ds_read_b128 v[212:215], v142 offset:3072
	s_mov_b32 m0, s69
	s_nop 0
	global_load_lds_dwordx4 v134, s[40:41]
	s_mov_b32 m0, s70
	s_nop 0
	global_load_lds_dwordx4 v134, s[42:43]
	s_barrier
	s_setprio 1
	s_waitcnt lgkmcnt(3)
	v_mfma_f32_16x16x32_bf16 v[116:119], v[156:159], v[200:203], v[116:119]
	s_waitcnt lgkmcnt(1)
	v_mfma_f32_16x16x32_bf16 v[112:115], v[156:159], v[208:211], v[112:115]
	v_mfma_f32_16x16x32_bf16 v[100:103], v[164:167], v[200:203], v[100:103]
	v_mfma_f32_16x16x32_bf16 v[96:99], v[164:167], v[208:211], v[96:99]
	v_mfma_f32_16x16x32_bf16 v[84:87], v[172:175], v[200:203], v[84:87]
	v_mfma_f32_16x16x32_bf16 v[80:83], v[172:175], v[208:211], v[80:83]
	v_mfma_f32_16x16x32_bf16 v[68:71], v[192:195], v[200:203], v[68:71]
	v_mfma_f32_16x16x32_bf16 v[64:67], v[192:195], v[208:211], v[64:67]
	v_mfma_f32_16x16x32_bf16 v[116:119], v[160:163], v[204:207], v[116:119]
	s_waitcnt lgkmcnt(0)
	v_mfma_f32_16x16x32_bf16 v[112:115], v[160:163], v[212:215], v[112:115]
	v_mfma_f32_16x16x32_bf16 v[100:103], v[168:171], v[204:207], v[100:103]
	v_mfma_f32_16x16x32_bf16 v[96:99], v[168:171], v[212:215], v[96:99]
	v_mfma_f32_16x16x32_bf16 v[84:87], v[178:181], v[204:207], v[84:87]
	v_mfma_f32_16x16x32_bf16 v[80:83], v[178:181], v[212:215], v[80:83]
	v_mfma_f32_16x16x32_bf16 v[68:71], v[196:199], v[204:207], v[68:71]
	v_mfma_f32_16x16x32_bf16 v[64:67], v[196:199], v[212:215], v[64:67]
	s_setprio 0
	s_barrier
; #define STAGE_A(Ak_, b, h) do { const char* _s = (Ak_) + (h) * sHA; \
;     glds16(lds0 + ((b) * 2 + (h)) * (HT * 2), voffA, _s); glds16(lds0 + ((b) * 2 + (h)) * (HT * 2) + 8192, voffA, _s + s2A); } while (0)
; #define STAGE_B(Bk_, Bkh_, vh_, b, h) do { const char* _s = (h) ? (Bkh_) : (Bk_); const unsigned _v0 = (h) ? (vh_)[0] : voffB, _v1 = (h) ? (vh_)[1] : voffB; const long _d = (h) ? s2Bh : s2B; \
;     glds16(lds0 + (4 + (b) * 2 + (h)) * (HT * 2), _v0, _s); glds16(lds0 + (4 + (b) * 2 + (h)) * (HT * 2) + 8192, _v1, _s + _d); } while (0)
; #define LDA(dst, b, h) for (int m = 0; m < 4; ++m) for (int k = 0; k < 2; ++k) \
;     dst[m][k] = *reinterpret_cast<const bf16x8*>((char*)SA(b, h) + lds_byte(wr * 64 + m * 16 + fr, k * 32 + fq * 8))
; #define WAIT_V(n) asm volatile("s_waitcnt vmcnt(" #n ")" ::: "memory")
; #define WAIT_L(n) asm volatile("s_waitcnt lgkmcnt(" #n ")" ::: "memory")
; template <int EPI>
; __device__ __forceinline__ void gemm_phase(const GemmDesc d, u16* shm, unsigned sx, unsigned srank, unsigned snloc) {
;     ...
;       for (int kt = 0; kt < nt; kt += 2) {
;         const bool lastk = (kt + 2 >= nt);
;         const char* A1 = Au + (long)(kt + 1) * sKA;
;         const char* A2 = lastk ? Aun : Au + (long)(kt + 2) * sKA;
;         const char* B2 = lastk ? Bun : Bu + (long)(kt + 2) * sKB;
;         const char* B2h = lastk ? Bunh : Buh + (long)(kt + 2) * sKB;
;         const unsigned vh[2] = {lastk ? voffBhn[0] : voffBh[0], lastk ? voffBhn[1] : voffBh[1]};
;         const char* A3 = A2 + sKA; const char* B3 = B2 + sKB; const char* B3h = B2h + sKB;
;         LDB(B0, 0, 0); SCHED; LDA(At, 0, 0); STAGE_A(A1, 1, 1);
;         WAIT_L(8); BAR; MMA(0, 0, At, B0); BAR; SCHED;
;         LDB(B1, 0, 1); STAGE_B(B2, B2h, vh, 0, 0);
;         BAR; MMA(0, 1, At, B1); BAR;
;         LDA(At, 0, 1); STAGE_A(A2, 0, 0);
;         BAR; MMA(1, 0, At, B0); BAR; SCHED;
;         STAGE_B(B2, B2h, vh, 0, 1);
;         WAIT_V(6); BAR; MMA(1, 1, At, B1); BAR;
;         LDB(B0, 1, 0); SCHED; LDA(At, 1, 0); STAGE_A(A2, 0, 1);
;         WAIT_L(8); BAR; MMA(0, 0, At, B0); BAR; SCHED;
;         LDB(B1, 1, 1); STAGE_B(B3, B3h, vh, 1, 0);
;         BAR; MMA(0, 1, At, B1); BAR;
;         LDA(At, 1, 1); STAGE_A(A3, 1, 0);
;         BAR; MMA(1, 0, At, B0); BAR; SCHED;
;         STAGE_B(B3, B3h, vh, 1, 1);
;         WAIT_V(6); BAR; MMA(1, 1, At, B1); BAR;
;       }
	ds_read_b128 v[156:159], v136 offset:49152
	ds_read_b128 v[160:163], v136 offset:50176
	ds_read_b128 v[164:167], v137 offset:49152
	ds_read_b128 v[168:171], v137 offset:50176
	ds_read_b128 v[172:175], v138 offset:49152
	ds_read_b128 v[178:181], v138 offset:50176
	ds_read_b128 v[192:195], v139 offset:49152
	ds_read_b128 v[196:199], v139 offset:50176
	s_mov_b32 m0, s71
	s_nop 0
	global_load_lds_dwordx4 v134, s[22:23]
	s_mov_b32 m0, s72
	s_nop 0
	global_load_lds_dwordx4 v134, s[30:31]
	s_barrier
	s_setprio 1
	s_waitcnt lgkmcnt(7)
	v_mfma_f32_16x16x32_bf16 v[60:63], v[156:159], v[128:131], v[60:63]
	v_mfma_f32_16x16x32_bf16 v[56:59], v[156:159], v[148:151], v[56:59]
	s_waitcnt lgkmcnt(5)
	v_mfma_f32_16x16x32_bf16 v[44:47], v[164:167], v[128:131], v[44:47]
	v_mfma_f32_16x16x32_bf16 v[40:43], v[164:167], v[148:151], v[40:43]
	s_waitcnt lgkmcnt(3)
	v_mfma_f32_16x16x32_bf16 v[28:31], v[172:175], v[128:131], v[28:31]
	v_mfma_f32_16x16x32_bf16 v[24:27], v[172:175], v[148:151], v[24:27]
	s_waitcnt lgkmcnt(1)
	v_mfma_f32_16x16x32_bf16 v[12:15], v[192:195], v[128:131], v[12:15]
	v_mfma_f32_16x16x32_bf16 v[8:11], v[192:195], v[148:151], v[8:11]
	v_mfma_f32_16x16x32_bf16 v[60:63], v[160:163], v[144:147], v[60:63]
	v_mfma_f32_16x16x32_bf16 v[56:59], v[160:163], v[152:155], v[56:59]
	v_mfma_f32_16x16x32_bf16 v[44:47], v[168:171], v[144:147], v[44:47]
	v_mfma_f32_16x16x32_bf16 v[40:43], v[168:171], v[152:155], v[40:43]
	v_mfma_f32_16x16x32_bf16 v[28:31], v[178:181], v[144:147], v[28:31]
	v_mfma_f32_16x16x32_bf16 v[24:27], v[178:181], v[152:155], v[24:27]
	s_waitcnt lgkmcnt(0)
	v_mfma_f32_16x16x32_bf16 v[12:15], v[196:199], v[144:147], v[12:15]
	v_mfma_f32_16x16x32_bf16 v[8:11], v[196:199], v[152:155], v[8:11]
	s_setprio 0
	s_barrier
	s_mov_b32 m0, s73
	s_nop 0
	global_load_lds_dwordx4 v134, s[18:19]
	s_mov_b32 m0, s76
	s_nop 0
	global_load_lds_dwordx4 v134, s[4:5]
	s_mov_b64 s[12:13], s[38:39]
	s_mov_b32 s20, s21
	s_add_i32 s21, s20, 2
	s_add_u32 s4, s12, 0xfffc0080
	s_addc_u32 s5, s13, -1
	s_cmp_lt_u32 s20, 14
	s_cselect_b32 s92, s88, s24
	s_cselect_b32 s51, s5, s17
	s_cselect_b32 s50, s4, s16
	s_cselect_b32 s93, s89, s25
	s_cselect_b32 s47, s91, s35
	s_cselect_b32 s46, s90, s34
	s_add_u32 s40, s92, 0x80
	s_addc_u32 s41, s93, 0
	s_add_u32 s22, s50, 0x80
	s_addc_u32 s23, s51, 0
	s_add_u32 s94, s12, 0x20000
	s_addc_u32 s95, s13, 0
	s_add_u32 s96, s92, 0x20000
	s_addc_u32 s97, s93, 0
	s_add_u32 s52, s50, 0x20000
	s_addc_u32 s53, s51, 0
	s_add_u32 s48, s46, 0x20000
	s_addc_u32 s49, s47, 0
	s_add_u32 s44, s50, 0x40000
	s_addc_u32 s45, s51, 0
	s_add_u32 s28, s50, 0x60000
	s_addc_u32 s29, s51, 0
	s_add_u32 s42, s92, 0x20080
	s_addc_u32 s43, s93, 0
	s_add_u32 s30, s50, 0x20080
	s_addc_u32 s31, s51, 0
	s_add_u32 s18, s46, 0x80
	s_addc_u32 s19, s47, 0
	s_add_u32 s4, s46, 0x20080
	s_addc_u32 s5, s47, 0
	s_add_u32 s38, s12, 0x100
	s_addc_u32 s39, s13, 0
	s_add_u32 s88, s88, 0x100
	s_addc_u32 s89, s89, 0
	s_add_u32 s90, s90, 0x100
	s_addc_u32 s91, s91, 0
	s_waitcnt vmcnt(6)
	s_barrier
	s_setprio 1
	v_mfma_f32_16x16x32_bf16 v[52:55], v[156:159], v[200:203], v[52:55]
	v_mfma_f32_16x16x32_bf16 v[48:51], v[156:159], v[208:211], v[48:51]
	v_mfma_f32_16x16x32_bf16 v[36:39], v[164:167], v[200:203], v[36:39]
	v_mfma_f32_16x16x32_bf16 v[32:35], v[164:167], v[208:211], v[32:35]
	v_mfma_f32_16x16x32_bf16 v[20:23], v[172:175], v[200:203], v[20:23]
	v_mfma_f32_16x16x32_bf16 v[16:19], v[172:175], v[208:211], v[16:19]
	v_mfma_f32_16x16x32_bf16 v[4:7], v[192:195], v[200:203], v[4:7]
	v_mfma_f32_16x16x32_bf16 v[0:3], v[192:195], v[208:211], v[0:3]
	v_mfma_f32_16x16x32_bf16 v[52:55], v[160:163], v[204:207], v[52:55]
	v_mfma_f32_16x16x32_bf16 v[48:51], v[160:163], v[212:215], v[48:51]
	v_mfma_f32_16x16x32_bf16 v[36:39], v[168:171], v[204:207], v[36:39]
	v_mfma_f32_16x16x32_bf16 v[32:35], v[168:171], v[212:215], v[32:35]
	v_mfma_f32_16x16x32_bf16 v[20:23], v[178:181], v[204:207], v[20:23]
	v_mfma_f32_16x16x32_bf16 v[16:19], v[178:181], v[212:215], v[16:19]
	v_mfma_f32_16x16x32_bf16 v[4:7], v[196:199], v[204:207], v[4:7]
	v_mfma_f32_16x16x32_bf16 v[0:3], v[196:199], v[212:215], v[0:3]
	s_setprio 0
	s_barrier
.Lk_aout:
	ds_read_b128 v[128:131], v135
	ds_read_b128 v[144:147], v135 offset:1024
	ds_read_b128 v[148:151], v135 offset:2048
	ds_read_b128 v[152:155], v135 offset:3072
	ds_read_b128 v[156:159], v136
	ds_read_b128 v[160:163], v136 offset:1024
	ds_read_b128 v[164:167], v137
	ds_read_b128 v[168:171], v137 offset:1024
	ds_read_b128 v[172:175], v138
	ds_read_b128 v[178:181], v138 offset:1024
	ds_read_b128 v[192:195], v139
	ds_read_b128 v[196:199], v139 offset:1024
	s_mov_b32 m0, s77
	s_nop 0
	global_load_lds_dwordx4 v134, s[12:13]
	s_mov_b32 m0, s78
	s_nop 0
	global_load_lds_dwordx4 v134, s[94:95]
	s_waitcnt lgkmcnt(8)
	s_barrier
	s_setprio 1
	s_waitcnt lgkmcnt(7)
	v_mfma_f32_16x16x32_bf16 v[124:127], v[156:159], v[128:131], v[124:127]
	v_mfma_f32_16x16x32_bf16 v[120:123], v[156:159], v[148:151], v[120:123]
	s_waitcnt lgkmcnt(5)
	v_mfma_f32_16x16x32_bf16 v[108:111], v[164:167], v[128:131], v[108:111]
	v_mfma_f32_16x16x32_bf16 v[104:107], v[164:167], v[148:151], v[104:107]
	s_waitcnt lgkmcnt(3)
	v_mfma_f32_16x16x32_bf16 v[92:95], v[172:175], v[128:131], v[92:95]
	v_mfma_f32_16x16x32_bf16 v[88:91], v[172:175], v[148:151], v[88:91]
	s_waitcnt lgkmcnt(1)
	v_mfma_f32_16x16x32_bf16 v[76:79], v[192:195], v[128:131], v[76:79]
	v_mfma_f32_16x16x32_bf16 v[72:75], v[192:195], v[148:151], v[72:75]
	v_mfma_f32_16x16x32_bf16 v[124:127], v[160:163], v[144:147], v[124:127]
	v_mfma_f32_16x16x32_bf16 v[120:123], v[160:163], v[152:155], v[120:123]
	v_mfma_f32_16x16x32_bf16 v[108:111], v[168:171], v[144:147], v[108:111]
	v_mfma_f32_16x16x32_bf16 v[104:107], v[168:171], v[152:155], v[104:107]
	v_mfma_f32_16x16x32_bf16 v[92:95], v[178:181], v[144:147], v[92:95]
	v_mfma_f32_16x16x32_bf16 v[88:91], v[178:181], v[152:155], v[88:91]
	s_waitcnt lgkmcnt(0)
	v_mfma_f32_16x16x32_bf16 v[76:79], v[196:199], v[144:147], v[76:79]
	v_mfma_f32_16x16x32_bf16 v[72:75], v[196:199], v[152:155], v[72:75]
	s_setprio 0
	s_barrier
; #define STAGE_A(Ak_, b, h) do { const char* _s = (Ak_) + (h) * sHA; \
;     glds16(lds0 + ((b) * 2 + (h)) * (HT * 2), voffA, _s); glds16(lds0 + ((b) * 2 + (h)) * (HT * 2) + 8192, voffA, _s + s2A); } while (0)
; #define STAGE_B(Bk_, Bkh_, vh_, b, h) do { const char* _s = (h) ? (Bkh_) : (Bk_); const unsigned _v0 = (h) ? (vh_)[0] : voffB, _v1 = (h) ? (vh_)[1] : voffB; const long _d = (h) ? s2Bh : s2B; \
;     glds16(lds0 + (4 + (b) * 2 + (h)) * (HT * 2), _v0, _s); glds16(lds0 + (4 + (b) * 2 + (h)) * (HT * 2) + 8192, _v1, _s + _d); } while (0)
; #define LDA(dst, b, h) for (int m = 0; m < 4; ++m) for (int k = 0; k < 2; ++k) \
;     dst[m][k] = *reinterpret_cast<const bf16x8*>((char*)SA(b, h) + lds_byte(wr * 64 + m * 16 + fr, k * 32 + fq * 8))
; #define LDB(dst, b, h) for (int n = 0; n < 2; ++n) for (int k = 0; k < 2; ++k) \
;     dst[n][k] = *reinterpret_cast<const bf16x8*>((char*)SB(b, h) + lds_byte(wc * 32 + n * 16 + fr, k * 32 + fq * 8))
; #define MMA(ai, bj, At_, Bt_) do { __builtin_amdgcn_s_setprio(1); \
;     for (int m = 0; m < 4; ++m) for (int n = 0; n < 2; ++n) for (int k = 0; k < 2; ++k) \
;       acc[ai][bj][m][n] = __builtin_amdgcn_mfma_f32_16x16x32_bf16(At_[m][k], Bt_[n][k], acc[ai][bj][m][n], 0, 0, 0); \
;     __builtin_amdgcn_s_setprio(0); } while (0)
; #define WAIT_V(n) asm volatile("s_waitcnt vmcnt(" #n ")" ::: "memory")
; #define WAIT_L(n) asm volatile("s_waitcnt lgkmcnt(" #n ")" ::: "memory")
; #define BAR __builtin_amdgcn_s_barrier()
; #define SCHED __builtin_amdgcn_sched_barrier(0)
; template <int EPI>
; __device__ __forceinline__ void gemm_phase(const GemmDesc d, u16* shm, unsigned sx, unsigned srank, unsigned snloc) {
;     ...
;         LDB(B1, 0, 1); STAGE_B(B2, B2h, vh, 0, 0);
;         BAR; MMA(0, 1, At, B1); BAR;
;         LDA(At, 0, 1); STAGE_A(A2, 0, 0);
;         BAR; MMA(1, 0, At, B0); BAR; SCHED;
;         STAGE_B(B2, B2h, vh, 0, 1);
;         WAIT_V(6); BAR; MMA(1, 1, At, B1); BAR;
;         LDB(B0, 1, 0); SCHED; LDA(At, 1, 0); STAGE_A(A2, 0, 1);
;         WAIT_L(8); BAR; MMA(0, 0, At, B0); BAR; SCHED;
;         LDB(B1, 1, 1); STAGE_B(B3, B3h, vh, 1, 0);
	ds_read_b128 v[200:203], v140
	ds_read_b128 v[204:207], v140 offset:1024
	ds_read_b128 v[208:211], v140 offset:2048
	ds_read_b128 v[212:215], v140 offset:3072
	s_mov_b32 m0, s55
	s_nop 0
	global_load_lds_dwordx4 v134, s[92:93]
	s_mov_b32 m0, s57
	s_nop 0
	global_load_lds_dwordx4 v134, s[96:97]
	s_barrier
	s_setprio 1
	s_waitcnt lgkmcnt(3)
	v_mfma_f32_16x16x32_bf16 v[116:119], v[156:159], v[200:203], v[116:119]
	s_waitcnt lgkmcnt(1)
	v_mfma_f32_16x16x32_bf16 v[112:115], v[156:159], v[208:211], v[112:115]
	v_mfma_f32_16x16x32_bf16 v[100:103], v[164:167], v[200:203], v[100:103]
	v_mfma_f32_16x16x32_bf16 v[96:99], v[164:167], v[208:211], v[96:99]
	v_mfma_f32_16x16x32_bf16 v[84:87], v[172:175], v[200:203], v[84:87]
	v_mfma_f32_16x16x32_bf16 v[80:83], v[172:175], v[208:211], v[80:83]
	v_mfma_f32_16x16x32_bf16 v[68:71], v[192:195], v[200:203], v[68:71]
	v_mfma_f32_16x16x32_bf16 v[64:67], v[192:195], v[208:211], v[64:67]
	v_mfma_f32_16x16x32_bf16 v[116:119], v[160:163], v[204:207], v[116:119]
	s_waitcnt lgkmcnt(0)
	v_mfma_f32_16x16x32_bf16 v[112:115], v[160:163], v[212:215], v[112:115]
	v_mfma_f32_16x16x32_bf16 v[100:103], v[168:171], v[204:207], v[100:103]
	v_mfma_f32_16x16x32_bf16 v[96:99], v[168:171], v[212:215], v[96:99]
	v_mfma_f32_16x16x32_bf16 v[84:87], v[178:181], v[204:207], v[84:87]
	v_mfma_f32_16x16x32_bf16 v[80:83], v[178:181], v[212:215], v[80:83]
	v_mfma_f32_16x16x32_bf16 v[68:71], v[196:199], v[204:207], v[68:71]
	v_mfma_f32_16x16x32_bf16 v[64:67], v[196:199], v[212:215], v[64:67]
	s_setprio 0
	s_barrier
	ds_read_b128 v[156:159], v136 offset:16384
	ds_read_b128 v[160:163], v136 offset:17408
	ds_read_b128 v[164:167], v137 offset:16384
	ds_read_b128 v[168:171], v137 offset:17408
	ds_read_b128 v[172:175], v138 offset:16384
	ds_read_b128 v[178:181], v138 offset:17408
	ds_read_b128 v[192:195], v139 offset:16384
	ds_read_b128 v[196:199], v139 offset:17408
	s_mov_b32 m0, s54
	s_nop 0
	global_load_lds_dwordx4 v134, s[50:51]
	s_mov_b32 m0, s59
	s_nop 0
	global_load_lds_dwordx4 v134, s[52:53]
	s_barrier
	s_setprio 1
	s_waitcnt lgkmcnt(7)
	v_mfma_f32_16x16x32_bf16 v[60:63], v[156:159], v[128:131], v[60:63]
	v_mfma_f32_16x16x32_bf16 v[56:59], v[156:159], v[148:151], v[56:59]
	s_waitcnt lgkmcnt(5)
	v_mfma_f32_16x16x32_bf16 v[44:47], v[164:167], v[128:131], v[44:47]
	v_mfma_f32_16x16x32_bf16 v[40:43], v[164:167], v[148:151], v[40:43]
	s_waitcnt lgkmcnt(3)
	v_mfma_f32_16x16x32_bf16 v[28:31], v[172:175], v[128:131], v[28:31]
	v_mfma_f32_16x16x32_bf16 v[24:27], v[172:175], v[148:151], v[24:27]
	s_waitcnt lgkmcnt(1)
	v_mfma_f32_16x16x32_bf16 v[12:15], v[192:195], v[128:131], v[12:15]
	v_mfma_f32_16x16x32_bf16 v[8:11], v[192:195], v[148:151], v[8:11]
	v_mfma_f32_16x16x32_bf16 v[60:63], v[160:163], v[144:147], v[60:63]
	v_mfma_f32_16x16x32_bf16 v[56:59], v[160:163], v[152:155], v[56:59]
	v_mfma_f32_16x16x32_bf16 v[44:47], v[168:171], v[144:147], v[44:47]
	v_mfma_f32_16x16x32_bf16 v[40:43], v[168:171], v[152:155], v[40:43]
	v_mfma_f32_16x16x32_bf16 v[28:31], v[178:181], v[144:147], v[28:31]
	v_mfma_f32_16x16x32_bf16 v[24:27], v[178:181], v[152:155], v[24:27]
	s_waitcnt lgkmcnt(0)
	v_mfma_f32_16x16x32_bf16 v[12:15], v[196:199], v[144:147], v[12:15]
	v_mfma_f32_16x16x32_bf16 v[8:11], v[196:199], v[152:155], v[8:11]
	s_setprio 0
	s_barrier
	s_mov_b32 m0, s62
	s_nop 0
	global_load_lds_dwordx4 v134, s[46:47]
	s_mov_b32 m0, s63
	s_nop 0
	global_load_lds_dwordx4 v134, s[48:49]
	s_waitcnt vmcnt(6)
	s_barrier
	s_setprio 1
	v_mfma_f32_16x16x32_bf16 v[52:55], v[156:159], v[200:203], v[52:55]
	v_mfma_f32_16x16x32_bf16 v[48:51], v[156:159], v[208:211], v[48:51]
	v_mfma_f32_16x16x32_bf16 v[36:39], v[164:167], v[200:203], v[36:39]
	v_mfma_f32_16x16x32_bf16 v[32:35], v[164:167], v[208:211], v[32:35]
	v_mfma_f32_16x16x32_bf16 v[20:23], v[172:175], v[200:203], v[20:23]
	v_mfma_f32_16x16x32_bf16 v[16:19], v[172:175], v[208:211], v[16:19]
	v_mfma_f32_16x16x32_bf16 v[4:7], v[192:195], v[200:203], v[4:7]
	v_mfma_f32_16x16x32_bf16 v[0:3], v[192:195], v[208:211], v[0:3]
	v_mfma_f32_16x16x32_bf16 v[52:55], v[160:163], v[204:207], v[52:55]
	v_mfma_f32_16x16x32_bf16 v[48:51], v[160:163], v[212:215], v[48:51]
	v_mfma_f32_16x16x32_bf16 v[36:39], v[168:171], v[204:207], v[36:39]
	v_mfma_f32_16x16x32_bf16 v[32:35], v[168:171], v[212:215], v[32:35]
	v_mfma_f32_16x16x32_bf16 v[20:23], v[178:181], v[204:207], v[20:23]
	v_mfma_f32_16x16x32_bf16 v[16:19], v[178:181], v[212:215], v[16:19]
	v_mfma_f32_16x16x32_bf16 v[4:7], v[196:199], v[204:207], v[4:7]
	v_mfma_f32_16x16x32_bf16 v[0:3], v[196:199], v[212:215], v[0:3]
	s_setprio 0
	s_barrier
	ds_read_b128 v[128:131], v141
	ds_read_b128 v[144:147], v141 offset:1024
	ds_read_b128 v[148:151], v141 offset:2048
	ds_read_b128 v[152:155], v141 offset:3072
	ds_read_b128 v[156:159], v136 offset:32768
	ds_read_b128 v[160:163], v136 offset:33792
	ds_read_b128 v[164:167], v137 offset:32768
	ds_read_b128 v[168:171], v137 offset:33792
	ds_read_b128 v[172:175], v138 offset:32768
	ds_read_b128 v[178:181], v138 offset:33792
	ds_read_b128 v[192:195], v139 offset:32768
	ds_read_b128 v[196:199], v139 offset:33792
	s_mov_b32 m0, s64
	s_nop 0
	global_load_lds_dwordx4 v134, s[44:45]
	s_mov_b32 m0, s65
	s_nop 0
	global_load_lds_dwordx4 v134, s[28:29]
	s_waitcnt lgkmcnt(8)
	s_barrier
; #define STAGE_A(Ak_, b, h) do { const char* _s = (Ak_) + (h) * sHA; \
;     glds16(lds0 + ((b) * 2 + (h)) * (HT * 2), voffA, _s); glds16(lds0 + ((b) * 2 + (h)) * (HT * 2) + 8192, voffA, _s + s2A); } while (0)
; #define STAGE_B(Bk_, Bkh_, vh_, b, h) do { const char* _s = (h) ? (Bkh_) : (Bk_); const unsigned _v0 = (h) ? (vh_)[0] : voffB, _v1 = (h) ? (vh_)[1] : voffB; const long _d = (h) ? s2Bh : s2B; \
;     glds16(lds0 + (4 + (b) * 2 + (h)) * (HT * 2), _v0, _s); glds16(lds0 + (4 + (b) * 2 + (h)) * (HT * 2) + 8192, _v1, _s + _d); } while (0)
; #define LDA(dst, b, h) for (int m = 0; m < 4; ++m) for (int k = 0; k < 2; ++k) \
;     dst[m][k] = *reinterpret_cast<const bf16x8*>((char*)SA(b, h) + lds_byte(wr * 64 + m * 16 + fr, k * 32 + fq * 8))
; #define LDB(dst, b, h) for (int n = 0; n < 2; ++n) for (int k = 0; k < 2; ++k) \
;     dst[n][k] = *reinterpret_cast<const bf16x8*>((char*)SB(b, h) + lds_byte(wc * 32 + n * 16 + fr, k * 32 + fq * 8))
; #define MMA(ai, bj, At_, Bt_) do { __builtin_amdgcn_s_setprio(1); \
;     for (int m = 0; m < 4; ++m) for (int n = 0; n < 2; ++n) for (int k = 0; k < 2; ++k) \
;       acc[ai][bj][m][n] = __builtin_amdgcn_mfma_f32_16x16x32_bf16(At_[m][k], Bt_[n][k], acc[ai][bj][m][n], 0, 0, 0); \
;     __builtin_amdgcn_s_setprio(0); } while (0)
; #define WAIT_L(n) asm volatile("s_waitcnt lgkmcnt(" #n ")" ::: "memory")
; #define BAR __builtin_amdgcn_s_barrier()
; #define SCHED __builtin_amdgcn_sched_barrier(0)
; template <int EPI>
; __device__ __forceinline__ void gemm_phase(const GemmDesc d, u16* shm, unsigned sx, unsigned srank, unsigned snloc) {
;     ...
;         WAIT_L(8); BAR; MMA(0, 0, At, B0); BAR; SCHED;
;         LDB(B1, 1, 1); STAGE_B(B3, B3h, vh, 1, 0);
;         BAR; MMA(0, 1, At, B1); BAR;
;         LDA(At, 1, 1); STAGE_A(A3, 1, 0);
;         BAR; MMA(1, 0, At, B0); BAR; SCHED;
	s_setprio 1
	s_waitcnt lgkmcnt(7)
	v_mfma_f32_16x16x32_bf16 v[124:127], v[156:159], v[128:131], v[124:127]
	v_mfma_f32_16x16x32_bf16 v[120:123], v[156:159], v[148:151], v[120:123]
	s_waitcnt lgkmcnt(5)
	v_mfma_f32_16x16x32_bf16 v[108:111], v[164:167], v[128:131], v[108:111]
	v_mfma_f32_16x16x32_bf16 v[104:107], v[164:167], v[148:151], v[104:107]
	s_waitcnt lgkmcnt(3)
	v_mfma_f32_16x16x32_bf16 v[92:95], v[172:175], v[128:131], v[92:95]
	v_mfma_f32_16x16x32_bf16 v[88:91], v[172:175], v[148:151], v[88:91]
	s_waitcnt lgkmcnt(1)
	v_mfma_f32_16x16x32_bf16 v[76:79], v[192:195], v[128:131], v[76:79]
	v_mfma_f32_16x16x32_bf16 v[72:75], v[192:195], v[148:151], v[72:75]
	v_mfma_f32_16x16x32_bf16 v[124:127], v[160:163], v[144:147], v[124:127]
	v_mfma_f32_16x16x32_bf16 v[120:123], v[160:163], v[152:155], v[120:123]
	v_mfma_f32_16x16x32_bf16 v[108:111], v[168:171], v[144:147], v[108:111]
	v_mfma_f32_16x16x32_bf16 v[104:107], v[168:171], v[152:155], v[104:107]
	v_mfma_f32_16x16x32_bf16 v[92:95], v[178:181], v[144:147], v[92:95]
	v_mfma_f32_16x16x32_bf16 v[88:91], v[178:181], v[152:155], v[88:91]
	s_waitcnt lgkmcnt(0)
	v_mfma_f32_16x16x32_bf16 v[76:79], v[196:199], v[144:147], v[76:79]
	v_mfma_f32_16x16x32_bf16 v[72:75], v[196:199], v[152:155], v[72:75]
	s_setprio 0
	s_barrier
	ds_read_b128 v[200:203], v142
	ds_read_b128 v[204:207], v142 offset:1024
	ds_read_b128 v[208:211], v142 offset:2048
	ds_read_b128 v[212:215], v142 offset:3072
	s_mov_b32 m0, s69
	s_nop 0
	global_load_lds_dwordx4 v134, s[40:41]
	s_mov_b32 m0, s70
	s_nop 0
	global_load_lds_dwordx4 v134, s[42:43]
	s_barrier
	s_setprio 1
	s_waitcnt lgkmcnt(3)
	v_mfma_f32_16x16x32_bf16 v[116:119], v[156:159], v[200:203], v[116:119]
	s_waitcnt lgkmcnt(1)
	v_mfma_f32_16x16x32_bf16 v[112:115], v[156:159], v[208:211], v[112:115]
	v_mfma_f32_16x16x32_bf16 v[100:103], v[164:167], v[200:203], v[100:103]
	v_mfma_f32_16x16x32_bf16 v[96:99], v[164:167], v[208:211], v[96:99]
	v_mfma_f32_16x16x32_bf16 v[84:87], v[172:175], v[200:203], v[84:87]
	v_mfma_f32_16x16x32_bf16 v[80:83], v[172:175], v[208:211], v[80:83]
	v_mfma_f32_16x16x32_bf16 v[68:71], v[192:195], v[200:203], v[68:71]
	v_mfma_f32_16x16x32_bf16 v[64:67], v[192:195], v[208:211], v[64:67]
	v_mfma_f32_16x16x32_bf16 v[116:119], v[160:163], v[204:207], v[116:119]
	s_waitcnt lgkmcnt(0)
	v_mfma_f32_16x16x32_bf16 v[112:115], v[160:163], v[212:215], v[112:115]
	v_mfma_f32_16x16x32_bf16 v[100:103], v[168:171], v[204:207], v[100:103]
	v_mfma_f32_16x16x32_bf16 v[96:99], v[168:171], v[212:215], v[96:99]
	v_mfma_f32_16x16x32_bf16 v[84:87], v[178:181], v[204:207], v[84:87]
	v_mfma_f32_16x16x32_bf16 v[80:83], v[178:181], v[212:215], v[80:83]
	v_mfma_f32_16x16x32_bf16 v[68:71], v[196:199], v[204:207], v[68:71]
	v_mfma_f32_16x16x32_bf16 v[64:67], v[196:199], v[212:215], v[64:67]
	s_setprio 0
	s_barrier
	ds_read_b128 v[156:159], v136 offset:49152
	ds_read_b128 v[160:163], v136 offset:50176
	ds_read_b128 v[164:167], v137 offset:49152
	ds_read_b128 v[168:171], v137 offset:50176
	ds_read_b128 v[172:175], v138 offset:49152
	ds_read_b128 v[178:181], v138 offset:50176
	ds_read_b128 v[192:195], v139 offset:49152
	ds_read_b128 v[196:199], v139 offset:50176
	s_mov_b32 m0, s71
	s_nop 0
	global_load_lds_dwordx4 v134, s[22:23]
	s_mov_b32 m0, s72
	s_nop 0
	global_load_lds_dwordx4 v134, s[30:31]
	s_barrier
; #define STAGE_B(Bk_, Bkh_, vh_, b, h) do { const char* _s = (h) ? (Bkh_) : (Bk_); const unsigned _v0 = (h) ? (vh_)[0] : voffB, _v1 = (h) ? (vh_)[1] : voffB; const long _d = (h) ? s2Bh : s2B; \
;     glds16(lds0 + (4 + (b) * 2 + (h)) * (HT * 2), _v0, _s); glds16(lds0 + (4 + (b) * 2 + (h)) * (HT * 2) + 8192, _v1, _s + _d); } while (0)
; #define MMA(ai, bj, At_, Bt_) do { __builtin_amdgcn_s_setprio(1); \
;     for (int m = 0; m < 4; ++m) for (int n = 0; n < 2; ++n) for (int k = 0; k < 2; ++k) \
;       acc[ai][bj][m][n] = __builtin_amdgcn_mfma_f32_16x16x32_bf16(At_[m][k], Bt_[n][k], acc[ai][bj][m][n], 0, 0, 0); \
;     __builtin_amdgcn_s_setprio(0); } while (0)
; #define WAIT_V(n) asm volatile("s_waitcnt vmcnt(" #n ")" ::: "memory")
; #define BAR __builtin_amdgcn_s_barrier()
; #define SCHED __builtin_amdgcn_sched_barrier(0)
; template <int EPI>
; __device__ __forceinline__ void gemm_phase(const GemmDesc d, u16* shm, unsigned sx, unsigned srank, unsigned snloc) {
;     ...
;         BAR; MMA(1, 0, At, B0); BAR; SCHED;
;         STAGE_B(B3, B3h, vh, 1, 1);
;         WAIT_V(6); BAR; MMA(1, 1, At, B1); BAR;
;       }
	s_setprio 1
	s_waitcnt lgkmcnt(7)
	v_mfma_f32_16x16x32_bf16 v[60:63], v[156:159], v[128:131], v[60:63]
	v_mfma_f32_16x16x32_bf16 v[56:59], v[156:159], v[148:151], v[56:59]
	s_waitcnt lgkmcnt(5)
	v_mfma_f32_16x16x32_bf16 v[44:47], v[164:167], v[128:131], v[44:47]
	v_mfma_f32_16x16x32_bf16 v[40:43], v[164:167], v[148:151], v[40:43]
	s_waitcnt lgkmcnt(3)
	v_mfma_f32_16x16x32_bf16 v[28:31], v[172:175], v[128:131], v[28:31]
	v_mfma_f32_16x16x32_bf16 v[24:27], v[172:175], v[148:151], v[24:27]
	s_waitcnt lgkmcnt(1)
	v_mfma_f32_16x16x32_bf16 v[12:15], v[192:195], v[128:131], v[12:15]
	v_mfma_f32_16x16x32_bf16 v[8:11], v[192:195], v[148:151], v[8:11]
	v_mfma_f32_16x16x32_bf16 v[60:63], v[160:163], v[144:147], v[60:63]
	v_mfma_f32_16x16x32_bf16 v[56:59], v[160:163], v[152:155], v[56:59]
	v_mfma_f32_16x16x32_bf16 v[44:47], v[168:171], v[144:147], v[44:47]
	v_mfma_f32_16x16x32_bf16 v[40:43], v[168:171], v[152:155], v[40:43]
	v_mfma_f32_16x16x32_bf16 v[28:31], v[178:181], v[144:147], v[28:31]
	v_mfma_f32_16x16x32_bf16 v[24:27], v[178:181], v[152:155], v[24:27]
	s_waitcnt lgkmcnt(0)
	v_mfma_f32_16x16x32_bf16 v[12:15], v[196:199], v[144:147], v[12:15]
	v_mfma_f32_16x16x32_bf16 v[8:11], v[196:199], v[152:155], v[8:11]
	s_setprio 0
	s_barrier
	s_mov_b32 m0, s73
	s_nop 0
	global_load_lds_dwordx4 v134, s[18:19]
	s_mov_b32 m0, s76
	s_nop 0
	global_load_lds_dwordx4 v134, s[4:5]
	s_mov_b64 s[12:13], s[38:39]
	s_mov_b32 s20, s21
	s_add_i32 s21, s20, 2
	s_add_u32 s4, s12, 0xfffc0080
	s_addc_u32 s5, s13, -1
	s_cmp_lt_u32 s20, 14
	s_cselect_b32 s92, s88, s24
	s_cselect_b32 s51, s5, s17
	s_cselect_b32 s50, s4, s16
	s_cselect_b32 s93, s89, s25
	s_cselect_b32 s47, s91, s35
	s_cselect_b32 s46, s90, s34
	s_add_u32 s40, s92, 0x80
	s_addc_u32 s41, s93, 0
	s_add_u32 s22, s50, 0x80
	s_addc_u32 s23, s51, 0
	s_add_u32 s94, s12, 0x20000
	s_addc_u32 s95, s13, 0
	s_add_u32 s96, s92, 0x20000
	s_addc_u32 s97, s93, 0
	s_add_u32 s52, s50, 0x20000
	s_addc_u32 s53, s51, 0
	s_add_u32 s48, s46, 0x20000
	s_addc_u32 s49, s47, 0
	s_add_u32 s44, s50, 0x40000
	s_addc_u32 s45, s51, 0
	s_add_u32 s28, s50, 0x60000
	s_addc_u32 s29, s51, 0
	s_add_u32 s42, s92, 0x20080
	s_addc_u32 s43, s93, 0
	s_add_u32 s30, s50, 0x20080
	s_addc_u32 s31, s51, 0
	s_add_u32 s18, s46, 0x80
	s_addc_u32 s19, s47, 0
	s_add_u32 s4, s46, 0x20080
	s_addc_u32 s5, s47, 0
	s_add_u32 s38, s12, 0x100
	s_addc_u32 s39, s13, 0
	s_add_u32 s88, s88, 0x100
	s_addc_u32 s89, s89, 0
	s_add_u32 s90, s90, 0x100
	s_addc_u32 s91, s91, 0
	s_waitcnt vmcnt(6)
	s_barrier
	s_setprio 1
	v_mfma_f32_16x16x32_bf16 v[52:55], v[156:159], v[200:203], v[52:55]
	v_mfma_f32_16x16x32_bf16 v[48:51], v[156:159], v[208:211], v[48:51]
	v_mfma_f32_16x16x32_bf16 v[36:39], v[164:167], v[200:203], v[36:39]
	v_mfma_f32_16x16x32_bf16 v[32:35], v[164:167], v[208:211], v[32:35]
	v_mfma_f32_16x16x32_bf16 v[20:23], v[172:175], v[200:203], v[20:23]
	v_mfma_f32_16x16x32_bf16 v[16:19], v[172:175], v[208:211], v[16:19]
	v_mfma_f32_16x16x32_bf16 v[4:7], v[192:195], v[200:203], v[4:7]
	v_mfma_f32_16x16x32_bf16 v[0:3], v[192:195], v[208:211], v[0:3]
	v_mfma_f32_16x16x32_bf16 v[52:55], v[160:163], v[204:207], v[52:55]
	v_mfma_f32_16x16x32_bf16 v[48:51], v[160:163], v[212:215], v[48:51]
	v_mfma_f32_16x16x32_bf16 v[36:39], v[168:171], v[204:207], v[36:39]
	v_mfma_f32_16x16x32_bf16 v[32:35], v[168:171], v[212:215], v[32:35]
	v_mfma_f32_16x16x32_bf16 v[20:23], v[178:181], v[204:207], v[20:23]
	v_mfma_f32_16x16x32_bf16 v[16:19], v[178:181], v[212:215], v[16:19]
	v_mfma_f32_16x16x32_bf16 v[4:7], v[196:199], v[204:207], v[4:7]
	v_mfma_f32_16x16x32_bf16 v[0:3], v[196:199], v[212:215], v[0:3]
	s_setprio 0
	s_cmp_lt_u32 s20, 16
	s_barrier
	s_cbranch_scc1 .Lk_aout
	s_and_saveexec_b64 s[4:5], s[10:11]
	s_cbranch_execz .LBB0_958
	s_barrier

; #define DECODE(t_, z_, pm_, pn_) do { if constexpr (EPI == E_CHDFT) { z_ = (t_) >> 5; pm_ = ((t_) >> 4) & 1; pn_ = (int)sx * 16 + ((t_) & 15); break; } \
;     int wgid = (int)sx * tq + (t_); \
;     z_ = wgid / per; int id = wgid % per; \
;     int nig = WGM * nN, gid = id / nig, fm = gid * WGM, gsz = min(nM - fm, WGM); \
;     pm_ = fm + ((id % nig) % gsz); pn_ = (id % nig) / gsz; } while (0)
; #define STAGE_A(Ak_, b, h) do { const char* _s = (Ak_) + (h) * sHA; \
;     glds16(lds0 + ((b) * 2 + (h)) * (HT * 2), voffA, _s); glds16(lds0 + ((b) * 2 + (h)) * (HT * 2) + 8192, voffA, _s + s2A); } while (0)
; #define STAGE_B(Bk_, Bkh_, vh_, b, h) do { const char* _s = (h) ? (Bkh_) : (Bk_); const unsigned _v0 = (h) ? (vh_)[0] : voffB, _v1 = (h) ? (vh_)[1] : voffB; const long _d = (h) ? s2Bh : s2B; \
;     glds16(lds0 + (4 + (b) * 2 + (h)) * (HT * 2), _v0, _s); glds16(lds0 + (4 + (b) * 2 + (h)) * (HT * 2) + 8192, _v1, _s + _d); } while (0)
; #define WAIT_V(n) asm volatile("s_waitcnt vmcnt(" #n ")" ::: "memory")
; template <int EPI>
; __device__ __forceinline__ void gemm_phase(const GemmDesc d, u16* shm, unsigned sx, unsigned srank, unsigned snloc) {
;     ...
;     int z, pm, pn; const char *Au, *Bu, *Buh; unsigned voffBh[2];
;     DECODE(t, z, pm, pn); BASES(z, pm, pn, Au, Bu, Buh, voffBh);
;     ...
;     WAIT_V(0);
;     STAGE_B(Bu, Buh, voffBh, 0, 0); STAGE_A(Au, 0, 0); STAGE_B(Bu, Buh, voffBh, 0, 1); STAGE_A(Au, 0, 1);
;     if constexpr (NEED_R) {
;       if (tid < 256) {
;         float rv = rsqrtf(SS_ROW(d.ss + (size_t)R_ROW(pm, pn, tid) * 16) * (1.0f / DM) + EPS);
;         lds_r[tid] = R_ZERO(pn, tid) ? 0.f : rv;
;       }
.LBB0_1435:
	v_readlane_b32 s0, v239, 9
	v_readlane_b32 s1, v239, 20
	s_andn2_b64 vcc, exec, s[2:3]
	s_or_b32 s54, s1, s0
	s_cbranch_vccnz .LBB0_1523
	v_readlane_b32 s0, v240, 2
	v_readlane_b32 s1, v240, 3
	s_waitcnt vmcnt(1)
	v_mov_b32_e32 v0, v182
	v_writelane_b32 v240, s0, 2
	s_nop 0
	v_ashrrev_i32_e32 v1, 6, v0
	v_writelane_b32 v240, s1, 3
	v_readlane_b32 s0, v238, 24
	v_readlane_b32 s1, v238, 25
	s_andn2_b64 vcc, exec, s[0:1]
	v_readfirstlane_b32 s4, v1
	s_cbranch_vccnz .LBB0_1457
	v_readlane_b32 s0, v240, 2
	v_readlane_b32 s1, v240, 3
	s_load_dwordx2 s[2:3], s[0:1], 0xa8
	s_mul_i32 s6, s54, 0x580000
	s_mov_b32 s7, s36
	s_lshl_b64 s[6:7], s[6:7], 1
	v_bfe_i32 v4, v0, 27, 1
	s_waitcnt lgkmcnt(0)
	s_add_u32 s0, s2, s6
	s_addc_u32 s1, s3, s7
	s_add_u32 s55, s0, 0xf000000
	v_lshlrev_b32_e32 v2, 4, v0
	s_addc_u32 s57, s1, 0
	v_lshrrev_b32_e32 v4, 22, v4
	s_add_u32 s10, s2, 0x17d00000
	v_add_u32_e32 v4, v2, v4
	s_addc_u32 s11, s3, 0
	v_and_b32_e32 v4, 0xfffffc00, v4
	s_lshl_b32 s14, s4, 10
	v_sub_u32_e32 v2, v2, v4
	s_cmp_lg_u32 0, -1
	v_lshrrev_b32_e32 v4, 4, v2
	s_cselect_b32 s0, 0, 0
	v_bitop3_b32 v4, v4, v2, 32 bitop3:0x6c
	v_ashrrev_i32_e32 v2, 31, v2
	s_add_i32 s59, s14, s0
	v_readlane_b32 s0, v238, 48
	v_ashrrev_i32_e32 v3, 31, v0
	v_lshrrev_b32_e32 v2, 26, v2
	v_readlane_b32 s1, v238, 49
	s_add_u32 s34, s2, s0
	v_lshrrev_b32_e32 v3, 26, v3
	v_add_u32_e32 v2, v4, v2
	s_addc_u32 s35, s3, s1
	v_readlane_b32 s0, v238, 30
	v_add_u32_e32 v3, v0, v3
	v_ashrrev_i32_e32 v2, 6, v2
	v_readlane_b32 s1, v238, 31
	s_add_u32 s38, s55, s0
	v_ashrrev_i32_e32 v3, 6, v3
	v_mul_i32_i24_e32 v6, 64, v2
	s_addc_u32 s39, s57, s1
	v_lshlrev_b32_e32 v5, 3, v3
	v_lshlrev_b32_e32 v3, 5, v3
	v_sub_u32_e32 v4, v4, v6
	s_add_u32 s4, s38, 0x40000
	v_and_b32_e32 v5, 0x1ffff0, v5
	v_and_b32_e32 v3, 32, v3
	v_ashrrev_i16_sdwa v4, v187, sext(v4) dst_sel:DWORD dst_unused:UNUSED_PAD src0_sel:DWORD src1_sel:BYTE_0
	s_addc_u32 s5, s39, 0
	s_add_i32 s62, s59, 0x10000
	s_add_i32 s63, s59, 0x12000
	v_add_u32_sdwa v3, v3, sext(v4) dst_sel:DWORD dst_unused:UNUSED_PAD src0_sel:DWORD src1_sel:WORD_0
	v_add_lshl_u32 v2, v2, v5, 11
	s_waitcnt vmcnt(0)
	s_add_u32 s6, s38, 0x20000
	v_lshl_add_u32 v130, v3, 1, v2
	s_mov_b32 m0, s62
	s_nop 0
	global_load_lds_dwordx4 v130, s[38:39]
	s_addc_u32 s7, s39, 0
	s_add_i32 s64, s59, 0x2000
	s_mov_b32 m0, s63
	s_nop 0
	global_load_lds_dwordx4 v130, s[6:7]
	s_add_u32 s6, s34, 0x20000
	s_mov_b32 m0, s59
	s_nop 0
	global_load_lds_dwordx4 v130, s[34:35]
	s_addc_u32 s7, s35, 0
	s_add_i32 s65, s59, 0x14000
	s_add_i32 s66, s59, 0x16000
	s_mov_b32 m0, s64
	s_nop 0
	global_load_lds_dwordx4 v130, s[6:7]
	s_add_u32 s6, s38, 0x60000
	s_mov_b32 m0, s65
	s_nop 0
	global_load_lds_dwordx4 v130, s[4:5]
	s_addc_u32 s7, s39, 0
	s_mov_b32 m0, s66
	s_nop 0
	global_load_lds_dwordx4 v130, s[6:7]
	s_add_u32 s6, s34, 0x40000
	s_addc_u32 s7, s35, 0
	s_add_i32 s67, s59, 0x4000
	s_add_i32 s69, s59, 0x6000
	s_mov_b32 m0, s67
	s_nop 0
	global_load_lds_dwordx4 v130, s[6:7]
	s_add_u32 s6, s34, 0x60000
	s_addc_u32 s7, s35, 0
	s_mov_b32 m0, s69
	s_nop 0
	global_load_lds_dwordx4 v130, s[6:7]
	v_cmp_gt_i32_e32 vcc, s58, v0
	s_and_saveexec_b64 s[6:7], vcc
	s_cbranch_execz .LBB0_1439
	v_readlane_b32 s0, v238, 46
	v_readlane_b32 s1, v238, 47
	s_nop 0
	v_add_u32_e32 v2, s0, v0
	v_ashrrev_i32_e32 v3, 31, v2
	v_lshlrev_b64 v[2:3], 6, v[2:3]
	v_lshl_add_u64 v[14:15], s[10:11], 0, v[2:3]
	global_load_dwordx4 v[2:5], v[14:15], off
	global_load_dwordx4 v[6:9], v[14:15], off offset:16
	global_load_dwordx4 v[10:13], v[14:15], off offset:32
	s_nop 0
	global_load_dwordx4 v[14:17], v[14:15], off offset:48
	s_waitcnt vmcnt(3)
	v_mov_b32_e32 v18, v2
	s_waitcnt vmcnt(2)
	v_mov_b32_e32 v19, v6
	v_mov_b32_e32 v6, v3
	v_mov_b32_e32 v2, v4
	v_mov_b32_e32 v3, v8
	v_mov_b32_e32 v8, v5
	s_waitcnt vmcnt(1)
	v_mov_b32_e32 v4, v10
	s_waitcnt vmcnt(0)
	v_mov_b32_e32 v5, v14
	v_mov_b32_e32 v14, v11
	v_pk_add_f32 v[6:7], v[18:19], v[6:7]
	v_mov_b32_e32 v10, v12
	v_mov_b32_e32 v11, v16
	v_pk_add_f32 v[4:5], v[4:5], v[14:15]
	v_pk_add_f32 v[2:3], v[2:3], v[6:7]
	v_mov_b32_e32 v16, v13
	v_pk_add_f32 v[4:5], v[10:11], v[4:5]
	v_pk_add_f32 v[2:3], v[8:9], v[2:3]
	v_pk_add_f32 v[4:5], v[16:17], v[4:5]
	v_add_f32_e32 v2, v2, v3
	v_add_f32_e32 v2, v2, v4
	v_add_f32_e32 v2, v2, v5
	v_fmamk_f32 v2, v2, 0x3a800000, v186
	v_mov_b32_e32 v5, v2
	v_mul_f32_e32 v3, 0x4b800000, v2
	v_cmp_gt_f32_e32 vcc, s31, v2
	s_nop 1
	v_cndmask_b32_e32 v2, v2, v3, vcc
	v_rsq_f32_e32 v2, v2
	v_lshl_add_u32 v3, v0, 2, 0
	v_add_u32_e32 v3, 0x20000, v3
	v_mul_f32_e32 v4, 0x45800000, v2
	v_cndmask_b32_e32 v2, v2, v4, vcc
	v_mul_f32_e32 v2, s86, v2
	ds_write_b32 v3, v2
	ds_write_b32 v3, v5 offset:20480

; template <int EPI>
; __device__ __forceinline__ void gemm_phase(const GemmDesc d, u16* shm, unsigned sx, unsigned srank, unsigned snloc) {
;     ...
;       if constexpr (EPI == E_SWIGLU) {
;         using f32x2 = __attribute__((ext_vector_type(2))) float;
;         const int sw_row = lane2 >> 2, sw_c8 = (lane2 & 3) * 8;
;         u16* sw_base = d.outb + ((size_t)(brow >> 7) * 44 + pn * 2 + (wc2 >> 1)) * 8192
;                      + ((((sw_row * 64 + sw_c8 * 2) ^ ((sw_row >> 3) << 5)) + (wr2 * 8 + (wc2 & 1)) * 1024) >> 1);
; #pragma unroll
;         for (int ai = 0; ai < 2; ++ai)
; #pragma unroll
;           for (int m = 0; m < 4; ++m) {
;             const f32x4 r4 = *(const f32x4*)&lr[ai * 128 + wr2 * 64 + m * 16 + fq2 * 4];
;             const f32x4 rc4 = r4 * (-1.4426950408889634f), rr4 = r4 * r4;
; #pragma unroll
;             for (int n = 0; n < 2; ++n)
; #pragma unroll
;               for (int jp = 0; jp < 4; jp += 2) {
;                 const f32x2 a = {acc[ai][0][m][n][jp], acc[ai][0][m][n][jp + 1]}, b = {acc[ai][1][m][n][jp], acc[ai][1][m][n][jp + 1]};
;                 const f32x2 rc = {rc4[jp], rc4[jp + 1]}, rr = {rr4[jp], rr4[jp + 1]};
;                 const f32x2 tl = a * rc;
;                 f32x2 dd = {__builtin_amdgcn_exp2f(tl[0]), __builtin_amdgcn_exp2f(tl[1])};
;                 dd = dd + 1.0f;
;                 const f32x2 s = {__builtin_amdgcn_rcpf(dd[0]), __builtin_amdgcn_rcpf(dd[1])};
;                 const f32x2 o = (a * b) * (rr * s);
;                 stg[(fq2 * 4 + jp) * 36 + n * 16 + fr2] = o[0];
;                 stg[(fq2 * 4 + jp + 1) * 36 + n * 16 + fr2] = o[1];
;               }
.LBB0_1452:
	s_or_b64 exec, exec, s[4:5]
	v_ashrrev_i32_e32 v141, 6, v139
	s_movk_i32 s0, 0x900
	v_mul_lo_u32 v128, v141, s0
	s_lshl_b32 s0, s70, 8
	s_and_b32 s18, s0, 0x100
	v_add_u32_e32 v156, s83, v128
	s_lshl_b32 s0, s18, 2
	v_lshlrev_b32_e32 v128, 3, v139
	s_add_i32 s0, s0, 0
	v_bfe_u32 v145, v139, 2, 4
	v_and_b32_e32 v146, 24, v128
	s_lshl_b32 s5, s88, 1
	s_add_i32 s0, s0, 0x20000
	s_lshl_b32 s1, s89, 1
	s_mul_i32 s4, s89, 0x58
	s_ashr_i32 s19, s5, 31
	v_lshlrev_b32_e32 v142, 6, v145
	v_lshlrev_b32_e32 v143, 1, v146
	v_and_b32_e32 v147, 32, v139
	s_mul_hi_i32 s1, s1, 44
	s_add_u32 s4, s4, s5
	v_lshrrev_b32_e32 v128, 1, v141
	v_bitop3_b32 v142, v142, v147, v143 bitop3:0x36
	v_lshlrev_b32_e32 v143, 5, v139
	v_lshlrev_b32_e32 v141, 10, v141
	s_addc_u32 s1, s1, s19
	v_and_b32_e32 v143, 0xffffe000, v143
	v_and_b32_e32 v141, 0x400, v141
	v_and_or_b32 v128, v128, 1, s4
	v_mov_b32_e32 v129, s1
	v_or3_b32 v141, v141, v143, v142
	v_lshlrev_b64 v[128:129], 14, v[128:129]
	v_ashrrev_i32_e32 v142, 1, v141
	v_lshrrev_b32_e32 v144, 2, v139
	v_lshl_add_u64 v[128:129], s[12:13], 0, v[128:129]
	v_ashrrev_i32_e32 v143, 31, v142
	v_lshl_add_u64 v[128:129], v[142:143], 1, v[128:129]
	v_and_b32_e32 v143, 12, v144
	v_and_b32_e32 v141, 0xffffff00, v139
	v_lshlrev_b32_e32 v142, 2, v143
	v_add3_u32 v142, s0, v141, v142
	v_lshlrev_b32_e32 v141, 2, v139
	v_and_b32_e32 v157, 60, v141
	v_mul_u32_u24_e32 v141, 0x90, v145
	v_lshlrev_b32_e32 v144, 2, v146
	v_add3_u32 v141, v156, v141, v144
	v_mul_u32_u24_e32 v144, 36, v143
	v_lshlrev_b32_e32 v144, 2, v144
	v_add3_u32 v143, v156, v157, v144
	ds_read_b128 v[150:153], v142
	ds_read_b128 v[158:161], v142 offset:20480
	ds_read_b128 v[154:157], v142 offset:64
	ds_read_b128 v[162:165], v142 offset:20544
	s_mov_b32 s0, 0x1000
	s_mov_b32 s1, 0
	v_lshl_add_u64 v[144:145], v[128:129], 0, s[0:1]
	s_mov_b32 s0, 0xb0000
	v_pk_mul_f32 v[120:121], v[124:125], v[120:121]
	v_pk_mul_f32 v[122:123], v[126:127], v[122:123]
	v_lshl_add_u64 v[146:147], v[128:129], 0, s[0:1]
	s_mov_b32 s0, 0xb1000
	v_pk_mul_f32 v[112:113], v[116:117], v[112:113]
	v_pk_mul_f32 v[114:115], v[118:119], v[114:115]
	v_lshl_add_u64 v[148:149], v[128:129], 0, s[0:1]
	s_waitcnt lgkmcnt(2)
	v_pk_mul_f32 v[124:125], v[124:125], v[150:151]
	v_pk_mul_f32 v[126:127], v[126:127], v[152:153]
	v_pk_mul_f32 v[116:117], v[116:117], v[150:151]
	v_pk_mul_f32 v[118:119], v[118:119], v[152:153]
	v_exp_f32_e32 v124, v124
	v_exp_f32_e32 v125, v125
	v_exp_f32_e32 v126, v126
	v_exp_f32_e32 v127, v127
	v_exp_f32_e32 v116, v116
	v_exp_f32_e32 v117, v117
	v_exp_f32_e32 v118, v118
	v_exp_f32_e32 v119, v119
	v_pk_mul_f32 v[104:105], v[108:109], v[104:105]
	v_pk_mul_f32 v[106:107], v[110:111], v[106:107]
	v_pk_mul_f32 v[96:97], v[100:101], v[96:97]
	v_pk_mul_f32 v[98:99], v[102:103], v[98:99]
	v_pk_fma_f32 v[124:125], v[124:125], v[158:159], v[158:159]
	v_pk_fma_f32 v[126:127], v[126:127], v[160:161], v[160:161]
	v_pk_fma_f32 v[116:117], v[116:117], v[158:159], v[158:159]
	v_pk_fma_f32 v[118:119], v[118:119], v[160:161], v[160:161]
	v_rcp_f32_e32 v124, v124
	v_rcp_f32_e32 v125, v125
	v_rcp_f32_e32 v126, v126
	v_rcp_f32_e32 v127, v127
	v_rcp_f32_e32 v116, v116
	v_rcp_f32_e32 v117, v117
	v_rcp_f32_e32 v118, v118
	v_rcp_f32_e32 v119, v119
	v_pk_mul_f32 v[120:121], v[120:121], v[124:125]
	v_pk_mul_f32 v[122:123], v[122:123], v[126:127]
	v_pk_mul_f32 v[112:113], v[112:113], v[116:117]
	v_pk_mul_f32 v[114:115], v[114:115], v[118:119]
	ds_write2_b32 v143, v120, v112 offset1:16
	ds_write2_b32 v143, v121, v113 offset0:36 offset1:52
	ds_write2_b32 v143, v122, v114 offset0:72 offset1:88
	ds_write2_b32 v143, v123, v115 offset0:108 offset1:124
	ds_read_b128 v[166:169], v141
	ds_read_b128 v[170:173], v141 offset:16
	ds_read_b128 v[150:153], v142 offset:128
	ds_read_b128 v[158:161], v142 offset:20608
	s_waitcnt lgkmcnt(8)
	v_pk_mul_f32 v[108:109], v[108:109], v[154:155]
	v_pk_mul_f32 v[110:111], v[110:111], v[156:157]
	v_pk_mul_f32 v[100:101], v[100:101], v[154:155]
	v_pk_mul_f32 v[102:103], v[102:103], v[156:157]
	v_exp_f32_e32 v108, v108
	v_exp_f32_e32 v109, v109
	v_exp_f32_e32 v110, v110
	v_exp_f32_e32 v111, v111
	v_exp_f32_e32 v100, v100
	v_exp_f32_e32 v101, v101
	v_exp_f32_e32 v102, v102
	v_exp_f32_e32 v103, v103
	v_pk_mul_f32 v[88:89], v[92:93], v[88:89]
	v_pk_mul_f32 v[90:91], v[94:95], v[90:91]
	v_pk_mul_f32 v[80:81], v[84:85], v[80:81]
	v_pk_mul_f32 v[82:83], v[86:87], v[82:83]
	s_waitcnt lgkmcnt(2)
	v_cvt_pk_bf16_f32 v166, v166, v167
	v_cvt_pk_bf16_f32 v167, v168, v169
	v_cvt_pk_bf16_f32 v168, v170, v171
	v_cvt_pk_bf16_f32 v169, v172, v173
	global_store_dwordx4 v[128:129], v[166:169], off nt
	v_pk_fma_f32 v[108:109], v[108:109], v[162:163], v[162:163]
	v_pk_fma_f32 v[110:111], v[110:111], v[164:165], v[164:165]
	v_pk_fma_f32 v[100:101], v[100:101], v[162:163], v[162:163]
	v_pk_fma_f32 v[102:103], v[102:103], v[164:165], v[164:165]
	v_rcp_f32_e32 v108, v108
	v_rcp_f32_e32 v109, v109
	v_rcp_f32_e32 v110, v110
	v_rcp_f32_e32 v111, v111
	v_rcp_f32_e32 v100, v100
	v_rcp_f32_e32 v101, v101
	v_rcp_f32_e32 v102, v102
	v_rcp_f32_e32 v103, v103
	v_pk_mul_f32 v[104:105], v[104:105], v[108:109]
	v_pk_mul_f32 v[106:107], v[106:107], v[110:111]
	v_pk_mul_f32 v[96:97], v[96:97], v[100:101]
	v_pk_mul_f32 v[98:99], v[98:99], v[102:103]
	ds_write2_b32 v143, v104, v96 offset1:16
	ds_write2_b32 v143, v105, v97 offset0:36 offset1:52
	ds_write2_b32 v143, v106, v98 offset0:72 offset1:88
	ds_write2_b32 v143, v107, v99 offset0:108 offset1:124
	ds_read_b128 v[190:193], v141
	ds_read_b128 v[194:197], v141 offset:16
	ds_read_b128 v[154:157], v142 offset:192
	ds_read_b128 v[162:165], v142 offset:20672
	s_waitcnt lgkmcnt(8)
; __device__ __forceinline__ unsigned pack2(float lo, float hi) { unsigned r; asm volatile("v_cvt_pk_bf16_f32 %0, %1, %2" : "=v"(r) : "v"(lo), "v"(hi)); return r; }
; template <int EPI>
; __device__ __forceinline__ void gemm_phase(const GemmDesc d, u16* shm, unsigned sx, unsigned srank, unsigned snloc) {
;     ...
;         for (int ai = 0; ai < 2; ++ai)
; #pragma unroll
;           for (int m = 0; m < 4; ++m) {
;             const f32x4 r4 = *(const f32x4*)&lr[ai * 128 + wr2 * 64 + m * 16 + fq2 * 4];
;             const f32x4 rc4 = r4 * (-1.4426950408889634f), rr4 = r4 * r4;
; #pragma unroll
;             for (int n = 0; n < 2; ++n)
; #pragma unroll
;               for (int jp = 0; jp < 4; jp += 2) {
;                 const f32x2 a = {acc[ai][0][m][n][jp], acc[ai][0][m][n][jp + 1]}, b = {acc[ai][1][m][n][jp], acc[ai][1][m][n][jp + 1]};
;                 const f32x2 rc = {rc4[jp], rc4[jp + 1]}, rr = {rr4[jp], rr4[jp + 1]};
;                 const f32x2 tl = a * rc;
;                 f32x2 dd = {__builtin_amdgcn_exp2f(tl[0]), __builtin_amdgcn_exp2f(tl[1])};
;                 dd = dd + 1.0f;
;                 const f32x2 s = {__builtin_amdgcn_rcpf(dd[0]), __builtin_amdgcn_rcpf(dd[1])};
;                 const f32x2 o = (a * b) * (rr * s);
;                 stg[(fq2 * 4 + jp) * 36 + n * 16 + fr2] = o[0];
;                 stg[(fq2 * 4 + jp + 1) * 36 + n * 16 + fr2] = o[1];
;               }
;             {
;               const f32x4 v0 = *(const f32x4*)&stg[sw_row * 36 + sw_c8], v1 = *(const f32x4*)&stg[sw_row * 36 + sw_c8 + 4];
;               u32x4 w = {pack2(v0[0], v0[1]), pack2(v0[2], v0[3]), pack2(v1[0], v1[1]), pack2(v1[2], v1[3])};
;               __builtin_nontemporal_store(w, (u32x4*)(sw_base + (size_t)ai * (44 * 8192) + m * 1024));
;             }
;           }
	v_pk_mul_f32 v[92:93], v[92:93], v[150:151]
	v_pk_mul_f32 v[94:95], v[94:95], v[152:153]
	v_pk_mul_f32 v[84:85], v[84:85], v[150:151]
	v_pk_mul_f32 v[86:87], v[86:87], v[152:153]
	v_exp_f32_e32 v92, v92
	v_exp_f32_e32 v93, v93
	v_exp_f32_e32 v94, v94
	v_exp_f32_e32 v95, v95
	v_exp_f32_e32 v84, v84
	v_exp_f32_e32 v85, v85
	v_exp_f32_e32 v86, v86
	v_exp_f32_e32 v87, v87
	v_pk_mul_f32 v[72:73], v[76:77], v[72:73]
	v_pk_mul_f32 v[74:75], v[78:79], v[74:75]
	v_pk_mul_f32 v[64:65], v[68:69], v[64:65]
	v_pk_mul_f32 v[66:67], v[70:71], v[66:67]
	s_waitcnt lgkmcnt(2)
	v_cvt_pk_bf16_f32 v190, v190, v191
	v_cvt_pk_bf16_f32 v191, v192, v193
	v_cvt_pk_bf16_f32 v192, v194, v195
	v_cvt_pk_bf16_f32 v193, v196, v197
	global_store_dwordx4 v[128:129], v[190:193], off offset:2048 nt
	v_pk_fma_f32 v[92:93], v[92:93], v[158:159], v[158:159]
	v_pk_fma_f32 v[94:95], v[94:95], v[160:161], v[160:161]
	v_pk_fma_f32 v[84:85], v[84:85], v[158:159], v[158:159]
	v_pk_fma_f32 v[86:87], v[86:87], v[160:161], v[160:161]
	v_rcp_f32_e32 v92, v92
	v_rcp_f32_e32 v93, v93
	v_rcp_f32_e32 v94, v94
	v_rcp_f32_e32 v95, v95
	v_rcp_f32_e32 v84, v84
	v_rcp_f32_e32 v85, v85
	v_rcp_f32_e32 v86, v86
	v_rcp_f32_e32 v87, v87
	v_pk_mul_f32 v[88:89], v[88:89], v[92:93]
	v_pk_mul_f32 v[90:91], v[90:91], v[94:95]
	v_pk_mul_f32 v[80:81], v[80:81], v[84:85]
	v_pk_mul_f32 v[82:83], v[82:83], v[86:87]
	ds_write2_b32 v143, v88, v80 offset1:16
	ds_write2_b32 v143, v89, v81 offset0:36 offset1:52
	ds_write2_b32 v143, v90, v82 offset0:72 offset1:88
	ds_write2_b32 v143, v91, v83 offset0:108 offset1:124
	ds_read_b128 v[166:169], v141
	ds_read_b128 v[170:173], v141 offset:16
	ds_read_b128 v[150:153], v142 offset:512
	ds_read_b128 v[158:161], v142 offset:20992
	s_waitcnt lgkmcnt(8)
	v_pk_mul_f32 v[76:77], v[76:77], v[154:155]
	v_pk_mul_f32 v[78:79], v[78:79], v[156:157]
	v_pk_mul_f32 v[68:69], v[68:69], v[154:155]
	v_pk_mul_f32 v[70:71], v[70:71], v[156:157]
	v_exp_f32_e32 v76, v76
	v_exp_f32_e32 v77, v77
	v_exp_f32_e32 v78, v78
	v_exp_f32_e32 v79, v79
	v_exp_f32_e32 v68, v68
	v_exp_f32_e32 v69, v69
	v_exp_f32_e32 v70, v70
	v_exp_f32_e32 v71, v71
	v_pk_mul_f32 v[56:57], v[60:61], v[56:57]
	v_pk_mul_f32 v[58:59], v[62:63], v[58:59]
	v_pk_mul_f32 v[48:49], v[52:53], v[48:49]
	v_pk_mul_f32 v[50:51], v[54:55], v[50:51]
	s_waitcnt lgkmcnt(2)
	v_cvt_pk_bf16_f32 v166, v166, v167
	v_cvt_pk_bf16_f32 v167, v168, v169
	v_cvt_pk_bf16_f32 v168, v170, v171
	v_cvt_pk_bf16_f32 v169, v172, v173
	global_store_dwordx4 v[144:145], v[166:169], off nt
	v_pk_fma_f32 v[76:77], v[76:77], v[162:163], v[162:163]
	v_pk_fma_f32 v[78:79], v[78:79], v[164:165], v[164:165]
	v_pk_fma_f32 v[68:69], v[68:69], v[162:163], v[162:163]
	v_pk_fma_f32 v[70:71], v[70:71], v[164:165], v[164:165]
	v_rcp_f32_e32 v76, v76
	v_rcp_f32_e32 v77, v77
	v_rcp_f32_e32 v78, v78
	v_rcp_f32_e32 v79, v79
	v_rcp_f32_e32 v68, v68
	v_rcp_f32_e32 v69, v69
	v_rcp_f32_e32 v70, v70
	v_rcp_f32_e32 v71, v71
	v_pk_mul_f32 v[72:73], v[72:73], v[76:77]
	v_pk_mul_f32 v[74:75], v[74:75], v[78:79]
	v_pk_mul_f32 v[64:65], v[64:65], v[68:69]
	v_pk_mul_f32 v[66:67], v[66:67], v[70:71]
	ds_write2_b32 v143, v72, v64 offset1:16
	ds_write2_b32 v143, v73, v65 offset0:36 offset1:52
	ds_write2_b32 v143, v74, v66 offset0:72 offset1:88
	ds_write2_b32 v143, v75, v67 offset0:108 offset1:124
	ds_read_b128 v[190:193], v141
	ds_read_b128 v[194:197], v141 offset:16
	ds_read_b128 v[154:157], v142 offset:576
	ds_read_b128 v[162:165], v142 offset:21056
	s_waitcnt lgkmcnt(8)
	v_pk_mul_f32 v[60:61], v[60:61], v[150:151]
	v_pk_mul_f32 v[62:63], v[62:63], v[152:153]
	v_pk_mul_f32 v[52:53], v[52:53], v[150:151]
	v_pk_mul_f32 v[54:55], v[54:55], v[152:153]
	v_exp_f32_e32 v60, v60
	v_exp_f32_e32 v61, v61
	v_exp_f32_e32 v62, v62
	v_exp_f32_e32 v63, v63
	v_exp_f32_e32 v52, v52
	v_exp_f32_e32 v53, v53
	v_exp_f32_e32 v54, v54
	v_exp_f32_e32 v55, v55
	v_pk_mul_f32 v[40:41], v[44:45], v[40:41]
	v_pk_mul_f32 v[42:43], v[46:47], v[42:43]
	v_pk_mul_f32 v[32:33], v[36:37], v[32:33]
	v_pk_mul_f32 v[34:35], v[38:39], v[34:35]
	s_waitcnt lgkmcnt(2)
	v_cvt_pk_bf16_f32 v190, v190, v191
	v_cvt_pk_bf16_f32 v191, v192, v193
	v_cvt_pk_bf16_f32 v192, v194, v195
	v_cvt_pk_bf16_f32 v193, v196, v197
	global_store_dwordx4 v[144:145], v[190:193], off offset:2048 nt
	v_pk_fma_f32 v[60:61], v[60:61], v[158:159], v[158:159]
	v_pk_fma_f32 v[62:63], v[62:63], v[160:161], v[160:161]
	v_pk_fma_f32 v[52:53], v[52:53], v[158:159], v[158:159]
	v_pk_fma_f32 v[54:55], v[54:55], v[160:161], v[160:161]
	v_rcp_f32_e32 v60, v60
	v_rcp_f32_e32 v61, v61
	v_rcp_f32_e32 v62, v62
	v_rcp_f32_e32 v63, v63
	v_rcp_f32_e32 v52, v52
	v_rcp_f32_e32 v53, v53
	v_rcp_f32_e32 v54, v54
	v_rcp_f32_e32 v55, v55
	v_pk_mul_f32 v[56:57], v[56:57], v[60:61]
	v_pk_mul_f32 v[58:59], v[58:59], v[62:63]
	v_pk_mul_f32 v[48:49], v[48:49], v[52:53]
	v_pk_mul_f32 v[50:51], v[50:51], v[54:55]
	ds_write2_b32 v143, v56, v48 offset1:16
	ds_write2_b32 v143, v57, v49 offset0:36 offset1:52
	ds_write2_b32 v143, v58, v50 offset0:72 offset1:88
	ds_write2_b32 v143, v59, v51 offset0:108 offset1:124
	ds_read_b128 v[166:169], v141
	ds_read_b128 v[170:173], v141 offset:16
	ds_read_b128 v[150:153], v142 offset:640
	ds_read_b128 v[158:161], v142 offset:21120
	s_waitcnt lgkmcnt(8)
; __device__ __forceinline__ unsigned pack2(float lo, float hi) { unsigned r; asm volatile("v_cvt_pk_bf16_f32 %0, %1, %2" : "=v"(r) : "v"(lo), "v"(hi)); return r; }
; template <int EPI>
; __device__ __forceinline__ void gemm_phase(const GemmDesc d, u16* shm, unsigned sx, unsigned srank, unsigned snloc) {
;     ...
;         for (int ai = 0; ai < 2; ++ai)
; #pragma unroll
;           for (int m = 0; m < 4; ++m) {
;             const f32x4 r4 = *(const f32x4*)&lr[ai * 128 + wr2 * 64 + m * 16 + fq2 * 4];
;             const f32x4 rc4 = r4 * (-1.4426950408889634f), rr4 = r4 * r4;
; #pragma unroll
;             for (int n = 0; n < 2; ++n)
; #pragma unroll
;               for (int jp = 0; jp < 4; jp += 2) {
;                 const f32x2 a = {acc[ai][0][m][n][jp], acc[ai][0][m][n][jp + 1]}, b = {acc[ai][1][m][n][jp], acc[ai][1][m][n][jp + 1]};
;                 const f32x2 rc = {rc4[jp], rc4[jp + 1]}, rr = {rr4[jp], rr4[jp + 1]};
;                 const f32x2 tl = a * rc;
;                 f32x2 dd = {__builtin_amdgcn_exp2f(tl[0]), __builtin_amdgcn_exp2f(tl[1])};
;                 dd = dd + 1.0f;
;                 const f32x2 s = {__builtin_amdgcn_rcpf(dd[0]), __builtin_amdgcn_rcpf(dd[1])};
;                 const f32x2 o = (a * b) * (rr * s);
;                 stg[(fq2 * 4 + jp) * 36 + n * 16 + fr2] = o[0];
;                 stg[(fq2 * 4 + jp + 1) * 36 + n * 16 + fr2] = o[1];
;               }
;             {
;               const f32x4 v0 = *(const f32x4*)&stg[sw_row * 36 + sw_c8], v1 = *(const f32x4*)&stg[sw_row * 36 + sw_c8 + 4];
;               u32x4 w = {pack2(v0[0], v0[1]), pack2(v0[2], v0[3]), pack2(v1[0], v1[1]), pack2(v1[2], v1[3])};
;               __builtin_nontemporal_store(w, (u32x4*)(sw_base + (size_t)ai * (44 * 8192) + m * 1024));
;             }
;           }
;     ...
;       if constexpr (NEED_R) {
;         if (has_next && t2 < 256) lds_r[((it + 1) & 1) * 256 + t2] = R_ZERO(pnn, t2) ? 0.f : rsqrtf(ssn * (1.0f / DM) + EPS);
;       }
	v_pk_mul_f32 v[44:45], v[44:45], v[154:155]
	v_pk_mul_f32 v[46:47], v[46:47], v[156:157]
	v_pk_mul_f32 v[36:37], v[36:37], v[154:155]
	v_pk_mul_f32 v[38:39], v[38:39], v[156:157]
	v_exp_f32_e32 v44, v44
	v_exp_f32_e32 v45, v45
	v_exp_f32_e32 v46, v46
	v_exp_f32_e32 v47, v47
	v_exp_f32_e32 v36, v36
	v_exp_f32_e32 v37, v37
	v_exp_f32_e32 v38, v38
	v_exp_f32_e32 v39, v39
	v_pk_mul_f32 v[24:25], v[28:29], v[24:25]
	v_pk_mul_f32 v[26:27], v[30:31], v[26:27]
	v_pk_mul_f32 v[16:17], v[20:21], v[16:17]
	v_pk_mul_f32 v[18:19], v[22:23], v[18:19]
	s_waitcnt lgkmcnt(2)
	v_cvt_pk_bf16_f32 v166, v166, v167
	v_cvt_pk_bf16_f32 v167, v168, v169
	v_cvt_pk_bf16_f32 v168, v170, v171
	v_cvt_pk_bf16_f32 v169, v172, v173
	global_store_dwordx4 v[146:147], v[166:169], off nt
	v_pk_fma_f32 v[44:45], v[44:45], v[162:163], v[162:163]
	v_pk_fma_f32 v[46:47], v[46:47], v[164:165], v[164:165]
	v_pk_fma_f32 v[36:37], v[36:37], v[162:163], v[162:163]
	v_pk_fma_f32 v[38:39], v[38:39], v[164:165], v[164:165]
	v_rcp_f32_e32 v44, v44
	v_rcp_f32_e32 v45, v45
	v_rcp_f32_e32 v46, v46
	v_rcp_f32_e32 v47, v47
	v_rcp_f32_e32 v36, v36
	v_rcp_f32_e32 v37, v37
	v_rcp_f32_e32 v38, v38
	v_rcp_f32_e32 v39, v39
	v_pk_mul_f32 v[40:41], v[40:41], v[44:45]
	v_pk_mul_f32 v[42:43], v[42:43], v[46:47]
	v_pk_mul_f32 v[32:33], v[32:33], v[36:37]
	v_pk_mul_f32 v[34:35], v[34:35], v[38:39]
	ds_write2_b32 v143, v40, v32 offset1:16
	ds_write2_b32 v143, v41, v33 offset0:36 offset1:52
	ds_write2_b32 v143, v42, v34 offset0:72 offset1:88
	ds_write2_b32 v143, v43, v35 offset0:108 offset1:124
	ds_read_b128 v[190:193], v141
	ds_read_b128 v[194:197], v141 offset:16
	ds_read_b128 v[154:157], v142 offset:704
	ds_read_b128 v[162:165], v142 offset:21184
	s_waitcnt lgkmcnt(8)
	v_pk_mul_f32 v[28:29], v[28:29], v[150:151]
	v_pk_mul_f32 v[30:31], v[30:31], v[152:153]
	v_pk_mul_f32 v[20:21], v[20:21], v[150:151]
	v_pk_mul_f32 v[22:23], v[22:23], v[152:153]
	v_exp_f32_e32 v28, v28
	v_exp_f32_e32 v29, v29
	v_exp_f32_e32 v30, v30
	v_exp_f32_e32 v31, v31
	v_exp_f32_e32 v20, v20
	v_exp_f32_e32 v21, v21
	v_exp_f32_e32 v22, v22
	v_exp_f32_e32 v23, v23
	v_pk_mul_f32 v[8:9], v[12:13], v[8:9]
	v_pk_mul_f32 v[10:11], v[14:15], v[10:11]
	v_pk_mul_f32 v[0:1], v[4:5], v[0:1]
	v_pk_mul_f32 v[2:3], v[6:7], v[2:3]
	s_waitcnt lgkmcnt(2)
	v_cvt_pk_bf16_f32 v190, v190, v191
	v_cvt_pk_bf16_f32 v191, v192, v193
	v_cvt_pk_bf16_f32 v192, v194, v195
	v_cvt_pk_bf16_f32 v193, v196, v197
	global_store_dwordx4 v[146:147], v[190:193], off offset:2048 nt
	v_pk_fma_f32 v[28:29], v[28:29], v[158:159], v[158:159]
	v_pk_fma_f32 v[30:31], v[30:31], v[160:161], v[160:161]
	v_pk_fma_f32 v[20:21], v[20:21], v[158:159], v[158:159]
	v_pk_fma_f32 v[22:23], v[22:23], v[160:161], v[160:161]
	v_rcp_f32_e32 v28, v28
	v_rcp_f32_e32 v29, v29
	v_rcp_f32_e32 v30, v30
	v_rcp_f32_e32 v31, v31
	v_rcp_f32_e32 v20, v20
	v_rcp_f32_e32 v21, v21
	v_rcp_f32_e32 v22, v22
	v_rcp_f32_e32 v23, v23
	v_pk_mul_f32 v[24:25], v[24:25], v[28:29]
	v_pk_mul_f32 v[26:27], v[26:27], v[30:31]
	v_pk_mul_f32 v[16:17], v[16:17], v[20:21]
	v_pk_mul_f32 v[18:19], v[18:19], v[22:23]
	ds_write2_b32 v143, v24, v16 offset1:16
	ds_write2_b32 v143, v25, v17 offset0:36 offset1:52
	ds_write2_b32 v143, v26, v18 offset0:72 offset1:88
	ds_write2_b32 v143, v27, v19 offset0:108 offset1:124
	ds_read_b128 v[166:169], v141
	ds_read_b128 v[170:173], v141 offset:16
	s_waitcnt lgkmcnt(6)
	v_pk_mul_f32 v[12:13], v[12:13], v[154:155]
	v_pk_mul_f32 v[14:15], v[14:15], v[156:157]
	v_pk_mul_f32 v[4:5], v[4:5], v[154:155]
	v_pk_mul_f32 v[6:7], v[6:7], v[156:157]
	v_exp_f32_e32 v12, v12
	v_exp_f32_e32 v13, v13
	v_exp_f32_e32 v14, v14
	v_exp_f32_e32 v15, v15
	v_exp_f32_e32 v4, v4
	v_exp_f32_e32 v5, v5
	v_exp_f32_e32 v6, v6
	v_exp_f32_e32 v7, v7
	s_waitcnt lgkmcnt(0)
	v_cvt_pk_bf16_f32 v166, v166, v167
	v_cvt_pk_bf16_f32 v167, v168, v169
	v_cvt_pk_bf16_f32 v168, v170, v171
	v_cvt_pk_bf16_f32 v169, v172, v173
	global_store_dwordx4 v[148:149], v[166:169], off nt
	v_pk_fma_f32 v[12:13], v[12:13], v[162:163], v[162:163]
	v_pk_fma_f32 v[14:15], v[14:15], v[164:165], v[164:165]
	v_pk_fma_f32 v[4:5], v[4:5], v[162:163], v[162:163]
	v_pk_fma_f32 v[6:7], v[6:7], v[164:165], v[164:165]
	v_rcp_f32_e32 v12, v12
	v_rcp_f32_e32 v13, v13
	v_rcp_f32_e32 v14, v14
	v_rcp_f32_e32 v15, v15
	v_rcp_f32_e32 v4, v4
	v_rcp_f32_e32 v5, v5
	v_rcp_f32_e32 v6, v6
	v_rcp_f32_e32 v7, v7
	v_pk_mul_f32 v[8:9], v[8:9], v[12:13]
	v_pk_mul_f32 v[10:11], v[10:11], v[14:15]
	v_pk_mul_f32 v[0:1], v[0:1], v[4:5]
	v_pk_mul_f32 v[2:3], v[2:3], v[6:7]
	ds_write2_b32 v143, v8, v0 offset1:16
	ds_write2_b32 v143, v9, v1 offset0:36 offset1:52
	ds_write2_b32 v143, v10, v2 offset0:72 offset1:88
	ds_write2_b32 v143, v11, v3 offset0:108 offset1:124
	ds_read_b128 v[190:193], v141
	ds_read_b128 v[194:197], v141 offset:16
	s_waitcnt lgkmcnt(0)
	v_cvt_pk_bf16_f32 v190, v190, v191
	v_cvt_pk_bf16_f32 v191, v192, v193
	v_cvt_pk_bf16_f32 v192, v194, v195
	v_cvt_pk_bf16_f32 v193, v196, v197
	global_store_dwordx4 v[148:149], v[190:193], off offset:2048 nt
	s_and_saveexec_b64 s[4:5], s[34:35]
	s_cbranch_execz .LBB0_1454
	v_cmp_gt_f32_e32 vcc, s31, v140
	v_mul_f32_e32 v0, 0x4b800000, v140
	s_xor_b32 s0, s18, 0x100
	v_cndmask_b32_e32 v0, v140, v0, vcc
	v_rsq_f32_e32 v0, v0
	s_lshl_b32 s0, s0, 2
	s_add_i32 s0, s0, 0
	v_mul_f32_e32 v1, 0x45800000, v0
	v_cndmask_b32_e32 v0, v0, v1, vcc
	v_lshl_add_u32 v1, v139, 2, s0
	v_add_u32_e32 v1, 0x20000, v1
	v_mul_f32_e32 v0, s86, v0
	ds_write_b32 v1, v0
	ds_write_b32 v1, v140 offset:20480

; #define DECODE(t_, z_, pm_, pn_) do { if constexpr (EPI == E_CHDFT) { z_ = (t_) >> 5; pm_ = ((t_) >> 4) & 1; pn_ = (int)sx * 16 + ((t_) & 15); break; } \
;     int wgid = (int)sx * tq + (t_); \
;     z_ = wgid / per; int id = wgid % per; \
;     int nig = WGM * nN, gid = id / nig, fm = gid * WGM, gsz = min(nM - fm, WGM); \
;     pm_ = fm + ((id % nig) % gsz); pn_ = (id % nig) / gsz; } while (0)
; #define STAGE_A(Ak_, b, h) do { const char* _s = (Ak_) + (h) * sHA; \
;     glds16(lds0 + ((b) * 2 + (h)) * (HT * 2), voffA, _s); glds16(lds0 + ((b) * 2 + (h)) * (HT * 2) + 8192, voffA, _s + s2A); } while (0)
; #define WAIT_V(n) asm volatile("s_waitcnt vmcnt(" #n ")" ::: "memory")
; #define WAIT_L(n) asm volatile("s_waitcnt lgkmcnt(" #n ")" ::: "memory")
; template <int EPI>
; __device__ __forceinline__ void gemm_phase(const GemmDesc d, u16* shm, unsigned sx, unsigned srank, unsigned snloc) {
;     ...
;       f32x4 acc[2][2][4][2] = {};
;       bf16x8 At[4][2], B0[2][2], B1[2][2];
;       const int tn = t + (int)snloc;
;       const bool has_next = tn < tq;
;       int zn = z, pmn = pm, pnn = pn; const char *Aun = Au, *Bun = Bu, *Bunh = Buh; unsigned voffBhn[2] = {voffBh[0], voffBh[1]};
;       if (has_next) { DECODE(tn, zn, pmn, pnn); BASES(zn, pmn, pnn, Aun, Bun, Bunh, voffBhn); }
; #pragma unroll 1
;       for (int kt = 0; kt < nt; kt += 2) {
;         const bool lastk = (kt + 2 >= nt);
;         const char* A1 = Au + (long)(kt + 1) * sKA;
;         const char* A2 = lastk ? Aun : Au + (long)(kt + 2) * sKA;
;         const char* B2 = lastk ? Bun : Bu + (long)(kt + 2) * sKB;
;         const char* B2h = lastk ? Bunh : Buh + (long)(kt + 2) * sKB;
;         const unsigned vh[2] = {lastk ? voffBhn[0] : voffBh[0], lastk ? voffBhn[1] : voffBh[1]};
;         const char* A3 = A2 + sKA; const char* B3 = B2 + sKB; const char* B3h = B2h + sKB;
;         LDB(B0, 0, 0); SCHED; LDA(At, 0, 0); STAGE_A(A1, 1, 1);
;         WAIT_L(8); BAR; MMA(0, 0, At, B0); BAR; SCHED;
;         LDB(B1, 0, 1); STAGE_B(B2, B2h, vh, 0, 0);
;         BAR; MMA(0, 1, At, B1); BAR;
;         LDA(At, 0, 1); STAGE_A(A2, 0, 0);
;         BAR; MMA(1, 0, At, B0); BAR; SCHED;
;         STAGE_B(B2, B2h, vh, 0, 1);
;         WAIT_V(6); BAR; MMA(1, 1, At, B1); BAR;
;         LDB(B0, 1, 0); SCHED; LDA(At, 1, 0); STAGE_A(A2, 0, 1);
;         WAIT_L(8); BAR; MMA(0, 0, At, B0); BAR; SCHED;
.LBB0_1534:
	s_add_u32 s10, s10, 0xb4000
	s_addc_u32 s11, s11, 0
	s_add_u32 s89, s18, 0x100
	s_addc_u32 s90, s19, 0
	s_add_u32 s91, s4, 0x100
	s_addc_u32 s92, s5, 0
	s_mov_b32 s20, 0
	s_waitcnt lgkmcnt(0)
.LBB0_1535:
	s_add_i32 s21, s20, 2
	s_add_u32 s0, s10, 0xfff54000
	s_addc_u32 s1, s11, -1
	s_cmp_lt_u32 s20, 42
	s_cselect_b32 s46, s0, s12
	s_cselect_b32 s0, s89, s14
	s_cselect_b32 s47, s1, s13
	s_cselect_b32 s1, s90, s15
	s_cselect_b32 s43, s92, s17
	s_cselect_b32 s42, s91, s16
	s_add_u32 s34, s0, 0x80
	s_addc_u32 s35, s1, 0
	s_add_u32 s22, s46, 0x4000
	s_addc_u32 s23, s47, 0
	s_add_u32 s94, s10, 0x2000
	s_addc_u32 s95, s11, 0
	s_add_u32 s96, s0, 0x58000
	s_addc_u32 s97, s1, 0
	s_add_u32 s48, s46, 0x2000
	s_addc_u32 s49, s47, 0
	s_add_u32 s44, s42, 0x58000
	s_addc_u32 s45, s43, 0
	s_add_u32 s40, s46, 0xb0000
	s_addc_u32 s41, s47, 0
	s_add_u32 s28, s46, 0xb2000
	s_addc_u32 s29, s47, 0
	s_add_u32 s38, s0, 0x58080
	s_addc_u32 s39, s1, 0
	s_add_u32 s30, s46, 0x6000
	s_addc_u32 s31, s47, 0
	s_add_u32 s18, s42, 0x80
	s_addc_u32 s19, s43, 0
	s_add_u32 s4, s42, 0x58080
	s_addc_u32 s5, s43, 0
	s_add_u32 s26, s10, 0x8000
	s_addc_u32 s27, s11, 0
	s_add_u32 s89, s89, 0x100
	s_addc_u32 s90, s90, 0
	s_add_u32 s91, s91, 0x100
	s_addc_u32 s92, s92, 0
	ds_read_b128 v[128:131], v136
	ds_read_b128 v[144:147], v136 offset:1024
	ds_read_b128 v[148:151], v136 offset:2048
	ds_read_b128 v[152:155], v136 offset:3072
	ds_read_b128 v[156:159], v137
	ds_read_b128 v[160:163], v137 offset:1024
	ds_read_b128 v[164:167], v138
	ds_read_b128 v[168:171], v138 offset:1024
	ds_read_b128 v[172:175], v139
	ds_read_b128 v[178:181], v139 offset:1024
	ds_read_b128 v[190:193], v140
	ds_read_b128 v[194:197], v140 offset:1024
	s_mov_b32 m0, s78
	s_nop 0
	global_load_lds_dwordx4 v134, s[10:11]
	s_mov_b32 m0, s79
	s_nop 0
	global_load_lds_dwordx4 v134, s[94:95]
	s_waitcnt lgkmcnt(8)
	s_barrier
	s_setprio 1
	s_waitcnt lgkmcnt(7)
	v_mfma_f32_16x16x32_bf16 v[124:127], v[156:159], v[128:131], 0
	v_mfma_f32_16x16x32_bf16 v[120:123], v[156:159], v[148:151], 0
	s_waitcnt lgkmcnt(5)
	v_mfma_f32_16x16x32_bf16 v[108:111], v[164:167], v[128:131], 0
	v_mfma_f32_16x16x32_bf16 v[104:107], v[164:167], v[148:151], 0
	s_waitcnt lgkmcnt(3)
	v_mfma_f32_16x16x32_bf16 v[92:95], v[172:175], v[128:131], 0
	v_mfma_f32_16x16x32_bf16 v[88:91], v[172:175], v[148:151], 0
	s_waitcnt lgkmcnt(1)
	v_mfma_f32_16x16x32_bf16 v[76:79], v[190:193], v[128:131], 0
	v_mfma_f32_16x16x32_bf16 v[72:75], v[190:193], v[148:151], 0
	v_mfma_f32_16x16x32_bf16 v[124:127], v[160:163], v[144:147], v[124:127]
	v_mfma_f32_16x16x32_bf16 v[120:123], v[160:163], v[152:155], v[120:123]
	v_mfma_f32_16x16x32_bf16 v[108:111], v[168:171], v[144:147], v[108:111]
	v_mfma_f32_16x16x32_bf16 v[104:107], v[168:171], v[152:155], v[104:107]
	v_mfma_f32_16x16x32_bf16 v[92:95], v[178:181], v[144:147], v[92:95]
	v_mfma_f32_16x16x32_bf16 v[88:91], v[178:181], v[152:155], v[88:91]
	s_waitcnt lgkmcnt(0)
	v_mfma_f32_16x16x32_bf16 v[76:79], v[194:197], v[144:147], v[76:79]
	v_mfma_f32_16x16x32_bf16 v[72:75], v[194:197], v[152:155], v[72:75]
	s_setprio 0
	s_barrier
	ds_read_b128 v[198:201], v141
	ds_read_b128 v[202:205], v141 offset:1024
	ds_read_b128 v[206:209], v141 offset:2048
	ds_read_b128 v[210:213], v141 offset:3072
	s_mov_b32 m0, s57
	s_nop 0
	global_load_lds_dwordx4 v135, s[0:1]
	s_mov_b32 m0, s59
	s_nop 0
	global_load_lds_dwordx4 v135, s[96:97]
	s_barrier
	s_setprio 1
	s_waitcnt lgkmcnt(3)
	v_mfma_f32_16x16x32_bf16 v[116:119], v[156:159], v[198:201], 0
	s_waitcnt lgkmcnt(1)
	v_mfma_f32_16x16x32_bf16 v[112:115], v[156:159], v[206:209], 0
	v_mfma_f32_16x16x32_bf16 v[100:103], v[164:167], v[198:201], 0
	v_mfma_f32_16x16x32_bf16 v[96:99], v[164:167], v[206:209], 0
	v_mfma_f32_16x16x32_bf16 v[84:87], v[172:175], v[198:201], 0
	v_mfma_f32_16x16x32_bf16 v[80:83], v[172:175], v[206:209], 0
	v_mfma_f32_16x16x32_bf16 v[68:71], v[190:193], v[198:201], 0
	v_mfma_f32_16x16x32_bf16 v[64:67], v[190:193], v[206:209], 0
	v_mfma_f32_16x16x32_bf16 v[116:119], v[160:163], v[202:205], v[116:119]
	s_waitcnt lgkmcnt(0)
	v_mfma_f32_16x16x32_bf16 v[112:115], v[160:163], v[210:213], v[112:115]
	v_mfma_f32_16x16x32_bf16 v[100:103], v[168:171], v[202:205], v[100:103]
	v_mfma_f32_16x16x32_bf16 v[96:99], v[168:171], v[210:213], v[96:99]
	v_mfma_f32_16x16x32_bf16 v[84:87], v[178:181], v[202:205], v[84:87]
	v_mfma_f32_16x16x32_bf16 v[80:83], v[178:181], v[210:213], v[80:83]
	v_mfma_f32_16x16x32_bf16 v[68:71], v[194:197], v[202:205], v[68:71]
	v_mfma_f32_16x16x32_bf16 v[64:67], v[194:197], v[210:213], v[64:67]
	s_setprio 0
	s_barrier
	ds_read_b128 v[156:159], v137 offset:16384
	ds_read_b128 v[160:163], v137 offset:17408
	ds_read_b128 v[164:167], v138 offset:16384
	ds_read_b128 v[168:171], v138 offset:17408
	ds_read_b128 v[172:175], v139 offset:16384
	ds_read_b128 v[178:181], v139 offset:17408
	ds_read_b128 v[190:193], v140 offset:16384
	ds_read_b128 v[194:197], v140 offset:17408
	s_mov_b32 m0, s55
	s_nop 0
	global_load_lds_dwordx4 v134, s[46:47]
	s_mov_b32 m0, s62
	s_nop 0
	global_load_lds_dwordx4 v134, s[48:49]
	s_barrier
; #define STAGE_A(Ak_, b, h) do { const char* _s = (Ak_) + (h) * sHA; \
;     glds16(lds0 + ((b) * 2 + (h)) * (HT * 2), voffA, _s); glds16(lds0 + ((b) * 2 + (h)) * (HT * 2) + 8192, voffA, _s + s2A); } while (0)
; #define STAGE_B(Bk_, Bkh_, vh_, b, h) do { const char* _s = (h) ? (Bkh_) : (Bk_); const unsigned _v0 = (h) ? (vh_)[0] : voffB, _v1 = (h) ? (vh_)[1] : voffB; const long _d = (h) ? s2Bh : s2B; \
;     glds16(lds0 + (4 + (b) * 2 + (h)) * (HT * 2), _v0, _s); glds16(lds0 + (4 + (b) * 2 + (h)) * (HT * 2) + 8192, _v1, _s + _d); } while (0)
; #define LDA(dst, b, h) for (int m = 0; m < 4; ++m) for (int k = 0; k < 2; ++k) \
;     dst[m][k] = *reinterpret_cast<const bf16x8*>((char*)SA(b, h) + lds_byte(wr * 64 + m * 16 + fr, k * 32 + fq * 8))
; #define LDB(dst, b, h) for (int n = 0; n < 2; ++n) for (int k = 0; k < 2; ++k) \
;     dst[n][k] = *reinterpret_cast<const bf16x8*>((char*)SB(b, h) + lds_byte(wc * 32 + n * 16 + fr, k * 32 + fq * 8))
; #define MMA(ai, bj, At_, Bt_) do { __builtin_amdgcn_s_setprio(1); \
;     for (int m = 0; m < 4; ++m) for (int n = 0; n < 2; ++n) for (int k = 0; k < 2; ++k) \
;       acc[ai][bj][m][n] = __builtin_amdgcn_mfma_f32_16x16x32_bf16(At_[m][k], Bt_[n][k], acc[ai][bj][m][n], 0, 0, 0); \
;     __builtin_amdgcn_s_setprio(0); } while (0)
; #define WAIT_V(n) asm volatile("s_waitcnt vmcnt(" #n ")" ::: "memory")
; #define WAIT_L(n) asm volatile("s_waitcnt lgkmcnt(" #n ")" ::: "memory")
; #define BAR __builtin_amdgcn_s_barrier()
; #define SCHED __builtin_amdgcn_sched_barrier(0)
; template <int EPI>
; __device__ __forceinline__ void gemm_phase(const GemmDesc d, u16* shm, unsigned sx, unsigned srank, unsigned snloc) {
;     ...
;         BAR; MMA(1, 0, At, B0); BAR; SCHED;
;         STAGE_B(B2, B2h, vh, 0, 1);
;         WAIT_V(6); BAR; MMA(1, 1, At, B1); BAR;
;         LDB(B0, 1, 0); SCHED; LDA(At, 1, 0); STAGE_A(A2, 0, 1);
;         WAIT_L(8); BAR; MMA(0, 0, At, B0); BAR; SCHED;
;         LDB(B1, 1, 1); STAGE_B(B3, B3h, vh, 1, 0);
;         BAR; MMA(0, 1, At, B1); BAR;
	s_setprio 1
	s_waitcnt lgkmcnt(7)
	v_mfma_f32_16x16x32_bf16 v[60:63], v[156:159], v[128:131], 0
	v_mfma_f32_16x16x32_bf16 v[56:59], v[156:159], v[148:151], 0
	s_waitcnt lgkmcnt(5)
	v_mfma_f32_16x16x32_bf16 v[44:47], v[164:167], v[128:131], 0
	v_mfma_f32_16x16x32_bf16 v[40:43], v[164:167], v[148:151], 0
	s_waitcnt lgkmcnt(3)
	v_mfma_f32_16x16x32_bf16 v[28:31], v[172:175], v[128:131], 0
	v_mfma_f32_16x16x32_bf16 v[24:27], v[172:175], v[148:151], 0
	s_waitcnt lgkmcnt(1)
	v_mfma_f32_16x16x32_bf16 v[12:15], v[190:193], v[128:131], 0
	v_mfma_f32_16x16x32_bf16 v[8:11], v[190:193], v[148:151], 0
	v_mfma_f32_16x16x32_bf16 v[60:63], v[160:163], v[144:147], v[60:63]
	v_mfma_f32_16x16x32_bf16 v[56:59], v[160:163], v[152:155], v[56:59]
	v_mfma_f32_16x16x32_bf16 v[44:47], v[168:171], v[144:147], v[44:47]
	v_mfma_f32_16x16x32_bf16 v[40:43], v[168:171], v[152:155], v[40:43]
	v_mfma_f32_16x16x32_bf16 v[28:31], v[178:181], v[144:147], v[28:31]
	v_mfma_f32_16x16x32_bf16 v[24:27], v[178:181], v[152:155], v[24:27]
	s_waitcnt lgkmcnt(0)
	v_mfma_f32_16x16x32_bf16 v[12:15], v[194:197], v[144:147], v[12:15]
	v_mfma_f32_16x16x32_bf16 v[8:11], v[194:197], v[152:155], v[8:11]
	s_setprio 0
	s_barrier
	s_mov_b32 m0, s63
	s_nop 0
	global_load_lds_dwordx4 v135, s[42:43]
	s_mov_b32 m0, s64
	s_nop 0
	global_load_lds_dwordx4 v135, s[44:45]
	s_waitcnt vmcnt(6)
	s_barrier
	s_setprio 1
	v_mfma_f32_16x16x32_bf16 v[52:55], v[156:159], v[198:201], 0
	v_mfma_f32_16x16x32_bf16 v[48:51], v[156:159], v[206:209], 0
	v_mfma_f32_16x16x32_bf16 v[36:39], v[164:167], v[198:201], 0
	v_mfma_f32_16x16x32_bf16 v[32:35], v[164:167], v[206:209], 0
	v_mfma_f32_16x16x32_bf16 v[20:23], v[172:175], v[198:201], 0
	v_mfma_f32_16x16x32_bf16 v[16:19], v[172:175], v[206:209], 0
	v_mfma_f32_16x16x32_bf16 v[4:7], v[190:193], v[198:201], 0
	v_mfma_f32_16x16x32_bf16 v[0:3], v[190:193], v[206:209], 0
	v_mfma_f32_16x16x32_bf16 v[52:55], v[160:163], v[202:205], v[52:55]
	v_mfma_f32_16x16x32_bf16 v[48:51], v[160:163], v[210:213], v[48:51]
	v_mfma_f32_16x16x32_bf16 v[36:39], v[168:171], v[202:205], v[36:39]
	v_mfma_f32_16x16x32_bf16 v[32:35], v[168:171], v[210:213], v[32:35]
	v_mfma_f32_16x16x32_bf16 v[20:23], v[178:181], v[202:205], v[20:23]
	v_mfma_f32_16x16x32_bf16 v[16:19], v[178:181], v[210:213], v[16:19]
	v_mfma_f32_16x16x32_bf16 v[4:7], v[194:197], v[202:205], v[4:7]
	v_mfma_f32_16x16x32_bf16 v[0:3], v[194:197], v[210:213], v[0:3]
	s_setprio 0
	s_barrier
	ds_read_b128 v[128:131], v142
	ds_read_b128 v[144:147], v142 offset:1024
	ds_read_b128 v[148:151], v142 offset:2048
	ds_read_b128 v[152:155], v142 offset:3072
	ds_read_b128 v[156:159], v137 offset:32768
	ds_read_b128 v[160:163], v137 offset:33792
	ds_read_b128 v[164:167], v138 offset:32768
	ds_read_b128 v[168:171], v138 offset:33792
	ds_read_b128 v[172:175], v139 offset:32768
	ds_read_b128 v[178:181], v139 offset:33792
	ds_read_b128 v[190:193], v140 offset:32768
	ds_read_b128 v[194:197], v140 offset:33792
	s_mov_b32 m0, s65
	s_nop 0
	global_load_lds_dwordx4 v134, s[40:41]
	s_mov_b32 m0, s66
	s_nop 0
	global_load_lds_dwordx4 v134, s[28:29]
	s_waitcnt lgkmcnt(8)
	s_barrier
	s_setprio 1
	s_waitcnt lgkmcnt(7)
	v_mfma_f32_16x16x32_bf16 v[124:127], v[156:159], v[128:131], v[124:127]
	v_mfma_f32_16x16x32_bf16 v[120:123], v[156:159], v[148:151], v[120:123]
	s_waitcnt lgkmcnt(5)
	v_mfma_f32_16x16x32_bf16 v[108:111], v[164:167], v[128:131], v[108:111]
	v_mfma_f32_16x16x32_bf16 v[104:107], v[164:167], v[148:151], v[104:107]
	s_waitcnt lgkmcnt(3)
	v_mfma_f32_16x16x32_bf16 v[92:95], v[172:175], v[128:131], v[92:95]
	v_mfma_f32_16x16x32_bf16 v[88:91], v[172:175], v[148:151], v[88:91]
	s_waitcnt lgkmcnt(1)
	v_mfma_f32_16x16x32_bf16 v[76:79], v[190:193], v[128:131], v[76:79]
	v_mfma_f32_16x16x32_bf16 v[72:75], v[190:193], v[148:151], v[72:75]
	v_mfma_f32_16x16x32_bf16 v[124:127], v[160:163], v[144:147], v[124:127]
	v_mfma_f32_16x16x32_bf16 v[120:123], v[160:163], v[152:155], v[120:123]
	v_mfma_f32_16x16x32_bf16 v[108:111], v[168:171], v[144:147], v[108:111]
	v_mfma_f32_16x16x32_bf16 v[104:107], v[168:171], v[152:155], v[104:107]
	v_mfma_f32_16x16x32_bf16 v[92:95], v[178:181], v[144:147], v[92:95]
	v_mfma_f32_16x16x32_bf16 v[88:91], v[178:181], v[152:155], v[88:91]
	s_waitcnt lgkmcnt(0)
	v_mfma_f32_16x16x32_bf16 v[76:79], v[194:197], v[144:147], v[76:79]
	v_mfma_f32_16x16x32_bf16 v[72:75], v[194:197], v[152:155], v[72:75]
	s_setprio 0
	s_barrier
	ds_read_b128 v[198:201], v143
	ds_read_b128 v[202:205], v143 offset:1024
	ds_read_b128 v[206:209], v143 offset:2048
	ds_read_b128 v[210:213], v143 offset:3072
	s_mov_b32 m0, s70
	s_nop 0
	global_load_lds_dwordx4 v135, s[34:35]
	s_mov_b32 m0, s71
	s_nop 0
	global_load_lds_dwordx4 v135, s[38:39]
	s_barrier
	s_setprio 1
	s_waitcnt lgkmcnt(3)
	v_mfma_f32_16x16x32_bf16 v[116:119], v[156:159], v[198:201], v[116:119]
	s_waitcnt lgkmcnt(1)
	v_mfma_f32_16x16x32_bf16 v[112:115], v[156:159], v[206:209], v[112:115]
	v_mfma_f32_16x16x32_bf16 v[100:103], v[164:167], v[198:201], v[100:103]
	v_mfma_f32_16x16x32_bf16 v[96:99], v[164:167], v[206:209], v[96:99]
	v_mfma_f32_16x16x32_bf16 v[84:87], v[172:175], v[198:201], v[84:87]
	v_mfma_f32_16x16x32_bf16 v[80:83], v[172:175], v[206:209], v[80:83]
	v_mfma_f32_16x16x32_bf16 v[68:71], v[190:193], v[198:201], v[68:71]
	v_mfma_f32_16x16x32_bf16 v[64:67], v[190:193], v[206:209], v[64:67]
	v_mfma_f32_16x16x32_bf16 v[116:119], v[160:163], v[202:205], v[116:119]
	s_waitcnt lgkmcnt(0)
	v_mfma_f32_16x16x32_bf16 v[112:115], v[160:163], v[210:213], v[112:115]
	v_mfma_f32_16x16x32_bf16 v[100:103], v[168:171], v[202:205], v[100:103]
	v_mfma_f32_16x16x32_bf16 v[96:99], v[168:171], v[210:213], v[96:99]
	v_mfma_f32_16x16x32_bf16 v[84:87], v[178:181], v[202:205], v[84:87]
	v_mfma_f32_16x16x32_bf16 v[80:83], v[178:181], v[210:213], v[80:83]
	v_mfma_f32_16x16x32_bf16 v[68:71], v[194:197], v[202:205], v[68:71]
	v_mfma_f32_16x16x32_bf16 v[64:67], v[194:197], v[210:213], v[64:67]
	s_setprio 0
	s_barrier
; #define STAGE_A(Ak_, b, h) do { const char* _s = (Ak_) + (h) * sHA; \
;     glds16(lds0 + ((b) * 2 + (h)) * (HT * 2), voffA, _s); glds16(lds0 + ((b) * 2 + (h)) * (HT * 2) + 8192, voffA, _s + s2A); } while (0)
; #define STAGE_B(Bk_, Bkh_, vh_, b, h) do { const char* _s = (h) ? (Bkh_) : (Bk_); const unsigned _v0 = (h) ? (vh_)[0] : voffB, _v1 = (h) ? (vh_)[1] : voffB; const long _d = (h) ? s2Bh : s2B; \
;     glds16(lds0 + (4 + (b) * 2 + (h)) * (HT * 2), _v0, _s); glds16(lds0 + (4 + (b) * 2 + (h)) * (HT * 2) + 8192, _v1, _s + _d); } while (0)
; #define LDA(dst, b, h) for (int m = 0; m < 4; ++m) for (int k = 0; k < 2; ++k) \
;     dst[m][k] = *reinterpret_cast<const bf16x8*>((char*)SA(b, h) + lds_byte(wr * 64 + m * 16 + fr, k * 32 + fq * 8))
; #define LDB(dst, b, h) for (int n = 0; n < 2; ++n) for (int k = 0; k < 2; ++k) \
;     dst[n][k] = *reinterpret_cast<const bf16x8*>((char*)SB(b, h) + lds_byte(wc * 32 + n * 16 + fr, k * 32 + fq * 8))
; template <int EPI>
; __device__ __forceinline__ void gemm_phase(const GemmDesc d, u16* shm, unsigned sx, unsigned srank, unsigned snloc) {
;     ...
;         const bool lastk = (kt + 2 >= nt);
;         const char* A1 = Au + (long)(kt + 1) * sKA;
;         const char* A2 = lastk ? Aun : Au + (long)(kt + 2) * sKA;
;         const char* B2 = lastk ? Bun : Bu + (long)(kt + 2) * sKB;
;         const char* B2h = lastk ? Bunh : Buh + (long)(kt + 2) * sKB;
;         const unsigned vh[2] = {lastk ? voffBhn[0] : voffBh[0], lastk ? voffBhn[1] : voffBh[1]};
;         const char* A3 = A2 + sKA; const char* B3 = B2 + sKB; const char* B3h = B2h + sKB;
;         LDB(B0, 0, 0); SCHED; LDA(At, 0, 0); STAGE_A(A1, 1, 1);
;         WAIT_L(8); BAR; MMA(0, 0, At, B0); BAR; SCHED;
;         LDB(B1, 0, 1); STAGE_B(B2, B2h, vh, 0, 0);
;         BAR; MMA(0, 1, At, B1); BAR;
;         LDA(At, 0, 1); STAGE_A(A2, 0, 0);
;         BAR; MMA(1, 0, At, B0); BAR; SCHED;
;         STAGE_B(B2, B2h, vh, 0, 1);
;         WAIT_V(6); BAR; MMA(1, 1, At, B1); BAR;
;         LDB(B0, 1, 0); SCHED; LDA(At, 1, 0); STAGE_A(A2, 0, 1);
;         WAIT_L(8); BAR; MMA(0, 0, At, B0); BAR; SCHED;
;         LDB(B1, 1, 1); STAGE_B(B3, B3h, vh, 1, 0);
;         BAR; MMA(0, 1, At, B1); BAR;
;         LDA(At, 1, 1); STAGE_A(A3, 1, 0);
;         BAR; MMA(1, 0, At, B0); BAR; SCHED;
;         STAGE_B(B3, B3h, vh, 1, 1);
;         WAIT_V(6); BAR; MMA(1, 1, At, B1); BAR;
	ds_read_b128 v[156:159], v137 offset:49152
	ds_read_b128 v[160:163], v137 offset:50176
	ds_read_b128 v[164:167], v138 offset:49152
	ds_read_b128 v[168:171], v138 offset:50176
	ds_read_b128 v[172:175], v139 offset:49152
	ds_read_b128 v[178:181], v139 offset:50176
	ds_read_b128 v[190:193], v140 offset:49152
	ds_read_b128 v[194:197], v140 offset:50176
	s_mov_b32 m0, s72
	s_nop 0
	global_load_lds_dwordx4 v134, s[22:23]
	s_mov_b32 m0, s73
	s_nop 0
	global_load_lds_dwordx4 v134, s[30:31]
	s_barrier
	s_setprio 1
	s_waitcnt lgkmcnt(7)
	v_mfma_f32_16x16x32_bf16 v[60:63], v[156:159], v[128:131], v[60:63]
	v_mfma_f32_16x16x32_bf16 v[56:59], v[156:159], v[148:151], v[56:59]
	s_waitcnt lgkmcnt(5)
	v_mfma_f32_16x16x32_bf16 v[44:47], v[164:167], v[128:131], v[44:47]
	v_mfma_f32_16x16x32_bf16 v[40:43], v[164:167], v[148:151], v[40:43]
	s_waitcnt lgkmcnt(3)
	v_mfma_f32_16x16x32_bf16 v[28:31], v[172:175], v[128:131], v[28:31]
	v_mfma_f32_16x16x32_bf16 v[24:27], v[172:175], v[148:151], v[24:27]
	s_waitcnt lgkmcnt(1)
	v_mfma_f32_16x16x32_bf16 v[12:15], v[190:193], v[128:131], v[12:15]
	v_mfma_f32_16x16x32_bf16 v[8:11], v[190:193], v[148:151], v[8:11]
	v_mfma_f32_16x16x32_bf16 v[60:63], v[160:163], v[144:147], v[60:63]
	v_mfma_f32_16x16x32_bf16 v[56:59], v[160:163], v[152:155], v[56:59]
	v_mfma_f32_16x16x32_bf16 v[44:47], v[168:171], v[144:147], v[44:47]
	v_mfma_f32_16x16x32_bf16 v[40:43], v[168:171], v[152:155], v[40:43]
	v_mfma_f32_16x16x32_bf16 v[28:31], v[178:181], v[144:147], v[28:31]
	v_mfma_f32_16x16x32_bf16 v[24:27], v[178:181], v[152:155], v[24:27]
	s_waitcnt lgkmcnt(0)
	v_mfma_f32_16x16x32_bf16 v[12:15], v[194:197], v[144:147], v[12:15]
	v_mfma_f32_16x16x32_bf16 v[8:11], v[194:197], v[152:155], v[8:11]
	s_setprio 0
	s_barrier
	s_mov_b32 m0, s76
	s_nop 0
	global_load_lds_dwordx4 v135, s[18:19]
	s_mov_b32 m0, s77
	s_nop 0
	global_load_lds_dwordx4 v135, s[4:5]
	s_mov_b64 s[10:11], s[26:27]
	s_mov_b32 s20, s21
	s_add_i32 s21, s20, 2
	s_add_u32 s0, s10, 0xfff54000
	s_addc_u32 s1, s11, -1
	s_cmp_lt_u32 s20, 42
	s_cselect_b32 s46, s0, s12
	s_cselect_b32 s0, s89, s14
	s_cselect_b32 s47, s1, s13
	s_cselect_b32 s1, s90, s15
	s_cselect_b32 s43, s92, s17
	s_cselect_b32 s42, s91, s16
	s_add_u32 s34, s0, 0x80
	s_addc_u32 s35, s1, 0
	s_add_u32 s22, s46, 0x4000
	s_addc_u32 s23, s47, 0
	s_add_u32 s94, s10, 0x2000
	s_addc_u32 s95, s11, 0
	s_add_u32 s96, s0, 0x58000
	s_addc_u32 s97, s1, 0
	s_add_u32 s48, s46, 0x2000
	s_addc_u32 s49, s47, 0
	s_add_u32 s44, s42, 0x58000
	s_addc_u32 s45, s43, 0
	s_add_u32 s40, s46, 0xb0000
	s_addc_u32 s41, s47, 0
	s_add_u32 s28, s46, 0xb2000
	s_addc_u32 s29, s47, 0
	s_add_u32 s38, s0, 0x58080
	s_addc_u32 s39, s1, 0
	s_add_u32 s30, s46, 0x6000
	s_addc_u32 s31, s47, 0
	s_add_u32 s18, s42, 0x80
	s_addc_u32 s19, s43, 0
	s_add_u32 s4, s42, 0x58080
	s_addc_u32 s5, s43, 0
	s_add_u32 s26, s10, 0x8000
	s_addc_u32 s27, s11, 0
	s_add_u32 s89, s89, 0x100
	s_addc_u32 s90, s90, 0
	s_add_u32 s91, s91, 0x100
	s_addc_u32 s92, s92, 0
	s_waitcnt vmcnt(6)
	s_barrier
	s_setprio 1
	v_mfma_f32_16x16x32_bf16 v[52:55], v[156:159], v[198:201], v[52:55]
	v_mfma_f32_16x16x32_bf16 v[48:51], v[156:159], v[206:209], v[48:51]
	v_mfma_f32_16x16x32_bf16 v[36:39], v[164:167], v[198:201], v[36:39]
	v_mfma_f32_16x16x32_bf16 v[32:35], v[164:167], v[206:209], v[32:35]
	v_mfma_f32_16x16x32_bf16 v[20:23], v[172:175], v[198:201], v[20:23]
	v_mfma_f32_16x16x32_bf16 v[16:19], v[172:175], v[206:209], v[16:19]
	v_mfma_f32_16x16x32_bf16 v[4:7], v[190:193], v[198:201], v[4:7]
	v_mfma_f32_16x16x32_bf16 v[0:3], v[190:193], v[206:209], v[0:3]
	v_mfma_f32_16x16x32_bf16 v[52:55], v[160:163], v[202:205], v[52:55]
	v_mfma_f32_16x16x32_bf16 v[48:51], v[160:163], v[210:213], v[48:51]
	v_mfma_f32_16x16x32_bf16 v[36:39], v[168:171], v[202:205], v[36:39]
	v_mfma_f32_16x16x32_bf16 v[32:35], v[168:171], v[210:213], v[32:35]
	v_mfma_f32_16x16x32_bf16 v[20:23], v[178:181], v[202:205], v[20:23]
	v_mfma_f32_16x16x32_bf16 v[16:19], v[178:181], v[210:213], v[16:19]
	v_mfma_f32_16x16x32_bf16 v[4:7], v[194:197], v[202:205], v[4:7]
	v_mfma_f32_16x16x32_bf16 v[0:3], v[194:197], v[210:213], v[0:3]
	s_setprio 0
	s_barrier
.Lk_down:
	ds_read_b128 v[128:131], v136
	ds_read_b128 v[144:147], v136 offset:1024
	ds_read_b128 v[148:151], v136 offset:2048
	ds_read_b128 v[152:155], v136 offset:3072
	ds_read_b128 v[156:159], v137
	ds_read_b128 v[160:163], v137 offset:1024
	ds_read_b128 v[164:167], v138
	ds_read_b128 v[168:171], v138 offset:1024
	ds_read_b128 v[172:175], v139
	ds_read_b128 v[178:181], v139 offset:1024
	ds_read_b128 v[190:193], v140
	ds_read_b128 v[194:197], v140 offset:1024
	s_mov_b32 m0, s78
	s_nop 0
	global_load_lds_dwordx4 v134, s[10:11]
	s_mov_b32 m0, s79
	s_nop 0
	global_load_lds_dwordx4 v134, s[94:95]
	s_waitcnt lgkmcnt(8)
	s_barrier
	s_setprio 1
	s_waitcnt lgkmcnt(7)
	v_mfma_f32_16x16x32_bf16 v[124:127], v[156:159], v[128:131], v[124:127]
	v_mfma_f32_16x16x32_bf16 v[120:123], v[156:159], v[148:151], v[120:123]
	s_waitcnt lgkmcnt(5)
	v_mfma_f32_16x16x32_bf16 v[108:111], v[164:167], v[128:131], v[108:111]
	v_mfma_f32_16x16x32_bf16 v[104:107], v[164:167], v[148:151], v[104:107]
	s_waitcnt lgkmcnt(3)
	v_mfma_f32_16x16x32_bf16 v[92:95], v[172:175], v[128:131], v[92:95]
	v_mfma_f32_16x16x32_bf16 v[88:91], v[172:175], v[148:151], v[88:91]
	s_waitcnt lgkmcnt(1)
	v_mfma_f32_16x16x32_bf16 v[76:79], v[190:193], v[128:131], v[76:79]
	v_mfma_f32_16x16x32_bf16 v[72:75], v[190:193], v[148:151], v[72:75]
	v_mfma_f32_16x16x32_bf16 v[124:127], v[160:163], v[144:147], v[124:127]
	v_mfma_f32_16x16x32_bf16 v[120:123], v[160:163], v[152:155], v[120:123]
	v_mfma_f32_16x16x32_bf16 v[108:111], v[168:171], v[144:147], v[108:111]
	v_mfma_f32_16x16x32_bf16 v[104:107], v[168:171], v[152:155], v[104:107]
	v_mfma_f32_16x16x32_bf16 v[92:95], v[178:181], v[144:147], v[92:95]
	v_mfma_f32_16x16x32_bf16 v[88:91], v[178:181], v[152:155], v[88:91]
	s_waitcnt lgkmcnt(0)
	v_mfma_f32_16x16x32_bf16 v[76:79], v[194:197], v[144:147], v[76:79]
	v_mfma_f32_16x16x32_bf16 v[72:75], v[194:197], v[152:155], v[72:75]
	s_setprio 0
	s_barrier
; #define STAGE_A(Ak_, b, h) do { const char* _s = (Ak_) + (h) * sHA; \
;     glds16(lds0 + ((b) * 2 + (h)) * (HT * 2), voffA, _s); glds16(lds0 + ((b) * 2 + (h)) * (HT * 2) + 8192, voffA, _s + s2A); } while (0)
; #define STAGE_B(Bk_, Bkh_, vh_, b, h) do { const char* _s = (h) ? (Bkh_) : (Bk_); const unsigned _v0 = (h) ? (vh_)[0] : voffB, _v1 = (h) ? (vh_)[1] : voffB; const long _d = (h) ? s2Bh : s2B; \
;     glds16(lds0 + (4 + (b) * 2 + (h)) * (HT * 2), _v0, _s); glds16(lds0 + (4 + (b) * 2 + (h)) * (HT * 2) + 8192, _v1, _s + _d); } while (0)
; #define LDA(dst, b, h) for (int m = 0; m < 4; ++m) for (int k = 0; k < 2; ++k) \
;     dst[m][k] = *reinterpret_cast<const bf16x8*>((char*)SA(b, h) + lds_byte(wr * 64 + m * 16 + fr, k * 32 + fq * 8))
; #define LDB(dst, b, h) for (int n = 0; n < 2; ++n) for (int k = 0; k < 2; ++k) \
;     dst[n][k] = *reinterpret_cast<const bf16x8*>((char*)SB(b, h) + lds_byte(wc * 32 + n * 16 + fr, k * 32 + fq * 8))
; #define MMA(ai, bj, At_, Bt_) do { __builtin_amdgcn_s_setprio(1); \
;     for (int m = 0; m < 4; ++m) for (int n = 0; n < 2; ++n) for (int k = 0; k < 2; ++k) \
;       acc[ai][bj][m][n] = __builtin_amdgcn_mfma_f32_16x16x32_bf16(At_[m][k], Bt_[n][k], acc[ai][bj][m][n], 0, 0, 0); \
;     __builtin_amdgcn_s_setprio(0); } while (0)
; #define WAIT_V(n) asm volatile("s_waitcnt vmcnt(" #n ")" ::: "memory")
; #define WAIT_L(n) asm volatile("s_waitcnt lgkmcnt(" #n ")" ::: "memory")
; #define BAR __builtin_amdgcn_s_barrier()
; #define SCHED __builtin_amdgcn_sched_barrier(0)
; template <int EPI>
; __device__ __forceinline__ void gemm_phase(const GemmDesc d, u16* shm, unsigned sx, unsigned srank, unsigned snloc) {
;     ...
;         LDB(B1, 0, 1); STAGE_B(B2, B2h, vh, 0, 0);
;         BAR; MMA(0, 1, At, B1); BAR;
;         LDA(At, 0, 1); STAGE_A(A2, 0, 0);
;         BAR; MMA(1, 0, At, B0); BAR; SCHED;
;         STAGE_B(B2, B2h, vh, 0, 1);
;         WAIT_V(6); BAR; MMA(1, 1, At, B1); BAR;
;         LDB(B0, 1, 0); SCHED; LDA(At, 1, 0); STAGE_A(A2, 0, 1);
;         WAIT_L(8); BAR; MMA(0, 0, At, B0); BAR; SCHED;
	ds_read_b128 v[198:201], v141
	ds_read_b128 v[202:205], v141 offset:1024
	ds_read_b128 v[206:209], v141 offset:2048
	ds_read_b128 v[210:213], v141 offset:3072
	s_mov_b32 m0, s57
	s_nop 0
	global_load_lds_dwordx4 v135, s[0:1]
	s_mov_b32 m0, s59
	s_nop 0
	global_load_lds_dwordx4 v135, s[96:97]
	s_barrier
	s_setprio 1
	s_waitcnt lgkmcnt(3)
	v_mfma_f32_16x16x32_bf16 v[116:119], v[156:159], v[198:201], v[116:119]
	s_waitcnt lgkmcnt(1)
	v_mfma_f32_16x16x32_bf16 v[112:115], v[156:159], v[206:209], v[112:115]
	v_mfma_f32_16x16x32_bf16 v[100:103], v[164:167], v[198:201], v[100:103]
	v_mfma_f32_16x16x32_bf16 v[96:99], v[164:167], v[206:209], v[96:99]
	v_mfma_f32_16x16x32_bf16 v[84:87], v[172:175], v[198:201], v[84:87]
	v_mfma_f32_16x16x32_bf16 v[80:83], v[172:175], v[206:209], v[80:83]
	v_mfma_f32_16x16x32_bf16 v[68:71], v[190:193], v[198:201], v[68:71]
	v_mfma_f32_16x16x32_bf16 v[64:67], v[190:193], v[206:209], v[64:67]
	v_mfma_f32_16x16x32_bf16 v[116:119], v[160:163], v[202:205], v[116:119]
	s_waitcnt lgkmcnt(0)
	v_mfma_f32_16x16x32_bf16 v[112:115], v[160:163], v[210:213], v[112:115]
	v_mfma_f32_16x16x32_bf16 v[100:103], v[168:171], v[202:205], v[100:103]
	v_mfma_f32_16x16x32_bf16 v[96:99], v[168:171], v[210:213], v[96:99]
	v_mfma_f32_16x16x32_bf16 v[84:87], v[178:181], v[202:205], v[84:87]
	v_mfma_f32_16x16x32_bf16 v[80:83], v[178:181], v[210:213], v[80:83]
	v_mfma_f32_16x16x32_bf16 v[68:71], v[194:197], v[202:205], v[68:71]
	v_mfma_f32_16x16x32_bf16 v[64:67], v[194:197], v[210:213], v[64:67]
	s_setprio 0
	s_barrier
	ds_read_b128 v[156:159], v137 offset:16384
	ds_read_b128 v[160:163], v137 offset:17408
	ds_read_b128 v[164:167], v138 offset:16384
	ds_read_b128 v[168:171], v138 offset:17408
	ds_read_b128 v[172:175], v139 offset:16384
	ds_read_b128 v[178:181], v139 offset:17408
	ds_read_b128 v[190:193], v140 offset:16384
	ds_read_b128 v[194:197], v140 offset:17408
	s_mov_b32 m0, s55
	s_nop 0
	global_load_lds_dwordx4 v134, s[46:47]
	s_mov_b32 m0, s62
	s_nop 0
	global_load_lds_dwordx4 v134, s[48:49]
	s_barrier
	s_setprio 1
	s_waitcnt lgkmcnt(7)
	v_mfma_f32_16x16x32_bf16 v[60:63], v[156:159], v[128:131], v[60:63]
	v_mfma_f32_16x16x32_bf16 v[56:59], v[156:159], v[148:151], v[56:59]
	s_waitcnt lgkmcnt(5)
	v_mfma_f32_16x16x32_bf16 v[44:47], v[164:167], v[128:131], v[44:47]
	v_mfma_f32_16x16x32_bf16 v[40:43], v[164:167], v[148:151], v[40:43]
	s_waitcnt lgkmcnt(3)
	v_mfma_f32_16x16x32_bf16 v[28:31], v[172:175], v[128:131], v[28:31]
	v_mfma_f32_16x16x32_bf16 v[24:27], v[172:175], v[148:151], v[24:27]
	s_waitcnt lgkmcnt(1)
	v_mfma_f32_16x16x32_bf16 v[12:15], v[190:193], v[128:131], v[12:15]
	v_mfma_f32_16x16x32_bf16 v[8:11], v[190:193], v[148:151], v[8:11]
	v_mfma_f32_16x16x32_bf16 v[60:63], v[160:163], v[144:147], v[60:63]
	v_mfma_f32_16x16x32_bf16 v[56:59], v[160:163], v[152:155], v[56:59]
	v_mfma_f32_16x16x32_bf16 v[44:47], v[168:171], v[144:147], v[44:47]
	v_mfma_f32_16x16x32_bf16 v[40:43], v[168:171], v[152:155], v[40:43]
	v_mfma_f32_16x16x32_bf16 v[28:31], v[178:181], v[144:147], v[28:31]
	v_mfma_f32_16x16x32_bf16 v[24:27], v[178:181], v[152:155], v[24:27]
	s_waitcnt lgkmcnt(0)
	v_mfma_f32_16x16x32_bf16 v[12:15], v[194:197], v[144:147], v[12:15]
	v_mfma_f32_16x16x32_bf16 v[8:11], v[194:197], v[152:155], v[8:11]
	s_setprio 0
	s_barrier
	s_mov_b32 m0, s63
	s_nop 0
	global_load_lds_dwordx4 v135, s[42:43]
	s_mov_b32 m0, s64
	s_nop 0
	global_load_lds_dwordx4 v135, s[44:45]
	s_waitcnt vmcnt(6)
	s_barrier
	s_setprio 1
	v_mfma_f32_16x16x32_bf16 v[52:55], v[156:159], v[198:201], v[52:55]
	v_mfma_f32_16x16x32_bf16 v[48:51], v[156:159], v[206:209], v[48:51]
	v_mfma_f32_16x16x32_bf16 v[36:39], v[164:167], v[198:201], v[36:39]
	v_mfma_f32_16x16x32_bf16 v[32:35], v[164:167], v[206:209], v[32:35]
	v_mfma_f32_16x16x32_bf16 v[20:23], v[172:175], v[198:201], v[20:23]
	v_mfma_f32_16x16x32_bf16 v[16:19], v[172:175], v[206:209], v[16:19]
	v_mfma_f32_16x16x32_bf16 v[4:7], v[190:193], v[198:201], v[4:7]
	v_mfma_f32_16x16x32_bf16 v[0:3], v[190:193], v[206:209], v[0:3]
	v_mfma_f32_16x16x32_bf16 v[52:55], v[160:163], v[202:205], v[52:55]
	v_mfma_f32_16x16x32_bf16 v[48:51], v[160:163], v[210:213], v[48:51]
	v_mfma_f32_16x16x32_bf16 v[36:39], v[168:171], v[202:205], v[36:39]
	v_mfma_f32_16x16x32_bf16 v[32:35], v[168:171], v[210:213], v[32:35]
	v_mfma_f32_16x16x32_bf16 v[20:23], v[178:181], v[202:205], v[20:23]
	v_mfma_f32_16x16x32_bf16 v[16:19], v[178:181], v[210:213], v[16:19]
	v_mfma_f32_16x16x32_bf16 v[4:7], v[194:197], v[202:205], v[4:7]
	v_mfma_f32_16x16x32_bf16 v[0:3], v[194:197], v[210:213], v[0:3]
	s_setprio 0
	s_barrier
	ds_read_b128 v[128:131], v142
	ds_read_b128 v[144:147], v142 offset:1024
	ds_read_b128 v[148:151], v142 offset:2048
	ds_read_b128 v[152:155], v142 offset:3072
	ds_read_b128 v[156:159], v137 offset:32768
	ds_read_b128 v[160:163], v137 offset:33792
	ds_read_b128 v[164:167], v138 offset:32768
	ds_read_b128 v[168:171], v138 offset:33792
	ds_read_b128 v[172:175], v139 offset:32768
	ds_read_b128 v[178:181], v139 offset:33792
	ds_read_b128 v[190:193], v140 offset:32768
	ds_read_b128 v[194:197], v140 offset:33792
	s_mov_b32 m0, s65
	s_nop 0
	global_load_lds_dwordx4 v134, s[40:41]
	s_mov_b32 m0, s66
	s_nop 0
	global_load_lds_dwordx4 v134, s[28:29]
	s_waitcnt lgkmcnt(8)
	s_barrier
; #define STAGE_A(Ak_, b, h) do { const char* _s = (Ak_) + (h) * sHA; \
;     glds16(lds0 + ((b) * 2 + (h)) * (HT * 2), voffA, _s); glds16(lds0 + ((b) * 2 + (h)) * (HT * 2) + 8192, voffA, _s + s2A); } while (0)
; #define STAGE_B(Bk_, Bkh_, vh_, b, h) do { const char* _s = (h) ? (Bkh_) : (Bk_); const unsigned _v0 = (h) ? (vh_)[0] : voffB, _v1 = (h) ? (vh_)[1] : voffB; const long _d = (h) ? s2Bh : s2B; \
;     glds16(lds0 + (4 + (b) * 2 + (h)) * (HT * 2), _v0, _s); glds16(lds0 + (4 + (b) * 2 + (h)) * (HT * 2) + 8192, _v1, _s + _d); } while (0)
; #define LDA(dst, b, h) for (int m = 0; m < 4; ++m) for (int k = 0; k < 2; ++k) \
;     dst[m][k] = *reinterpret_cast<const bf16x8*>((char*)SA(b, h) + lds_byte(wr * 64 + m * 16 + fr, k * 32 + fq * 8))
; #define LDB(dst, b, h) for (int n = 0; n < 2; ++n) for (int k = 0; k < 2; ++k) \
;     dst[n][k] = *reinterpret_cast<const bf16x8*>((char*)SB(b, h) + lds_byte(wc * 32 + n * 16 + fr, k * 32 + fq * 8))
; #define MMA(ai, bj, At_, Bt_) do { __builtin_amdgcn_s_setprio(1); \
;     for (int m = 0; m < 4; ++m) for (int n = 0; n < 2; ++n) for (int k = 0; k < 2; ++k) \
;       acc[ai][bj][m][n] = __builtin_amdgcn_mfma_f32_16x16x32_bf16(At_[m][k], Bt_[n][k], acc[ai][bj][m][n], 0, 0, 0); \
;     __builtin_amdgcn_s_setprio(0); } while (0)
; #define WAIT_L(n) asm volatile("s_waitcnt lgkmcnt(" #n ")" ::: "memory")
; #define BAR __builtin_amdgcn_s_barrier()
; #define SCHED __builtin_amdgcn_sched_barrier(0)
; template <int EPI>
; __device__ __forceinline__ void gemm_phase(const GemmDesc d, u16* shm, unsigned sx, unsigned srank, unsigned snloc) {
;     ...
;         WAIT_L(8); BAR; MMA(0, 0, At, B0); BAR; SCHED;
;         LDB(B1, 1, 1); STAGE_B(B3, B3h, vh, 1, 0);
;         BAR; MMA(0, 1, At, B1); BAR;
;         LDA(At, 1, 1); STAGE_A(A3, 1, 0);
	s_setprio 1
	s_waitcnt lgkmcnt(7)
	v_mfma_f32_16x16x32_bf16 v[124:127], v[156:159], v[128:131], v[124:127]
	v_mfma_f32_16x16x32_bf16 v[120:123], v[156:159], v[148:151], v[120:123]
	s_waitcnt lgkmcnt(5)
	v_mfma_f32_16x16x32_bf16 v[108:111], v[164:167], v[128:131], v[108:111]
	v_mfma_f32_16x16x32_bf16 v[104:107], v[164:167], v[148:151], v[104:107]
	s_waitcnt lgkmcnt(3)
	v_mfma_f32_16x16x32_bf16 v[92:95], v[172:175], v[128:131], v[92:95]
	v_mfma_f32_16x16x32_bf16 v[88:91], v[172:175], v[148:151], v[88:91]
	s_waitcnt lgkmcnt(1)
	v_mfma_f32_16x16x32_bf16 v[76:79], v[190:193], v[128:131], v[76:79]
	v_mfma_f32_16x16x32_bf16 v[72:75], v[190:193], v[148:151], v[72:75]
	v_mfma_f32_16x16x32_bf16 v[124:127], v[160:163], v[144:147], v[124:127]
	v_mfma_f32_16x16x32_bf16 v[120:123], v[160:163], v[152:155], v[120:123]
	v_mfma_f32_16x16x32_bf16 v[108:111], v[168:171], v[144:147], v[108:111]
	v_mfma_f32_16x16x32_bf16 v[104:107], v[168:171], v[152:155], v[104:107]
	v_mfma_f32_16x16x32_bf16 v[92:95], v[178:181], v[144:147], v[92:95]
	v_mfma_f32_16x16x32_bf16 v[88:91], v[178:181], v[152:155], v[88:91]
	s_waitcnt lgkmcnt(0)
	v_mfma_f32_16x16x32_bf16 v[76:79], v[194:197], v[144:147], v[76:79]
	v_mfma_f32_16x16x32_bf16 v[72:75], v[194:197], v[152:155], v[72:75]
	s_setprio 0
	s_barrier
	ds_read_b128 v[198:201], v143
	ds_read_b128 v[202:205], v143 offset:1024
	ds_read_b128 v[206:209], v143 offset:2048
	ds_read_b128 v[210:213], v143 offset:3072
	s_mov_b32 m0, s70
	s_nop 0
	global_load_lds_dwordx4 v135, s[34:35]
	s_mov_b32 m0, s71
	s_nop 0
	global_load_lds_dwordx4 v135, s[38:39]
	s_barrier
	s_setprio 1
	s_waitcnt lgkmcnt(3)
	v_mfma_f32_16x16x32_bf16 v[116:119], v[156:159], v[198:201], v[116:119]
	s_waitcnt lgkmcnt(1)
	v_mfma_f32_16x16x32_bf16 v[112:115], v[156:159], v[206:209], v[112:115]
	v_mfma_f32_16x16x32_bf16 v[100:103], v[164:167], v[198:201], v[100:103]
	v_mfma_f32_16x16x32_bf16 v[96:99], v[164:167], v[206:209], v[96:99]
	v_mfma_f32_16x16x32_bf16 v[84:87], v[172:175], v[198:201], v[84:87]
	v_mfma_f32_16x16x32_bf16 v[80:83], v[172:175], v[206:209], v[80:83]
	v_mfma_f32_16x16x32_bf16 v[68:71], v[190:193], v[198:201], v[68:71]
	v_mfma_f32_16x16x32_bf16 v[64:67], v[190:193], v[206:209], v[64:67]
	v_mfma_f32_16x16x32_bf16 v[116:119], v[160:163], v[202:205], v[116:119]
	s_waitcnt lgkmcnt(0)
	v_mfma_f32_16x16x32_bf16 v[112:115], v[160:163], v[210:213], v[112:115]
	v_mfma_f32_16x16x32_bf16 v[100:103], v[168:171], v[202:205], v[100:103]
	v_mfma_f32_16x16x32_bf16 v[96:99], v[168:171], v[210:213], v[96:99]
	v_mfma_f32_16x16x32_bf16 v[84:87], v[178:181], v[202:205], v[84:87]
	v_mfma_f32_16x16x32_bf16 v[80:83], v[178:181], v[210:213], v[80:83]
	v_mfma_f32_16x16x32_bf16 v[68:71], v[194:197], v[202:205], v[68:71]
	v_mfma_f32_16x16x32_bf16 v[64:67], v[194:197], v[210:213], v[64:67]
	s_setprio 0
	s_barrier
	ds_read_b128 v[156:159], v137 offset:49152
	ds_read_b128 v[160:163], v137 offset:50176
	ds_read_b128 v[164:167], v138 offset:49152
	ds_read_b128 v[168:171], v138 offset:50176
	ds_read_b128 v[172:175], v139 offset:49152
	ds_read_b128 v[178:181], v139 offset:50176
	ds_read_b128 v[190:193], v140 offset:49152
	ds_read_b128 v[194:197], v140 offset:50176
	s_mov_b32 m0, s72
	s_nop 0
	global_load_lds_dwordx4 v134, s[22:23]
	s_mov_b32 m0, s73
	s_nop 0
	global_load_lds_dwordx4 v134, s[30:31]
	s_barrier
; #define STAGE_A(Ak_, b, h) do { const char* _s = (Ak_) + (h) * sHA; \
;     glds16(lds0 + ((b) * 2 + (h)) * (HT * 2), voffA, _s); glds16(lds0 + ((b) * 2 + (h)) * (HT * 2) + 8192, voffA, _s + s2A); } while (0)
; #define STAGE_B(Bk_, Bkh_, vh_, b, h) do { const char* _s = (h) ? (Bkh_) : (Bk_); const unsigned _v0 = (h) ? (vh_)[0] : voffB, _v1 = (h) ? (vh_)[1] : voffB; const long _d = (h) ? s2Bh : s2B; \
;     glds16(lds0 + (4 + (b) * 2 + (h)) * (HT * 2), _v0, _s); glds16(lds0 + (4 + (b) * 2 + (h)) * (HT * 2) + 8192, _v1, _s + _d); } while (0)
; #define LDA(dst, b, h) for (int m = 0; m < 4; ++m) for (int k = 0; k < 2; ++k) \
;     dst[m][k] = *reinterpret_cast<const bf16x8*>((char*)SA(b, h) + lds_byte(wr * 64 + m * 16 + fr, k * 32 + fq * 8))
; #define LDB(dst, b, h) for (int n = 0; n < 2; ++n) for (int k = 0; k < 2; ++k) \
;     dst[n][k] = *reinterpret_cast<const bf16x8*>((char*)SB(b, h) + lds_byte(wc * 32 + n * 16 + fr, k * 32 + fq * 8))
; template <int EPI>
; __device__ __forceinline__ void gemm_phase(const GemmDesc d, u16* shm, unsigned sx, unsigned srank, unsigned snloc) {
;     ...
;         const bool lastk = (kt + 2 >= nt);
;         const char* A1 = Au + (long)(kt + 1) * sKA;
;         const char* A2 = lastk ? Aun : Au + (long)(kt + 2) * sKA;
;         const char* B2 = lastk ? Bun : Bu + (long)(kt + 2) * sKB;
;         const char* B2h = lastk ? Bunh : Buh + (long)(kt + 2) * sKB;
;         const unsigned vh[2] = {lastk ? voffBhn[0] : voffBh[0], lastk ? voffBhn[1] : voffBh[1]};
;         const char* A3 = A2 + sKA; const char* B3 = B2 + sKB; const char* B3h = B2h + sKB;
;         LDB(B0, 0, 0); SCHED; LDA(At, 0, 0); STAGE_A(A1, 1, 1);
;         WAIT_L(8); BAR; MMA(0, 0, At, B0); BAR; SCHED;
;         LDB(B1, 0, 1); STAGE_B(B2, B2h, vh, 0, 0);
;         BAR; MMA(0, 1, At, B1); BAR;
;         LDA(At, 0, 1); STAGE_A(A2, 0, 0);
;         BAR; MMA(1, 0, At, B0); BAR; SCHED;
;         STAGE_B(B2, B2h, vh, 0, 1);
;         WAIT_V(6); BAR; MMA(1, 1, At, B1); BAR;
;         LDB(B0, 1, 0); SCHED; LDA(At, 1, 0); STAGE_A(A2, 0, 1);
;         WAIT_L(8); BAR; MMA(0, 0, At, B0); BAR; SCHED;
;         LDB(B1, 1, 1); STAGE_B(B3, B3h, vh, 1, 0);
;         BAR; MMA(0, 1, At, B1); BAR;
;         LDA(At, 1, 1); STAGE_A(A3, 1, 0);
;         BAR; MMA(1, 0, At, B0); BAR; SCHED;
;         STAGE_B(B3, B3h, vh, 1, 1);
;         WAIT_V(6); BAR; MMA(1, 1, At, B1); BAR;
;       }
	s_setprio 1
	s_waitcnt lgkmcnt(7)
	v_mfma_f32_16x16x32_bf16 v[60:63], v[156:159], v[128:131], v[60:63]
	v_mfma_f32_16x16x32_bf16 v[56:59], v[156:159], v[148:151], v[56:59]
	s_waitcnt lgkmcnt(5)
	v_mfma_f32_16x16x32_bf16 v[44:47], v[164:167], v[128:131], v[44:47]
	v_mfma_f32_16x16x32_bf16 v[40:43], v[164:167], v[148:151], v[40:43]
	s_waitcnt lgkmcnt(3)
	v_mfma_f32_16x16x32_bf16 v[28:31], v[172:175], v[128:131], v[28:31]
	v_mfma_f32_16x16x32_bf16 v[24:27], v[172:175], v[148:151], v[24:27]
	s_waitcnt lgkmcnt(1)
	v_mfma_f32_16x16x32_bf16 v[12:15], v[190:193], v[128:131], v[12:15]
	v_mfma_f32_16x16x32_bf16 v[8:11], v[190:193], v[148:151], v[8:11]
	v_mfma_f32_16x16x32_bf16 v[60:63], v[160:163], v[144:147], v[60:63]
	v_mfma_f32_16x16x32_bf16 v[56:59], v[160:163], v[152:155], v[56:59]
	v_mfma_f32_16x16x32_bf16 v[44:47], v[168:171], v[144:147], v[44:47]
	v_mfma_f32_16x16x32_bf16 v[40:43], v[168:171], v[152:155], v[40:43]
	v_mfma_f32_16x16x32_bf16 v[28:31], v[178:181], v[144:147], v[28:31]
	v_mfma_f32_16x16x32_bf16 v[24:27], v[178:181], v[152:155], v[24:27]
	s_waitcnt lgkmcnt(0)
	v_mfma_f32_16x16x32_bf16 v[12:15], v[194:197], v[144:147], v[12:15]
	v_mfma_f32_16x16x32_bf16 v[8:11], v[194:197], v[152:155], v[8:11]
	s_setprio 0
	s_barrier
	s_mov_b32 m0, s76
	s_nop 0
	global_load_lds_dwordx4 v135, s[18:19]
	s_mov_b32 m0, s77
	s_nop 0
	global_load_lds_dwordx4 v135, s[4:5]
	s_mov_b64 s[10:11], s[26:27]
	s_mov_b32 s20, s21
	s_add_i32 s21, s20, 2
	s_add_u32 s0, s10, 0xfff54000
	s_addc_u32 s1, s11, -1
	s_cmp_lt_u32 s20, 42
	s_cselect_b32 s46, s0, s12
	s_cselect_b32 s0, s89, s14
	s_cselect_b32 s47, s1, s13
	s_cselect_b32 s1, s90, s15
	s_cselect_b32 s43, s92, s17
	s_cselect_b32 s42, s91, s16
	s_add_u32 s34, s0, 0x80
	s_addc_u32 s35, s1, 0
	s_add_u32 s22, s46, 0x4000
	s_addc_u32 s23, s47, 0
	s_add_u32 s94, s10, 0x2000
	s_addc_u32 s95, s11, 0
	s_add_u32 s96, s0, 0x58000
	s_addc_u32 s97, s1, 0
	s_add_u32 s48, s46, 0x2000
	s_addc_u32 s49, s47, 0
	s_add_u32 s44, s42, 0x58000
	s_addc_u32 s45, s43, 0
	s_add_u32 s40, s46, 0xb0000
	s_addc_u32 s41, s47, 0
	s_add_u32 s28, s46, 0xb2000
	s_addc_u32 s29, s47, 0
	s_add_u32 s38, s0, 0x58080
	s_addc_u32 s39, s1, 0
	s_add_u32 s30, s46, 0x6000
	s_addc_u32 s31, s47, 0
	s_add_u32 s18, s42, 0x80
	s_addc_u32 s19, s43, 0
	s_add_u32 s4, s42, 0x58080
	s_addc_u32 s5, s43, 0
	s_add_u32 s26, s10, 0x8000
	s_addc_u32 s27, s11, 0
	s_add_u32 s89, s89, 0x100
	s_addc_u32 s90, s90, 0
	s_add_u32 s91, s91, 0x100
	s_addc_u32 s92, s92, 0
	s_waitcnt vmcnt(6)
	s_barrier
	s_setprio 1
	v_mfma_f32_16x16x32_bf16 v[52:55], v[156:159], v[198:201], v[52:55]
	v_mfma_f32_16x16x32_bf16 v[48:51], v[156:159], v[206:209], v[48:51]
	v_mfma_f32_16x16x32_bf16 v[36:39], v[164:167], v[198:201], v[36:39]
	v_mfma_f32_16x16x32_bf16 v[32:35], v[164:167], v[206:209], v[32:35]
	v_mfma_f32_16x16x32_bf16 v[20:23], v[172:175], v[198:201], v[20:23]
	v_mfma_f32_16x16x32_bf16 v[16:19], v[172:175], v[206:209], v[16:19]
	v_mfma_f32_16x16x32_bf16 v[4:7], v[190:193], v[198:201], v[4:7]
	v_mfma_f32_16x16x32_bf16 v[0:3], v[190:193], v[206:209], v[0:3]
	v_mfma_f32_16x16x32_bf16 v[52:55], v[160:163], v[202:205], v[52:55]
	v_mfma_f32_16x16x32_bf16 v[48:51], v[160:163], v[210:213], v[48:51]
	v_mfma_f32_16x16x32_bf16 v[36:39], v[168:171], v[202:205], v[36:39]
	v_mfma_f32_16x16x32_bf16 v[32:35], v[168:171], v[210:213], v[32:35]
	v_mfma_f32_16x16x32_bf16 v[20:23], v[178:181], v[202:205], v[20:23]
	v_mfma_f32_16x16x32_bf16 v[16:19], v[178:181], v[210:213], v[16:19]
	v_mfma_f32_16x16x32_bf16 v[4:7], v[194:197], v[202:205], v[4:7]
	v_mfma_f32_16x16x32_bf16 v[0:3], v[194:197], v[210:213], v[0:3]
	s_setprio 0
	s_cmp_lt_u32 s20, 44
	s_barrier
	s_cbranch_scc1 .Lk_down
	s_and_saveexec_b64 s[4:5], s[8:9]
	s_cbranch_execz .LBB0_1538
	s_barrier

; __global__ void __launch_bounds__(NTHREADS, 2) fwd_megakernel(Params p_unused, int ph0, int ph1) {
;   extern __shared__ __attribute__((aligned(16))) char shm_raw[];
	.amdhsa_kernel _Z14fwd_megakernel6Paramsii
		.amdhsa_group_segment_fixed_size 2048
		.amdhsa_private_segment_fixed_size 0
		.amdhsa_kernarg_size 440
		.amdhsa_user_sgpr_count 2
		.amdhsa_user_sgpr_dispatch_ptr 0
		.amdhsa_user_sgpr_queue_ptr 0
		.amdhsa_user_sgpr_kernarg_segment_ptr 1
		.amdhsa_user_sgpr_dispatch_id 0
		.amdhsa_user_sgpr_kernarg_preload_length 0
		.amdhsa_user_sgpr_kernarg_preload_offset 0
		.amdhsa_user_sgpr_private_segment_size 0
		.amdhsa_uses_dynamic_stack 0
		.amdhsa_enable_private_segment 0
		.amdhsa_system_sgpr_workgroup_id_x 1
		.amdhsa_system_sgpr_workgroup_id_y 0
		.amdhsa_system_sgpr_workgroup_id_z 0
		.amdhsa_system_sgpr_workgroup_info 0
		.amdhsa_system_vgpr_workitem_id 2
		.amdhsa_next_free_vgpr 241
		.amdhsa_next_free_sgpr 100
		.amdhsa_accum_offset 244
		.amdhsa_reserve_vcc 1
		.amdhsa_float_round_mode_32 0
		.amdhsa_float_round_mode_16_64 0
		.amdhsa_float_denorm_mode_32 3
		.amdhsa_float_denorm_mode_16_64 3
		.amdhsa_dx10_clamp 1
		.amdhsa_ieee_mode 1
		.amdhsa_fp16_overflow 0
		.amdhsa_tg_split 0
		.amdhsa_exception_fp_ieee_invalid_op 0
		.amdhsa_exception_fp_denorm_src 0
		.amdhsa_exception_fp_ieee_div_zero 0
		.amdhsa_exception_fp_ieee_overflow 0
		.amdhsa_exception_fp_ieee_underflow 0
		.amdhsa_exception_fp_ieee_inexact 0
		.amdhsa_exception_int_div_zero 0
	.end_amdhsa_kernel

; __global__ void __launch_bounds__(NTHREADS, 2) fwd_megakernel(Params p_unused, int ph0, int ph1) {
;   extern __shared__ __attribute__((aligned(16))) char shm_raw[];
amdhsa.kernels:
  - .agpr_count:     0
    .args:
      - .offset:         0
        .size:           176
        .value_kind:     by_value
      - .offset:         176
        .size:           4
        .value_kind:     by_value
      - .offset:         180
        .size:           4
        .value_kind:     by_value
      - .offset:         184
        .size:           4
        .value_kind:     hidden_block_count_x
      - .offset:         188
        .size:           4
        .value_kind:     hidden_block_count_y
      - .offset:         192
        .size:           4
        .value_kind:     hidden_block_count_z
      - .offset:         196
        .size:           2
        .value_kind:     hidden_group_size_x
      - .offset:         198
        .size:           2
        .value_kind:     hidden_group_size_y
      - .offset:         200
        .size:           2
        .value_kind:     hidden_group_size_z
      - .offset:         202
        .size:           2
        .value_kind:     hidden_remainder_x
      - .offset:         204
        .size:           2
        .value_kind:     hidden_remainder_y
      - .offset:         206
        .size:           2
        .value_kind:     hidden_remainder_z
      - .offset:         224
        .size:           8
        .value_kind:     hidden_global_offset_x
      - .offset:         232
        .size:           8
        .value_kind:     hidden_global_offset_y
      - .offset:         240
        .size:           8
        .value_kind:     hidden_global_offset_z
      - .offset:         248
        .size:           2
        .value_kind:     hidden_grid_dims
      - .offset:         272
        .size:           8
        .value_kind:     hidden_multigrid_sync_arg
      - .offset:         304
        .size:           4
        .value_kind:     hidden_dynamic_lds_size
    .group_segment_fixed_size: 2048
    .kernarg_segment_align: 8
    .kernarg_segment_size: 440
    .language:       OpenCL C
    .language_version:
      - 2
      - 0
    .max_flat_workgroup_size: 512
    .name:           _Z14fwd_megakernel6Paramsii
    .private_segment_fixed_size: 0
    .sgpr_count:     106
    .sgpr_spill_count: 207
    .symbol:         _Z14fwd_megakernel6Paramsii.kd
    .uniform_work_group_size: 1
    .uses_dynamic_stack: false
    .vgpr_count:     241
    .vgpr_spill_count: 0
    .wavefront_size: 64
